# as v27 plus setprio 1 moved in front of the opening barrier of each MFMA segment
# baseline (speedup 1.0000x reference)
; #define PG8_STAGE(bufoff, gbase, voff) do { _Pragma("unroll") for (int _i = 0; _i < 2; ++_i) \
;         __builtin_amdgcn_global_load_lds((const unsigned*)((const char*)(gbase) + (voff)[_i]), (PG8_LAS unsigned*)(lds + (bufoff) + ldsw + _i * 8192), 16, 0, 0); } while (0)
; #define PG8_LDA(dst, b, h) do { _Pragma("unroll") for (int m = 0; m < 4; ++m) _Pragma("unroll") for (int k = 0; k < 2; ++k) dst[m][k] = *(const PG8_LAS bf16x8*)(lds + PG8_SA(b, h) + aoff + m * 2048 + k * 1024); } while (0)
; #define PG8_LDB(dst, b, h) do { _Pragma("unroll") for (int n = 0; n < 2; ++n) _Pragma("unroll") for (int k = 0; k < 2; ++k) dst[n][k] = *(const PG8_LAS bf16x8*)(lds + PG8_SB(b, h) + boff + n * 2048 + k * 1024); } while (0)
; #define PG8_MMA(ai, bj, At, Bt) do { __builtin_amdgcn_s_setprio(1); _Pragma("unroll") for (int m = 0; m < 4; ++m) _Pragma("unroll") for (int n = 0; n < 2; ++n) _Pragma("unroll") for (int k = 0; k < 2; ++k) \
;         acc[ai][bj][m][n] = __builtin_amdgcn_mfma_f32_16x16x32_bf16(Bt[n][k], At[m][k], acc[ai][bj][m][n], 0, 0, 0); __builtin_amdgcn_s_setprio(0); } while (0)
; #define PG8_WAIT_V(n) asm volatile("s_waitcnt vmcnt(" #n ")" ::: "memory")
; #define PG8_WAIT_L(n) asm volatile("s_waitcnt lgkmcnt(" #n ")" ::: "memory")
; #define PG8_BAR __builtin_amdgcn_s_barrier()
; template <class Epi, class Sched, bool ALIGN_EPI = false, bool SP2 = false>
; __device__ __forceinline__ void gemm_phase(PG8_LAS unsigned char* lds, const Gemm g, const Sched& S, const Epi& E) {
;     ...
;             const char* a1 = cA + (size_t)(t + 1) * kstep;
;             const char* a2 = last ? nA : cA + (size_t)(t + 2) * kstep; const char* b2 = last ? nB : cB + (size_t)(t + 2) * kstep;
;             const char* a3 = a2 + kstep; const char* b3 = b2 + kstep;
;             if (last && has_next) S.a_ready(nxt);
;             if constexpr (SP2) {
;             PG8_LDB(B0, 0, 0); PG8_LDB(B1, 0, 1); PG8_SCHED; PG8_LDA(At, 0, 0); PG8_STAGE(PG8_SA(1, 1), a1 + hstep, voffA);
;             PG8_WAIT_V(8); PG8_WAIT_L(0); PG8_BAR; PG8_MMA(0, 0, At, B0); PG8_MMA(0, 1, At, B1); PG8_BAR; PG8_SCHED;
;             PG8_LDA(At, 0, 1); PG8_STAGE(PG8_SB(0, 0), b2, voffB); PG8_STAGE(PG8_SB(0, 1), b2 + hstep, voffB); PG8_STAGE(PG8_SA(0, 0), a2, voffA);
;             PG8_WAIT_V(8); PG8_WAIT_L(0); PG8_BAR; PG8_MMA(1, 0, At, B0); PG8_MMA(1, 1, At, B1); PG8_BAR; PG8_SCHED;
.LBB0_232:
	ds_read_b128 v[154:157], v149
	ds_read_b128 v[158:161], v149 offset:1024
	ds_read_b128 v[162:165], v149 offset:2048
	ds_read_b128 v[166:169], v149 offset:3072
	ds_read_b128 v[170:173], v150
	ds_read_b128 v[174:177], v150 offset:1024
	ds_read_b128 v[178:181], v150 offset:2048
	ds_read_b128 v[182:185], v150 offset:3072
	s_add_u32 s40, s38, 0xfffc0080
	s_addc_u32 s41, s39, -1
	s_cmp_eq_u32 s68, 12
	s_cselect_b32 s43, s21, s41
	s_cselect_b32 s42, s64, s40
	s_cselect_b32 s41, s19, s67
	s_cselect_b32 s40, s65, s66
	v_lshl_add_u64 v[144:145], s[38:39], 0, v[136:137]
	s_add_i32 m0, s37, 0xc000
	ds_read_b128 v[186:189], v151
	ds_read_b128 v[190:193], v151 offset:1024
	ds_read_b128 v[194:197], v151 offset:2048
	ds_read_b128 v[198:201], v151 offset:3072
	ds_read_b128 v[202:205], v151 offset:4096
	ds_read_b128 v[206:209], v151 offset:5120
	ds_read_b128 v[210:213], v151 offset:6144
	ds_read_b128 v[214:217], v151 offset:7168
	global_load_lds_dwordx4 v[144:145], off
	v_lshl_add_u64 v[144:145], s[38:39], 0, v[138:139]
	s_add_i32 m0, s37, 0xe000
	s_nop 0
	global_load_lds_dwordx4 v[144:145], off
	s_waitcnt vmcnt(8)
	s_waitcnt lgkmcnt(0)
	s_setprio 1
	s_barrier
	v_mfma_f32_16x16x32_bf16 v[120:123], v[154:157], v[186:189], v[120:123]
	v_mfma_f32_16x16x32_bf16 v[116:119], v[162:165], v[186:189], v[116:119]
	v_mfma_f32_16x16x32_bf16 v[108:111], v[154:157], v[194:197], v[108:111]
	v_mfma_f32_16x16x32_bf16 v[100:103], v[162:165], v[194:197], v[100:103]
	v_mfma_f32_16x16x32_bf16 v[92:95], v[154:157], v[202:205], v[92:95]
	v_mfma_f32_16x16x32_bf16 v[84:87], v[162:165], v[202:205], v[84:87]
	v_mfma_f32_16x16x32_bf16 v[76:79], v[154:157], v[210:213], v[76:79]
	v_mfma_f32_16x16x32_bf16 v[68:71], v[162:165], v[210:213], v[68:71]
	v_mfma_f32_16x16x32_bf16 v[120:123], v[158:161], v[190:193], v[120:123]
	v_mfma_f32_16x16x32_bf16 v[116:119], v[166:169], v[190:193], v[116:119]
	v_mfma_f32_16x16x32_bf16 v[108:111], v[158:161], v[198:201], v[108:111]
	v_mfma_f32_16x16x32_bf16 v[100:103], v[166:169], v[198:201], v[100:103]
	v_mfma_f32_16x16x32_bf16 v[92:95], v[158:161], v[206:209], v[92:95]
	v_mfma_f32_16x16x32_bf16 v[84:87], v[166:169], v[206:209], v[84:87]
	v_mfma_f32_16x16x32_bf16 v[76:79], v[158:161], v[214:217], v[76:79]
	v_mfma_f32_16x16x32_bf16 v[68:71], v[166:169], v[214:217], v[68:71]
	v_mfma_f32_16x16x32_bf16 v[124:127], v[170:173], v[186:189], v[124:127]
	v_mfma_f32_16x16x32_bf16 v[112:115], v[178:181], v[186:189], v[112:115]
	v_mfma_f32_16x16x32_bf16 v[104:107], v[170:173], v[194:197], v[104:107]
	v_mfma_f32_16x16x32_bf16 v[96:99], v[178:181], v[194:197], v[96:99]
	v_mfma_f32_16x16x32_bf16 v[88:91], v[170:173], v[202:205], v[88:91]
	v_mfma_f32_16x16x32_bf16 v[80:83], v[178:181], v[202:205], v[80:83]
	v_mfma_f32_16x16x32_bf16 v[72:75], v[170:173], v[210:213], v[72:75]
	v_mfma_f32_16x16x32_bf16 v[64:67], v[178:181], v[210:213], v[64:67]
	v_mfma_f32_16x16x32_bf16 v[124:127], v[174:177], v[190:193], v[124:127]
	v_mfma_f32_16x16x32_bf16 v[112:115], v[182:185], v[190:193], v[112:115]
	v_mfma_f32_16x16x32_bf16 v[104:107], v[174:177], v[198:201], v[104:107]
	v_mfma_f32_16x16x32_bf16 v[96:99], v[182:185], v[198:201], v[96:99]
	v_mfma_f32_16x16x32_bf16 v[88:91], v[174:177], v[206:209], v[88:91]
	v_mfma_f32_16x16x32_bf16 v[80:83], v[182:185], v[206:209], v[80:83]
	v_mfma_f32_16x16x32_bf16 v[72:75], v[174:177], v[214:217], v[72:75]
	v_mfma_f32_16x16x32_bf16 v[64:67], v[182:185], v[214:217], v[64:67]
	s_barrier
	s_setprio 0
	s_add_i32 s69, s57, s48
	v_lshl_add_u64 v[144:145], s[40:41], 0, v[132:133]
	s_mov_b32 m0, s69
	ds_read_b128 v[186:189], v151 offset:16384
	ds_read_b128 v[190:193], v151 offset:17408
	ds_read_b128 v[194:197], v151 offset:18432
	ds_read_b128 v[198:201], v151 offset:19456
	ds_read_b128 v[202:205], v151 offset:20480
	ds_read_b128 v[206:209], v151 offset:21504
	ds_read_b128 v[210:213], v151 offset:22528
	ds_read_b128 v[214:217], v151 offset:23552
	global_load_lds_dwordx4 v[144:145], off
	s_add_i32 m0, s69, 0x2000
	s_add_u32 s70, s40, 0x40000
	v_lshl_add_u64 v[218:219], s[40:41], 0, v[128:129]
	s_addc_u32 s71, s41, 0
	s_add_i32 s69, s58, s48
	global_load_lds_dwordx4 v[218:219], off
	v_lshl_add_u64 v[220:221], s[70:71], 0, v[132:133]
	s_mov_b32 m0, s69
	v_lshl_add_u64 v[222:223], s[42:43], 0, v[130:131]
	global_load_lds_dwordx4 v[220:221], off
	v_lshl_add_u64 v[220:221], s[70:71], 0, v[128:129]
	s_add_i32 m0, s69, 0x2000
	s_nop 0
	global_load_lds_dwordx4 v[220:221], off
	v_lshl_add_u64 v[220:221], s[42:43], 0, v[134:135]
	s_mov_b32 m0, s37
	s_nop 0
	global_load_lds_dwordx4 v[220:221], off
	s_mov_b32 m0, s50
	s_nop 0
	global_load_lds_dwordx4 v[222:223], off
	s_waitcnt vmcnt(8)
	s_waitcnt lgkmcnt(0)
	s_setprio 1
	s_barrier
; #define PG8_STAGE(bufoff, gbase, voff) do { _Pragma("unroll") for (int _i = 0; _i < 2; ++_i) \
;         __builtin_amdgcn_global_load_lds((const unsigned*)((const char*)(gbase) + (voff)[_i]), (PG8_LAS unsigned*)(lds + (bufoff) + ldsw + _i * 8192), 16, 0, 0); } while (0)
; #define PG8_LDA(dst, b, h) do { _Pragma("unroll") for (int m = 0; m < 4; ++m) _Pragma("unroll") for (int k = 0; k < 2; ++k) dst[m][k] = *(const PG8_LAS bf16x8*)(lds + PG8_SA(b, h) + aoff + m * 2048 + k * 1024); } while (0)
; #define PG8_LDB(dst, b, h) do { _Pragma("unroll") for (int n = 0; n < 2; ++n) _Pragma("unroll") for (int k = 0; k < 2; ++k) dst[n][k] = *(const PG8_LAS bf16x8*)(lds + PG8_SB(b, h) + boff + n * 2048 + k * 1024); } while (0)
; #define PG8_MMA(ai, bj, At, Bt) do { __builtin_amdgcn_s_setprio(1); _Pragma("unroll") for (int m = 0; m < 4; ++m) _Pragma("unroll") for (int n = 0; n < 2; ++n) _Pragma("unroll") for (int k = 0; k < 2; ++k) \
;         acc[ai][bj][m][n] = __builtin_amdgcn_mfma_f32_16x16x32_bf16(Bt[n][k], At[m][k], acc[ai][bj][m][n], 0, 0, 0); __builtin_amdgcn_s_setprio(0); } while (0)
; #define PG8_WAIT_V(n) asm volatile("s_waitcnt vmcnt(" #n ")" ::: "memory")
; #define PG8_WAIT_L(n) asm volatile("s_waitcnt lgkmcnt(" #n ")" ::: "memory")
; #define PG8_BAR __builtin_amdgcn_s_barrier()
; #define PG8_SCHED __builtin_amdgcn_sched_barrier(0)
; template <class Epi, class Sched, bool ALIGN_EPI = false, bool SP2 = false>
; __device__ __forceinline__ void gemm_phase(PG8_LAS unsigned char* lds, const Gemm g, const Sched& S, const Epi& E) {
;     ...
;             PG8_WAIT_V(8); PG8_WAIT_L(0); PG8_BAR; PG8_MMA(1, 0, At, B0); PG8_MMA(1, 1, At, B1); PG8_BAR; PG8_SCHED;
;             PG8_LDB(B0, 1, 0); PG8_LDB(B1, 1, 1); PG8_SCHED; PG8_LDA(At, 1, 0); PG8_STAGE(PG8_SA(0, 1), a2 + hstep, voffA);
;             PG8_WAIT_V(8); PG8_WAIT_L(0); PG8_BAR; PG8_MMA(0, 0, At, B0); PG8_MMA(0, 1, At, B1); PG8_BAR; PG8_SCHED;
	v_mfma_f32_16x16x32_bf16 v[60:63], v[154:157], v[186:189], v[60:63]
	v_mfma_f32_16x16x32_bf16 v[52:55], v[162:165], v[186:189], v[52:55]
	v_mfma_f32_16x16x32_bf16 v[44:47], v[154:157], v[194:197], v[44:47]
	v_mfma_f32_16x16x32_bf16 v[36:39], v[162:165], v[194:197], v[36:39]
	v_mfma_f32_16x16x32_bf16 v[28:31], v[154:157], v[202:205], v[28:31]
	v_mfma_f32_16x16x32_bf16 v[20:23], v[162:165], v[202:205], v[20:23]
	v_mfma_f32_16x16x32_bf16 v[12:15], v[154:157], v[210:213], v[12:15]
	v_mfma_f32_16x16x32_bf16 v[4:7], v[162:165], v[210:213], v[4:7]
	v_mfma_f32_16x16x32_bf16 v[60:63], v[158:161], v[190:193], v[60:63]
	v_mfma_f32_16x16x32_bf16 v[52:55], v[166:169], v[190:193], v[52:55]
	v_mfma_f32_16x16x32_bf16 v[44:47], v[158:161], v[198:201], v[44:47]
	v_mfma_f32_16x16x32_bf16 v[36:39], v[166:169], v[198:201], v[36:39]
	v_mfma_f32_16x16x32_bf16 v[28:31], v[158:161], v[206:209], v[28:31]
	v_mfma_f32_16x16x32_bf16 v[20:23], v[166:169], v[206:209], v[20:23]
	v_mfma_f32_16x16x32_bf16 v[12:15], v[158:161], v[214:217], v[12:15]
	v_mfma_f32_16x16x32_bf16 v[4:7], v[166:169], v[214:217], v[4:7]
	v_mfma_f32_16x16x32_bf16 v[56:59], v[170:173], v[186:189], v[56:59]
	v_mfma_f32_16x16x32_bf16 v[48:51], v[178:181], v[186:189], v[48:51]
	v_mfma_f32_16x16x32_bf16 v[40:43], v[170:173], v[194:197], v[40:43]
	v_mfma_f32_16x16x32_bf16 v[32:35], v[178:181], v[194:197], v[32:35]
	v_mfma_f32_16x16x32_bf16 v[24:27], v[170:173], v[202:205], v[24:27]
	v_mfma_f32_16x16x32_bf16 v[16:19], v[178:181], v[202:205], v[16:19]
	v_mfma_f32_16x16x32_bf16 v[8:11], v[170:173], v[210:213], v[8:11]
	v_mfma_f32_16x16x32_bf16 v[0:3], v[178:181], v[210:213], v[0:3]
	v_mfma_f32_16x16x32_bf16 v[56:59], v[174:177], v[190:193], v[56:59]
	v_mfma_f32_16x16x32_bf16 v[48:51], v[182:185], v[190:193], v[48:51]
	v_mfma_f32_16x16x32_bf16 v[40:43], v[174:177], v[198:201], v[40:43]
	v_mfma_f32_16x16x32_bf16 v[32:35], v[182:185], v[198:201], v[32:35]
	v_mfma_f32_16x16x32_bf16 v[24:27], v[174:177], v[206:209], v[24:27]
	v_mfma_f32_16x16x32_bf16 v[16:19], v[182:185], v[206:209], v[16:19]
	v_mfma_f32_16x16x32_bf16 v[8:11], v[174:177], v[214:217], v[8:11]
	v_mfma_f32_16x16x32_bf16 v[0:3], v[182:185], v[214:217], v[0:3]
	s_barrier
	s_setprio 0
	s_add_i32 s69, 0, 0x18000
	v_add_u32_e32 v153, s69, v147
	s_add_i32 s70, 0, 0x1c000
	ds_read_b128 v[154:157], v153
	ds_read_b128 v[158:161], v153 offset:1024
	ds_read_b128 v[162:165], v153 offset:2048
	ds_read_b128 v[166:169], v153 offset:3072
	v_add_u32_e32 v153, s70, v147
	ds_read_b128 v[170:173], v153
	ds_read_b128 v[174:177], v153 offset:1024
	ds_read_b128 v[178:181], v153 offset:2048
	ds_read_b128 v[182:185], v153 offset:3072
	s_add_u32 s42, s42, 0x40000
	s_addc_u32 s43, s43, 0
	s_mov_b32 m0, s51
	v_lshl_add_u64 v[224:225], s[42:43], 0, v[134:135]
	ds_read_b128 v[186:189], v151 offset:32768
	ds_read_b128 v[190:193], v151 offset:33792
	ds_read_b128 v[194:197], v151 offset:34816
	ds_read_b128 v[198:201], v151 offset:35840
	ds_read_b128 v[202:205], v151 offset:36864
	ds_read_b128 v[206:209], v151 offset:37888
	ds_read_b128 v[210:213], v151 offset:38912
	ds_read_b128 v[214:217], v151 offset:39936
	global_load_lds_dwordx4 v[224:225], off
	v_lshl_add_u64 v[224:225], s[42:43], 0, v[130:131]
	s_mov_b32 m0, s52
	s_nop 0
	global_load_lds_dwordx4 v[224:225], off
	s_waitcnt vmcnt(8)
	s_waitcnt lgkmcnt(0)
	s_setprio 1
	s_barrier
	v_mfma_f32_16x16x32_bf16 v[120:123], v[154:157], v[186:189], v[120:123]
	v_mfma_f32_16x16x32_bf16 v[116:119], v[162:165], v[186:189], v[116:119]
	v_mfma_f32_16x16x32_bf16 v[108:111], v[154:157], v[194:197], v[108:111]
	v_mfma_f32_16x16x32_bf16 v[100:103], v[162:165], v[194:197], v[100:103]
	v_mfma_f32_16x16x32_bf16 v[92:95], v[154:157], v[202:205], v[92:95]
	v_mfma_f32_16x16x32_bf16 v[84:87], v[162:165], v[202:205], v[84:87]
	v_mfma_f32_16x16x32_bf16 v[76:79], v[154:157], v[210:213], v[76:79]
	v_mfma_f32_16x16x32_bf16 v[68:71], v[162:165], v[210:213], v[68:71]
	v_mfma_f32_16x16x32_bf16 v[120:123], v[158:161], v[190:193], v[120:123]
	v_mfma_f32_16x16x32_bf16 v[116:119], v[166:169], v[190:193], v[116:119]
	v_mfma_f32_16x16x32_bf16 v[108:111], v[158:161], v[198:201], v[108:111]
	v_mfma_f32_16x16x32_bf16 v[100:103], v[166:169], v[198:201], v[100:103]
	v_mfma_f32_16x16x32_bf16 v[92:95], v[158:161], v[206:209], v[92:95]
	v_mfma_f32_16x16x32_bf16 v[84:87], v[166:169], v[206:209], v[84:87]
	v_mfma_f32_16x16x32_bf16 v[76:79], v[158:161], v[214:217], v[76:79]
	v_mfma_f32_16x16x32_bf16 v[68:71], v[166:169], v[214:217], v[68:71]
	v_mfma_f32_16x16x32_bf16 v[124:127], v[170:173], v[186:189], v[124:127]
	v_mfma_f32_16x16x32_bf16 v[112:115], v[178:181], v[186:189], v[112:115]
	v_mfma_f32_16x16x32_bf16 v[104:107], v[170:173], v[194:197], v[104:107]
	v_mfma_f32_16x16x32_bf16 v[96:99], v[178:181], v[194:197], v[96:99]
	v_mfma_f32_16x16x32_bf16 v[88:91], v[170:173], v[202:205], v[88:91]
	v_mfma_f32_16x16x32_bf16 v[80:83], v[178:181], v[202:205], v[80:83]
	v_mfma_f32_16x16x32_bf16 v[72:75], v[170:173], v[210:213], v[72:75]
	v_mfma_f32_16x16x32_bf16 v[64:67], v[178:181], v[210:213], v[64:67]
	v_mfma_f32_16x16x32_bf16 v[124:127], v[174:177], v[190:193], v[124:127]
	v_mfma_f32_16x16x32_bf16 v[112:115], v[182:185], v[190:193], v[112:115]
	v_mfma_f32_16x16x32_bf16 v[104:107], v[174:177], v[198:201], v[104:107]
	v_mfma_f32_16x16x32_bf16 v[96:99], v[182:185], v[198:201], v[96:99]
	v_mfma_f32_16x16x32_bf16 v[88:91], v[174:177], v[206:209], v[88:91]
	v_mfma_f32_16x16x32_bf16 v[80:83], v[182:185], v[206:209], v[80:83]
	v_mfma_f32_16x16x32_bf16 v[72:75], v[174:177], v[214:217], v[72:75]
	v_mfma_f32_16x16x32_bf16 v[64:67], v[182:185], v[214:217], v[64:67]
	s_barrier
; #define PG8_STAGE(bufoff, gbase, voff) do { _Pragma("unroll") for (int _i = 0; _i < 2; ++_i) \
;         __builtin_amdgcn_global_load_lds((const unsigned*)((const char*)(gbase) + (voff)[_i]), (PG8_LAS unsigned*)(lds + (bufoff) + ldsw + _i * 8192), 16, 0, 0); } while (0)
; #define PG8_LDA(dst, b, h) do { _Pragma("unroll") for (int m = 0; m < 4; ++m) _Pragma("unroll") for (int k = 0; k < 2; ++k) dst[m][k] = *(const PG8_LAS bf16x8*)(lds + PG8_SA(b, h) + aoff + m * 2048 + k * 1024); } while (0)
; #define PG8_MMA(ai, bj, At, Bt) do { __builtin_amdgcn_s_setprio(1); _Pragma("unroll") for (int m = 0; m < 4; ++m) _Pragma("unroll") for (int n = 0; n < 2; ++n) _Pragma("unroll") for (int k = 0; k < 2; ++k) \
;         acc[ai][bj][m][n] = __builtin_amdgcn_mfma_f32_16x16x32_bf16(Bt[n][k], At[m][k], acc[ai][bj][m][n], 0, 0, 0); __builtin_amdgcn_s_setprio(0); } while (0)
; #define PG8_WAIT_V(n) asm volatile("s_waitcnt vmcnt(" #n ")" ::: "memory")
; #define PG8_WAIT_L(n) asm volatile("s_waitcnt lgkmcnt(" #n ")" ::: "memory")
; #define PG8_BAR __builtin_amdgcn_s_barrier()
; #define PG8_SCHED __builtin_amdgcn_sched_barrier(0)
; template <class Epi, class Sched, bool ALIGN_EPI = false, bool SP2 = false>
; __device__ __forceinline__ void gemm_phase(PG8_LAS unsigned char* lds, const Gemm g, const Sched& S, const Epi& E) {
;     ...
;             PG8_LDA(At, 1, 1); PG8_STAGE(PG8_SB(1, 0), b3, voffB); PG8_STAGE(PG8_SB(1, 1), b3 + hstep, voffB); PG8_STAGE(PG8_SA(1, 0), a3, voffA);
;             PG8_WAIT_V(8); PG8_WAIT_L(0); PG8_BAR; PG8_MMA(1, 0, At, B0); PG8_MMA(1, 1, At, B1); PG8_BAR; PG8_SCHED;
;     ...
;         if constexpr (ALIGN_EPI) { if (wr == 0) PG8_BAR; }
	s_setprio 0
	s_add_i32 s42, s69, s48
	v_lshl_add_u64 v[144:145], v[144:145], 0, s[14:15]
	s_mov_b32 m0, s42
	ds_read_b128 v[186:189], v151 offset:49152
	ds_read_b128 v[190:193], v151 offset:50176
	ds_read_b128 v[194:197], v151 offset:51200
	ds_read_b128 v[198:201], v151 offset:52224
	ds_read_b128 v[202:205], v151 offset:53248
	ds_read_b128 v[206:209], v151 offset:54272
	ds_read_b128 v[210:213], v151 offset:55296
	ds_read_b128 v[214:217], v151 offset:56320
	global_load_lds_dwordx4 v[144:145], off
	s_add_i32 m0, s42, 0x2000
	s_add_u32 s40, s40, 0x40080
	v_lshl_add_u64 v[144:145], v[218:219], 0, s[14:15]
	s_addc_u32 s41, s41, 0
	s_add_i32 s42, s70, s48
	global_load_lds_dwordx4 v[144:145], off
	v_lshl_add_u64 v[144:145], s[40:41], 0, v[132:133]
	s_mov_b32 m0, s42
	s_nop 0
	global_load_lds_dwordx4 v[144:145], off
	v_lshl_add_u64 v[144:145], s[40:41], 0, v[128:129]
	s_add_i32 m0, s42, 0x2000
	s_nop 0
	global_load_lds_dwordx4 v[144:145], off
	v_lshl_add_u64 v[144:145], v[220:221], 0, s[14:15]
	s_mov_b32 m0, s54
	s_nop 0
	global_load_lds_dwordx4 v[144:145], off
	v_lshl_add_u64 v[144:145], v[222:223], 0, s[14:15]
	s_mov_b32 m0, s55
	s_nop 0
	global_load_lds_dwordx4 v[144:145], off
	s_waitcnt vmcnt(8)
	s_waitcnt lgkmcnt(0)
	s_setprio 1
	s_barrier
	v_mfma_f32_16x16x32_bf16 v[60:63], v[154:157], v[186:189], v[60:63]
	v_mfma_f32_16x16x32_bf16 v[52:55], v[162:165], v[186:189], v[52:55]
	v_mfma_f32_16x16x32_bf16 v[44:47], v[154:157], v[194:197], v[44:47]
	v_mfma_f32_16x16x32_bf16 v[36:39], v[162:165], v[194:197], v[36:39]
	v_mfma_f32_16x16x32_bf16 v[28:31], v[154:157], v[202:205], v[28:31]
	v_mfma_f32_16x16x32_bf16 v[20:23], v[162:165], v[202:205], v[20:23]
	v_mfma_f32_16x16x32_bf16 v[12:15], v[154:157], v[210:213], v[12:15]
	v_mfma_f32_16x16x32_bf16 v[4:7], v[162:165], v[210:213], v[4:7]
	v_mfma_f32_16x16x32_bf16 v[60:63], v[158:161], v[190:193], v[60:63]
	v_mfma_f32_16x16x32_bf16 v[52:55], v[166:169], v[190:193], v[52:55]
	v_mfma_f32_16x16x32_bf16 v[44:47], v[158:161], v[198:201], v[44:47]
	v_mfma_f32_16x16x32_bf16 v[36:39], v[166:169], v[198:201], v[36:39]
	v_mfma_f32_16x16x32_bf16 v[28:31], v[158:161], v[206:209], v[28:31]
	v_mfma_f32_16x16x32_bf16 v[20:23], v[166:169], v[206:209], v[20:23]
	v_mfma_f32_16x16x32_bf16 v[12:15], v[158:161], v[214:217], v[12:15]
	v_mfma_f32_16x16x32_bf16 v[4:7], v[166:169], v[214:217], v[4:7]
	v_mfma_f32_16x16x32_bf16 v[56:59], v[170:173], v[186:189], v[56:59]
	v_mfma_f32_16x16x32_bf16 v[48:51], v[178:181], v[186:189], v[48:51]
	v_mfma_f32_16x16x32_bf16 v[40:43], v[170:173], v[194:197], v[40:43]
	v_mfma_f32_16x16x32_bf16 v[32:35], v[178:181], v[194:197], v[32:35]
	v_mfma_f32_16x16x32_bf16 v[24:27], v[170:173], v[202:205], v[24:27]
	v_mfma_f32_16x16x32_bf16 v[16:19], v[178:181], v[202:205], v[16:19]
	v_mfma_f32_16x16x32_bf16 v[8:11], v[170:173], v[210:213], v[8:11]
	v_mfma_f32_16x16x32_bf16 v[0:3], v[178:181], v[210:213], v[0:3]
	v_mfma_f32_16x16x32_bf16 v[56:59], v[174:177], v[190:193], v[56:59]
	v_mfma_f32_16x16x32_bf16 v[48:51], v[182:185], v[190:193], v[48:51]
	v_mfma_f32_16x16x32_bf16 v[40:43], v[174:177], v[198:201], v[40:43]
	v_mfma_f32_16x16x32_bf16 v[32:35], v[182:185], v[198:201], v[32:35]
	v_mfma_f32_16x16x32_bf16 v[24:27], v[174:177], v[206:209], v[24:27]
	v_mfma_f32_16x16x32_bf16 v[16:19], v[182:185], v[206:209], v[16:19]
	v_mfma_f32_16x16x32_bf16 v[8:11], v[174:177], v[214:217], v[8:11]
	v_mfma_f32_16x16x32_bf16 v[0:3], v[182:185], v[214:217], v[0:3]
	s_barrier
	s_setprio 0
	s_add_i32 s68, s68, 2
	s_add_u32 s38, s38, 0x100
	s_addc_u32 s39, s39, 0
	s_add_u32 s66, s66, 0x100
	s_addc_u32 s67, s67, 0
	s_cmp_gt_u32 s68, 13
	s_cbranch_scc0 .LBB0_232
	s_and_b64 vcc, exec, s[16:17]
	s_cbranch_vccz .LBB0_235
	s_barrier

; #define PG8_STAGE(bufoff, gbase, voff) do { _Pragma("unroll") for (int _i = 0; _i < 2; ++_i) \
;         __builtin_amdgcn_global_load_lds((const unsigned*)((const char*)(gbase) + (voff)[_i]), (PG8_LAS unsigned*)(lds + (bufoff) + ldsw + _i * 8192), 16, 0, 0); } while (0)
; #define PG8_LDA(dst, b, h) do { _Pragma("unroll") for (int m = 0; m < 4; ++m) _Pragma("unroll") for (int k = 0; k < 2; ++k) dst[m][k] = *(const PG8_LAS bf16x8*)(lds + PG8_SA(b, h) + aoff + m * 2048 + k * 1024); } while (0)
; #define PG8_LDB(dst, b, h) do { _Pragma("unroll") for (int n = 0; n < 2; ++n) _Pragma("unroll") for (int k = 0; k < 2; ++k) dst[n][k] = *(const PG8_LAS bf16x8*)(lds + PG8_SB(b, h) + boff + n * 2048 + k * 1024); } while (0)
; #define PG8_MMA(ai, bj, At, Bt) do { __builtin_amdgcn_s_setprio(1); _Pragma("unroll") for (int m = 0; m < 4; ++m) _Pragma("unroll") for (int n = 0; n < 2; ++n) _Pragma("unroll") for (int k = 0; k < 2; ++k) \
;         acc[ai][bj][m][n] = __builtin_amdgcn_mfma_f32_16x16x32_bf16(Bt[n][k], At[m][k], acc[ai][bj][m][n], 0, 0, 0); __builtin_amdgcn_s_setprio(0); } while (0)
; #define PG8_WAIT_V(n) asm volatile("s_waitcnt vmcnt(" #n ")" ::: "memory")
; #define PG8_WAIT_L(n) asm volatile("s_waitcnt lgkmcnt(" #n ")" ::: "memory")
; #define PG8_BAR __builtin_amdgcn_s_barrier()
; template <class Epi, class Sched, bool ALIGN_EPI = false, bool SP2 = false>
; __device__ __forceinline__ void gemm_phase(PG8_LAS unsigned char* lds, const Gemm g, const Sched& S, const Epi& E) {
;     ...
;             const char* a1 = cA + (size_t)(t + 1) * kstep;
;             const char* a2 = last ? nA : cA + (size_t)(t + 2) * kstep; const char* b2 = last ? nB : cB + (size_t)(t + 2) * kstep;
;             const char* a3 = a2 + kstep; const char* b3 = b2 + kstep;
;             if (last && has_next) S.a_ready(nxt);
;             if constexpr (SP2) {
;             PG8_LDB(B0, 0, 0); PG8_LDB(B1, 0, 1); PG8_SCHED; PG8_LDA(At, 0, 0); PG8_STAGE(PG8_SA(1, 1), a1 + hstep, voffA);
;             PG8_WAIT_V(8); PG8_WAIT_L(0); PG8_BAR; PG8_MMA(0, 0, At, B0); PG8_MMA(0, 1, At, B1); PG8_BAR; PG8_SCHED;
;             PG8_LDA(At, 0, 1); PG8_STAGE(PG8_SB(0, 0), b2, voffB); PG8_STAGE(PG8_SB(0, 1), b2 + hstep, voffB); PG8_STAGE(PG8_SA(0, 0), a2, voffA);
;             PG8_WAIT_V(8); PG8_WAIT_L(0); PG8_BAR; PG8_MMA(1, 0, At, B0); PG8_MMA(1, 1, At, B1); PG8_BAR; PG8_SCHED;
.LBB0_406:
	ds_read_b128 v[112:115], v246
	ds_read_b128 v[116:119], v246 offset:1024
	ds_read_b128 v[120:123], v246 offset:2048
	ds_read_b128 v[124:127], v246 offset:3072
	ds_read_b128 v[136:139], v247
	ds_read_b128 v[140:143], v247 offset:1024
	ds_read_b128 v[152:155], v247 offset:2048
	ds_read_b128 v[156:159], v247 offset:3072
	s_add_u32 s36, s34, 0xfff50080
	s_addc_u32 s37, s35, -1
	s_cmp_eq_u32 s64, 40
	s_cselect_b32 s39, s9, s37
	s_cselect_b32 s38, s8, s36
	s_cselect_b32 s37, s23, s63
	s_cselect_b32 s36, s22, s59
	v_lshl_add_u64 v[206:207], s[34:35], 0, v[200:201]
	s_add_i32 m0, s45, 0xc000
	ds_read_b128 v[160:163], v248
	ds_read_b128 v[164:167], v248 offset:1024
	ds_read_b128 v[168:171], v248 offset:2048
	ds_read_b128 v[172:175], v248 offset:3072
	ds_read_b128 v[176:179], v248 offset:4096
	ds_read_b128 v[180:183], v248 offset:5120
	ds_read_b128 v[184:187], v248 offset:6144
	ds_read_b128 v[188:191], v248 offset:7168
	global_load_lds_dwordx4 v[206:207], off
	v_lshl_add_u64 v[206:207], s[34:35], 0, v[202:203]
	s_add_i32 m0, s45, 0xe000
	s_nop 0
	global_load_lds_dwordx4 v[206:207], off
	s_waitcnt vmcnt(8)
	s_waitcnt lgkmcnt(0)
	s_setprio 1
	s_barrier
	v_mfma_f32_16x16x32_bf16 v[148:151], v[112:115], v[160:163], v[148:151]
	v_mfma_f32_16x16x32_bf16 v[144:147], v[120:123], v[160:163], v[144:147]
	v_mfma_f32_16x16x32_bf16 v[108:111], v[112:115], v[168:171], v[108:111]
	v_mfma_f32_16x16x32_bf16 v[104:107], v[120:123], v[168:171], v[104:107]
	v_mfma_f32_16x16x32_bf16 v[92:95], v[112:115], v[176:179], v[92:95]
	v_mfma_f32_16x16x32_bf16 v[88:91], v[120:123], v[176:179], v[88:91]
	v_mfma_f32_16x16x32_bf16 v[76:79], v[112:115], v[184:187], v[76:79]
	v_mfma_f32_16x16x32_bf16 v[72:75], v[120:123], v[184:187], v[72:75]
	v_mfma_f32_16x16x32_bf16 v[148:151], v[116:119], v[164:167], v[148:151]
	v_mfma_f32_16x16x32_bf16 v[144:147], v[124:127], v[164:167], v[144:147]
	v_mfma_f32_16x16x32_bf16 v[108:111], v[116:119], v[172:175], v[108:111]
	v_mfma_f32_16x16x32_bf16 v[104:107], v[124:127], v[172:175], v[104:107]
	v_mfma_f32_16x16x32_bf16 v[92:95], v[116:119], v[180:183], v[92:95]
	v_mfma_f32_16x16x32_bf16 v[88:91], v[124:127], v[180:183], v[88:91]
	v_mfma_f32_16x16x32_bf16 v[76:79], v[116:119], v[188:191], v[76:79]
	v_mfma_f32_16x16x32_bf16 v[72:75], v[124:127], v[188:191], v[72:75]
	v_mfma_f32_16x16x32_bf16 v[132:135], v[136:139], v[160:163], v[132:135]
	v_mfma_f32_16x16x32_bf16 v[128:131], v[152:155], v[160:163], v[128:131]
	v_mfma_f32_16x16x32_bf16 v[100:103], v[136:139], v[168:171], v[100:103]
	v_mfma_f32_16x16x32_bf16 v[96:99], v[152:155], v[168:171], v[96:99]
	v_mfma_f32_16x16x32_bf16 v[84:87], v[136:139], v[176:179], v[84:87]
	v_mfma_f32_16x16x32_bf16 v[80:83], v[152:155], v[176:179], v[80:83]
	v_mfma_f32_16x16x32_bf16 v[68:71], v[136:139], v[184:187], v[68:71]
	v_mfma_f32_16x16x32_bf16 v[64:67], v[152:155], v[184:187], v[64:67]
	v_mfma_f32_16x16x32_bf16 v[132:135], v[140:143], v[164:167], v[132:135]
	v_mfma_f32_16x16x32_bf16 v[128:131], v[156:159], v[164:167], v[128:131]
	v_mfma_f32_16x16x32_bf16 v[100:103], v[140:143], v[172:175], v[100:103]
	v_mfma_f32_16x16x32_bf16 v[96:99], v[156:159], v[172:175], v[96:99]
	v_mfma_f32_16x16x32_bf16 v[84:87], v[140:143], v[180:183], v[84:87]
	v_mfma_f32_16x16x32_bf16 v[80:83], v[156:159], v[180:183], v[80:83]
	v_mfma_f32_16x16x32_bf16 v[68:71], v[140:143], v[188:191], v[68:71]
	v_mfma_f32_16x16x32_bf16 v[64:67], v[156:159], v[188:191], v[64:67]
	s_barrier
	s_setprio 0
	s_add_i32 s65, s53, s44
	v_lshl_add_u64 v[206:207], s[36:37], 0, v[194:195]
	s_mov_b32 m0, s65
	ds_read_b128 v[160:163], v248 offset:16384
	ds_read_b128 v[164:167], v248 offset:17408
	ds_read_b128 v[168:171], v248 offset:18432
	ds_read_b128 v[172:175], v248 offset:19456
	ds_read_b128 v[176:179], v248 offset:20480
	ds_read_b128 v[180:183], v248 offset:21504
	ds_read_b128 v[184:187], v248 offset:22528
	ds_read_b128 v[188:191], v248 offset:23552
	global_load_lds_dwordx4 v[206:207], off
	s_add_i32 m0, s65, 0x2000
	s_add_u32 s66, s36, 0xb0000
	v_lshl_add_u64 v[208:209], s[36:37], 0, v[198:199]
	s_addc_u32 s67, s37, 0
	s_add_i32 s65, s54, s44
	global_load_lds_dwordx4 v[208:209], off
	v_lshl_add_u64 v[210:211], s[66:67], 0, v[194:195]
	s_mov_b32 m0, s65
	v_lshl_add_u64 v[212:213], s[38:39], 0, v[196:197]
	global_load_lds_dwordx4 v[210:211], off
	v_lshl_add_u64 v[210:211], s[66:67], 0, v[198:199]
	s_add_i32 m0, s65, 0x2000
	s_nop 0
	global_load_lds_dwordx4 v[210:211], off
	v_lshl_add_u64 v[210:211], s[38:39], 0, v[192:193]
	s_mov_b32 m0, s45
	s_nop 0
	global_load_lds_dwordx4 v[210:211], off
	s_mov_b32 m0, s46
	s_nop 0
	global_load_lds_dwordx4 v[212:213], off
	s_waitcnt vmcnt(8)
	s_waitcnt lgkmcnt(0)
	s_setprio 1
	s_barrier
; #define PG8_STAGE(bufoff, gbase, voff) do { _Pragma("unroll") for (int _i = 0; _i < 2; ++_i) \
;         __builtin_amdgcn_global_load_lds((const unsigned*)((const char*)(gbase) + (voff)[_i]), (PG8_LAS unsigned*)(lds + (bufoff) + ldsw + _i * 8192), 16, 0, 0); } while (0)
; #define PG8_LDA(dst, b, h) do { _Pragma("unroll") for (int m = 0; m < 4; ++m) _Pragma("unroll") for (int k = 0; k < 2; ++k) dst[m][k] = *(const PG8_LAS bf16x8*)(lds + PG8_SA(b, h) + aoff + m * 2048 + k * 1024); } while (0)
; #define PG8_LDB(dst, b, h) do { _Pragma("unroll") for (int n = 0; n < 2; ++n) _Pragma("unroll") for (int k = 0; k < 2; ++k) dst[n][k] = *(const PG8_LAS bf16x8*)(lds + PG8_SB(b, h) + boff + n * 2048 + k * 1024); } while (0)
; #define PG8_MMA(ai, bj, At, Bt) do { __builtin_amdgcn_s_setprio(1); _Pragma("unroll") for (int m = 0; m < 4; ++m) _Pragma("unroll") for (int n = 0; n < 2; ++n) _Pragma("unroll") for (int k = 0; k < 2; ++k) \
;         acc[ai][bj][m][n] = __builtin_amdgcn_mfma_f32_16x16x32_bf16(Bt[n][k], At[m][k], acc[ai][bj][m][n], 0, 0, 0); __builtin_amdgcn_s_setprio(0); } while (0)
; #define PG8_WAIT_V(n) asm volatile("s_waitcnt vmcnt(" #n ")" ::: "memory")
; #define PG8_WAIT_L(n) asm volatile("s_waitcnt lgkmcnt(" #n ")" ::: "memory")
; #define PG8_BAR __builtin_amdgcn_s_barrier()
; #define PG8_SCHED __builtin_amdgcn_sched_barrier(0)
; template <class Epi, class Sched, bool ALIGN_EPI = false, bool SP2 = false>
; __device__ __forceinline__ void gemm_phase(PG8_LAS unsigned char* lds, const Gemm g, const Sched& S, const Epi& E) {
;     ...
;             PG8_WAIT_V(8); PG8_WAIT_L(0); PG8_BAR; PG8_MMA(1, 0, At, B0); PG8_MMA(1, 1, At, B1); PG8_BAR; PG8_SCHED;
;             PG8_LDB(B0, 1, 0); PG8_LDB(B1, 1, 1); PG8_SCHED; PG8_LDA(At, 1, 0); PG8_STAGE(PG8_SA(0, 1), a2 + hstep, voffA);
;             PG8_WAIT_V(8); PG8_WAIT_L(0); PG8_BAR; PG8_MMA(0, 0, At, B0); PG8_MMA(0, 1, At, B1); PG8_BAR; PG8_SCHED;
	v_mfma_f32_16x16x32_bf16 v[60:63], v[112:115], v[160:163], v[60:63]
	v_mfma_f32_16x16x32_bf16 v[56:59], v[120:123], v[160:163], v[56:59]
	v_mfma_f32_16x16x32_bf16 v[44:47], v[112:115], v[168:171], v[44:47]
	v_mfma_f32_16x16x32_bf16 v[40:43], v[120:123], v[168:171], v[40:43]
	v_mfma_f32_16x16x32_bf16 v[28:31], v[112:115], v[176:179], v[28:31]
	v_mfma_f32_16x16x32_bf16 v[24:27], v[120:123], v[176:179], v[24:27]
	v_mfma_f32_16x16x32_bf16 v[12:15], v[112:115], v[184:187], v[12:15]
	v_mfma_f32_16x16x32_bf16 v[8:11], v[120:123], v[184:187], v[8:11]
	v_mfma_f32_16x16x32_bf16 v[60:63], v[116:119], v[164:167], v[60:63]
	v_mfma_f32_16x16x32_bf16 v[56:59], v[124:127], v[164:167], v[56:59]
	v_mfma_f32_16x16x32_bf16 v[44:47], v[116:119], v[172:175], v[44:47]
	v_mfma_f32_16x16x32_bf16 v[40:43], v[124:127], v[172:175], v[40:43]
	v_mfma_f32_16x16x32_bf16 v[28:31], v[116:119], v[180:183], v[28:31]
	v_mfma_f32_16x16x32_bf16 v[24:27], v[124:127], v[180:183], v[24:27]
	v_mfma_f32_16x16x32_bf16 v[12:15], v[116:119], v[188:191], v[12:15]
	v_mfma_f32_16x16x32_bf16 v[8:11], v[124:127], v[188:191], v[8:11]
	v_mfma_f32_16x16x32_bf16 v[52:55], v[136:139], v[160:163], v[52:55]
	v_mfma_f32_16x16x32_bf16 v[48:51], v[152:155], v[160:163], v[48:51]
	v_mfma_f32_16x16x32_bf16 v[36:39], v[136:139], v[168:171], v[36:39]
	v_mfma_f32_16x16x32_bf16 v[32:35], v[152:155], v[168:171], v[32:35]
	v_mfma_f32_16x16x32_bf16 v[20:23], v[136:139], v[176:179], v[20:23]
	v_mfma_f32_16x16x32_bf16 v[16:19], v[152:155], v[176:179], v[16:19]
	v_mfma_f32_16x16x32_bf16 v[4:7], v[136:139], v[184:187], v[4:7]
	v_mfma_f32_16x16x32_bf16 v[0:3], v[152:155], v[184:187], v[0:3]
	v_mfma_f32_16x16x32_bf16 v[52:55], v[140:143], v[164:167], v[52:55]
	v_mfma_f32_16x16x32_bf16 v[48:51], v[156:159], v[164:167], v[48:51]
	v_mfma_f32_16x16x32_bf16 v[36:39], v[140:143], v[172:175], v[36:39]
	v_mfma_f32_16x16x32_bf16 v[32:35], v[156:159], v[172:175], v[32:35]
	v_mfma_f32_16x16x32_bf16 v[20:23], v[140:143], v[180:183], v[20:23]
	v_mfma_f32_16x16x32_bf16 v[16:19], v[156:159], v[180:183], v[16:19]
	v_mfma_f32_16x16x32_bf16 v[4:7], v[140:143], v[188:191], v[4:7]
	v_mfma_f32_16x16x32_bf16 v[0:3], v[156:159], v[188:191], v[0:3]
	s_barrier
	s_setprio 0
	s_add_i32 s65, 0, 0x18000
	s_add_i32 s66, 0, 0x1c000
	v_add_u32_e32 v124, s65, v244
	v_add_u32_e32 v156, s66, v244
	ds_read_b128 v[112:115], v124
	ds_read_b128 v[116:119], v124 offset:1024
	ds_read_b128 v[120:123], v124 offset:2048
	ds_read_b128 v[124:127], v124 offset:3072
	ds_read_b128 v[136:139], v156
	ds_read_b128 v[140:143], v156 offset:1024
	ds_read_b128 v[152:155], v156 offset:2048
	ds_read_b128 v[156:159], v156 offset:3072
	s_add_u32 s38, s38, 0xb0000
	s_addc_u32 s39, s39, 0
	s_mov_b32 m0, s47
	v_lshl_add_u64 v[214:215], s[38:39], 0, v[192:193]
	ds_read_b128 v[160:163], v248 offset:32768
	ds_read_b128 v[164:167], v248 offset:33792
	ds_read_b128 v[168:171], v248 offset:34816
	ds_read_b128 v[172:175], v248 offset:35840
	ds_read_b128 v[176:179], v248 offset:36864
	ds_read_b128 v[180:183], v248 offset:37888
	ds_read_b128 v[184:187], v248 offset:38912
	ds_read_b128 v[188:191], v248 offset:39936
	global_load_lds_dwordx4 v[214:215], off
	v_lshl_add_u64 v[214:215], s[38:39], 0, v[196:197]
	s_mov_b32 m0, s48
	s_nop 0
	global_load_lds_dwordx4 v[214:215], off
	s_waitcnt vmcnt(8)
	s_waitcnt lgkmcnt(0)
	s_setprio 1
	s_barrier
	v_mfma_f32_16x16x32_bf16 v[148:151], v[112:115], v[160:163], v[148:151]
	v_mfma_f32_16x16x32_bf16 v[144:147], v[120:123], v[160:163], v[144:147]
	v_mfma_f32_16x16x32_bf16 v[108:111], v[112:115], v[168:171], v[108:111]
	v_mfma_f32_16x16x32_bf16 v[104:107], v[120:123], v[168:171], v[104:107]
	v_mfma_f32_16x16x32_bf16 v[92:95], v[112:115], v[176:179], v[92:95]
	v_mfma_f32_16x16x32_bf16 v[88:91], v[120:123], v[176:179], v[88:91]
	v_mfma_f32_16x16x32_bf16 v[76:79], v[112:115], v[184:187], v[76:79]
	v_mfma_f32_16x16x32_bf16 v[72:75], v[120:123], v[184:187], v[72:75]
	v_mfma_f32_16x16x32_bf16 v[148:151], v[116:119], v[164:167], v[148:151]
	v_mfma_f32_16x16x32_bf16 v[144:147], v[124:127], v[164:167], v[144:147]
	v_mfma_f32_16x16x32_bf16 v[108:111], v[116:119], v[172:175], v[108:111]
	v_mfma_f32_16x16x32_bf16 v[104:107], v[124:127], v[172:175], v[104:107]
	v_mfma_f32_16x16x32_bf16 v[92:95], v[116:119], v[180:183], v[92:95]
	v_mfma_f32_16x16x32_bf16 v[88:91], v[124:127], v[180:183], v[88:91]
	v_mfma_f32_16x16x32_bf16 v[76:79], v[116:119], v[188:191], v[76:79]
	v_mfma_f32_16x16x32_bf16 v[72:75], v[124:127], v[188:191], v[72:75]
	v_mfma_f32_16x16x32_bf16 v[132:135], v[136:139], v[160:163], v[132:135]
	v_mfma_f32_16x16x32_bf16 v[128:131], v[152:155], v[160:163], v[128:131]
	v_mfma_f32_16x16x32_bf16 v[100:103], v[136:139], v[168:171], v[100:103]
	v_mfma_f32_16x16x32_bf16 v[96:99], v[152:155], v[168:171], v[96:99]
	v_mfma_f32_16x16x32_bf16 v[84:87], v[136:139], v[176:179], v[84:87]
	v_mfma_f32_16x16x32_bf16 v[80:83], v[152:155], v[176:179], v[80:83]
	v_mfma_f32_16x16x32_bf16 v[68:71], v[136:139], v[184:187], v[68:71]
	v_mfma_f32_16x16x32_bf16 v[64:67], v[152:155], v[184:187], v[64:67]
	v_mfma_f32_16x16x32_bf16 v[132:135], v[140:143], v[164:167], v[132:135]
	v_mfma_f32_16x16x32_bf16 v[128:131], v[156:159], v[164:167], v[128:131]
	v_mfma_f32_16x16x32_bf16 v[100:103], v[140:143], v[172:175], v[100:103]
	v_mfma_f32_16x16x32_bf16 v[96:99], v[156:159], v[172:175], v[96:99]
	v_mfma_f32_16x16x32_bf16 v[84:87], v[140:143], v[180:183], v[84:87]
	v_mfma_f32_16x16x32_bf16 v[80:83], v[156:159], v[180:183], v[80:83]
	v_mfma_f32_16x16x32_bf16 v[68:71], v[140:143], v[188:191], v[68:71]
	v_mfma_f32_16x16x32_bf16 v[64:67], v[156:159], v[188:191], v[64:67]
	s_barrier
; #define PG8_STAGE(bufoff, gbase, voff) do { _Pragma("unroll") for (int _i = 0; _i < 2; ++_i) \
;         __builtin_amdgcn_global_load_lds((const unsigned*)((const char*)(gbase) + (voff)[_i]), (PG8_LAS unsigned*)(lds + (bufoff) + ldsw + _i * 8192), 16, 0, 0); } while (0)
; #define PG8_LDA(dst, b, h) do { _Pragma("unroll") for (int m = 0; m < 4; ++m) _Pragma("unroll") for (int k = 0; k < 2; ++k) dst[m][k] = *(const PG8_LAS bf16x8*)(lds + PG8_SA(b, h) + aoff + m * 2048 + k * 1024); } while (0)
; #define PG8_MMA(ai, bj, At, Bt) do { __builtin_amdgcn_s_setprio(1); _Pragma("unroll") for (int m = 0; m < 4; ++m) _Pragma("unroll") for (int n = 0; n < 2; ++n) _Pragma("unroll") for (int k = 0; k < 2; ++k) \
;         acc[ai][bj][m][n] = __builtin_amdgcn_mfma_f32_16x16x32_bf16(Bt[n][k], At[m][k], acc[ai][bj][m][n], 0, 0, 0); __builtin_amdgcn_s_setprio(0); } while (0)
; #define PG8_WAIT_V(n) asm volatile("s_waitcnt vmcnt(" #n ")" ::: "memory")
; #define PG8_WAIT_L(n) asm volatile("s_waitcnt lgkmcnt(" #n ")" ::: "memory")
; #define PG8_BAR __builtin_amdgcn_s_barrier()
; #define PG8_SCHED __builtin_amdgcn_sched_barrier(0)
; template <class Epi, class Sched, bool ALIGN_EPI = false, bool SP2 = false>
; __device__ __forceinline__ void gemm_phase(PG8_LAS unsigned char* lds, const Gemm g, const Sched& S, const Epi& E) {
;     ...
;             PG8_LDA(At, 1, 1); PG8_STAGE(PG8_SB(1, 0), b3, voffB); PG8_STAGE(PG8_SB(1, 1), b3 + hstep, voffB); PG8_STAGE(PG8_SA(1, 0), a3, voffA);
;             PG8_WAIT_V(8); PG8_WAIT_L(0); PG8_BAR; PG8_MMA(1, 0, At, B0); PG8_MMA(1, 1, At, B1); PG8_BAR; PG8_SCHED;
;     ...
;         if constexpr (ALIGN_EPI) { if (wr == 0) PG8_BAR; }
	s_setprio 0
	s_add_i32 s38, s65, s44
	v_lshl_add_u64 v[206:207], v[206:207], 0, s[18:19]
	s_mov_b32 m0, s38
	ds_read_b128 v[160:163], v248 offset:49152
	ds_read_b128 v[164:167], v248 offset:50176
	ds_read_b128 v[168:171], v248 offset:51200
	ds_read_b128 v[172:175], v248 offset:52224
	ds_read_b128 v[176:179], v248 offset:53248
	ds_read_b128 v[180:183], v248 offset:54272
	ds_read_b128 v[184:187], v248 offset:55296
	ds_read_b128 v[188:191], v248 offset:56320
	global_load_lds_dwordx4 v[206:207], off
	s_add_i32 m0, s38, 0x2000
	s_add_u32 s36, s36, 0xb0080
	v_lshl_add_u64 v[206:207], v[208:209], 0, s[18:19]
	s_addc_u32 s37, s37, 0
	s_add_i32 s38, s66, s44
	global_load_lds_dwordx4 v[206:207], off
	v_lshl_add_u64 v[206:207], s[36:37], 0, v[194:195]
	s_mov_b32 m0, s38
	s_nop 0
	global_load_lds_dwordx4 v[206:207], off
	v_lshl_add_u64 v[206:207], s[36:37], 0, v[198:199]
	s_add_i32 m0, s38, 0x2000
	s_nop 0
	global_load_lds_dwordx4 v[206:207], off
	v_lshl_add_u64 v[206:207], v[210:211], 0, s[18:19]
	s_mov_b32 m0, s50
	s_nop 0
	global_load_lds_dwordx4 v[206:207], off
	v_lshl_add_u64 v[206:207], v[212:213], 0, s[18:19]
	s_mov_b32 m0, s51
	s_nop 0
	global_load_lds_dwordx4 v[206:207], off
	s_waitcnt vmcnt(8)
	s_waitcnt lgkmcnt(0)
	s_setprio 1
	s_barrier
	v_mfma_f32_16x16x32_bf16 v[60:63], v[112:115], v[160:163], v[60:63]
	v_mfma_f32_16x16x32_bf16 v[56:59], v[120:123], v[160:163], v[56:59]
	v_mfma_f32_16x16x32_bf16 v[44:47], v[112:115], v[168:171], v[44:47]
	v_mfma_f32_16x16x32_bf16 v[40:43], v[120:123], v[168:171], v[40:43]
	v_mfma_f32_16x16x32_bf16 v[28:31], v[112:115], v[176:179], v[28:31]
	v_mfma_f32_16x16x32_bf16 v[24:27], v[120:123], v[176:179], v[24:27]
	v_mfma_f32_16x16x32_bf16 v[12:15], v[112:115], v[184:187], v[12:15]
	v_mfma_f32_16x16x32_bf16 v[8:11], v[120:123], v[184:187], v[8:11]
	v_mfma_f32_16x16x32_bf16 v[60:63], v[116:119], v[164:167], v[60:63]
	v_mfma_f32_16x16x32_bf16 v[56:59], v[124:127], v[164:167], v[56:59]
	v_mfma_f32_16x16x32_bf16 v[44:47], v[116:119], v[172:175], v[44:47]
	v_mfma_f32_16x16x32_bf16 v[40:43], v[124:127], v[172:175], v[40:43]
	v_mfma_f32_16x16x32_bf16 v[28:31], v[116:119], v[180:183], v[28:31]
	v_mfma_f32_16x16x32_bf16 v[24:27], v[124:127], v[180:183], v[24:27]
	v_mfma_f32_16x16x32_bf16 v[12:15], v[116:119], v[188:191], v[12:15]
	v_mfma_f32_16x16x32_bf16 v[8:11], v[124:127], v[188:191], v[8:11]
	v_mfma_f32_16x16x32_bf16 v[52:55], v[136:139], v[160:163], v[52:55]
	v_mfma_f32_16x16x32_bf16 v[48:51], v[152:155], v[160:163], v[48:51]
	v_mfma_f32_16x16x32_bf16 v[36:39], v[136:139], v[168:171], v[36:39]
	v_mfma_f32_16x16x32_bf16 v[32:35], v[152:155], v[168:171], v[32:35]
	v_mfma_f32_16x16x32_bf16 v[20:23], v[136:139], v[176:179], v[20:23]
	v_mfma_f32_16x16x32_bf16 v[16:19], v[152:155], v[176:179], v[16:19]
	v_mfma_f32_16x16x32_bf16 v[4:7], v[136:139], v[184:187], v[4:7]
	v_mfma_f32_16x16x32_bf16 v[0:3], v[152:155], v[184:187], v[0:3]
	v_mfma_f32_16x16x32_bf16 v[52:55], v[140:143], v[164:167], v[52:55]
	v_mfma_f32_16x16x32_bf16 v[48:51], v[156:159], v[164:167], v[48:51]
	v_mfma_f32_16x16x32_bf16 v[36:39], v[140:143], v[172:175], v[36:39]
	v_mfma_f32_16x16x32_bf16 v[32:35], v[156:159], v[172:175], v[32:35]
	v_mfma_f32_16x16x32_bf16 v[20:23], v[140:143], v[180:183], v[20:23]
	v_mfma_f32_16x16x32_bf16 v[16:19], v[156:159], v[180:183], v[16:19]
	v_mfma_f32_16x16x32_bf16 v[4:7], v[140:143], v[188:191], v[4:7]
	v_mfma_f32_16x16x32_bf16 v[0:3], v[156:159], v[188:191], v[0:3]
	s_barrier
	s_setprio 0
	s_add_i32 s64, s64, 2
	s_add_u32 s34, s34, 0x100
	s_addc_u32 s35, s35, 0
	s_add_u32 s59, s59, 0x100
	s_addc_u32 s63, s63, 0
	s_cmp_gt_u32 s64, 41
	s_cbranch_scc0 .LBB0_406
	s_and_b64 vcc, exec, s[20:21]
	s_cbranch_vccz .LBB0_409
	s_barrier

; #define PG8_STAGE(bufoff, gbase, voff) do { _Pragma("unroll") for (int _i = 0; _i < 2; ++_i) \
;         __builtin_amdgcn_global_load_lds((const unsigned*)((const char*)(gbase) + (voff)[_i]), (PG8_LAS unsigned*)(lds + (bufoff) + ldsw + _i * 8192), 16, 0, 0); } while (0)
; #define PG8_LDA(dst, b, h) do { _Pragma("unroll") for (int m = 0; m < 4; ++m) _Pragma("unroll") for (int k = 0; k < 2; ++k) dst[m][k] = *(const PG8_LAS bf16x8*)(lds + PG8_SA(b, h) + aoff + m * 2048 + k * 1024); } while (0)
; #define PG8_LDB(dst, b, h) do { _Pragma("unroll") for (int n = 0; n < 2; ++n) _Pragma("unroll") for (int k = 0; k < 2; ++k) dst[n][k] = *(const PG8_LAS bf16x8*)(lds + PG8_SB(b, h) + boff + n * 2048 + k * 1024); } while (0)
; #define PG8_MMA(ai, bj, At, Bt) do { __builtin_amdgcn_s_setprio(1); _Pragma("unroll") for (int m = 0; m < 4; ++m) _Pragma("unroll") for (int n = 0; n < 2; ++n) _Pragma("unroll") for (int k = 0; k < 2; ++k) \
;         acc[ai][bj][m][n] = __builtin_amdgcn_mfma_f32_16x16x32_bf16(Bt[n][k], At[m][k], acc[ai][bj][m][n], 0, 0, 0); __builtin_amdgcn_s_setprio(0); } while (0)
; #define PG8_WAIT_V(n) asm volatile("s_waitcnt vmcnt(" #n ")" ::: "memory")
; #define PG8_WAIT_L(n) asm volatile("s_waitcnt lgkmcnt(" #n ")" ::: "memory")
; #define PG8_BAR __builtin_amdgcn_s_barrier()
; template <class Epi, class Sched, bool ALIGN_EPI = false, bool SP2 = false>
; __device__ __forceinline__ void gemm_phase(PG8_LAS unsigned char* lds, const Gemm g, const Sched& S, const Epi& E) {
;     ...
;             const char* a1 = cA + (size_t)(t + 1) * kstep;
;             const char* a2 = last ? nA : cA + (size_t)(t + 2) * kstep; const char* b2 = last ? nB : cB + (size_t)(t + 2) * kstep;
;             const char* a3 = a2 + kstep; const char* b3 = b2 + kstep;
;             if (last && has_next) S.a_ready(nxt);
;             if constexpr (SP2) {
;             PG8_LDB(B0, 0, 0); PG8_LDB(B1, 0, 1); PG8_SCHED; PG8_LDA(At, 0, 0); PG8_STAGE(PG8_SA(1, 1), a1 + hstep, voffA);
;             PG8_WAIT_V(8); PG8_WAIT_L(0); PG8_BAR; PG8_MMA(0, 0, At, B0); PG8_MMA(0, 1, At, B1); PG8_BAR; PG8_SCHED;
;             PG8_LDA(At, 0, 1); PG8_STAGE(PG8_SB(0, 0), b2, voffB); PG8_STAGE(PG8_SB(0, 1), b2 + hstep, voffB); PG8_STAGE(PG8_SA(0, 0), a2, voffA);
;             PG8_WAIT_V(8); PG8_WAIT_L(0); PG8_BAR; PG8_MMA(1, 0, At, B0); PG8_MMA(1, 1, At, B1); PG8_BAR; PG8_SCHED;
.LBB0_593:
	ds_read_b128 v[144:147], v151
	ds_read_b128 v[156:159], v151 offset:1024
	ds_read_b128 v[160:163], v151 offset:2048
	ds_read_b128 v[164:167], v151 offset:3072
	ds_read_b128 v[168:171], v152
	ds_read_b128 v[172:175], v152 offset:1024
	ds_read_b128 v[176:179], v152 offset:2048
	ds_read_b128 v[180:183], v152 offset:3072
	s_add_u32 s46, s44, 0xfffc0080
	s_addc_u32 s47, s45, -1
	s_cmp_eq_u32 s80, 12
	s_cselect_b32 s49, s37, s47
	s_cselect_b32 s48, s76, s46
	s_cselect_b32 s47, s35, s79
	s_cselect_b32 s46, s77, s78
	v_lshl_add_u64 v[216:217], s[44:45], 0, v[136:137]
	s_add_i32 m0, s43, 0xc000
	ds_read_b128 v[184:187], v153
	ds_read_b128 v[188:191], v153 offset:1024
	ds_read_b128 v[192:195], v153 offset:2048
	ds_read_b128 v[196:199], v153 offset:3072
	ds_read_b128 v[200:203], v153 offset:4096
	ds_read_b128 v[204:207], v153 offset:5120
	ds_read_b128 v[208:211], v153 offset:6144
	ds_read_b128 v[212:215], v153 offset:7168
	global_load_lds_dwordx4 v[216:217], off
	v_lshl_add_u64 v[216:217], s[44:45], 0, v[138:139]
	s_add_i32 m0, s43, 0xe000
	s_nop 0
	global_load_lds_dwordx4 v[216:217], off
	s_waitcnt vmcnt(8)
	s_waitcnt lgkmcnt(0)
	s_setprio 1
	s_barrier
	v_mfma_f32_16x16x32_bf16 v[124:127], v[144:147], v[184:187], v[124:127]
	v_mfma_f32_16x16x32_bf16 v[120:123], v[160:163], v[184:187], v[120:123]
	v_mfma_f32_16x16x32_bf16 v[108:111], v[144:147], v[192:195], v[108:111]
	v_mfma_f32_16x16x32_bf16 v[104:107], v[160:163], v[192:195], v[104:107]
	v_mfma_f32_16x16x32_bf16 v[92:95], v[144:147], v[200:203], v[92:95]
	v_mfma_f32_16x16x32_bf16 v[88:91], v[160:163], v[200:203], v[88:91]
	v_mfma_f32_16x16x32_bf16 v[76:79], v[144:147], v[208:211], v[76:79]
	v_mfma_f32_16x16x32_bf16 v[72:75], v[160:163], v[208:211], v[72:75]
	v_mfma_f32_16x16x32_bf16 v[124:127], v[156:159], v[188:191], v[124:127]
	v_mfma_f32_16x16x32_bf16 v[120:123], v[164:167], v[188:191], v[120:123]
	v_mfma_f32_16x16x32_bf16 v[108:111], v[156:159], v[196:199], v[108:111]
	v_mfma_f32_16x16x32_bf16 v[104:107], v[164:167], v[196:199], v[104:107]
	v_mfma_f32_16x16x32_bf16 v[92:95], v[156:159], v[204:207], v[92:95]
	v_mfma_f32_16x16x32_bf16 v[88:91], v[164:167], v[204:207], v[88:91]
	v_mfma_f32_16x16x32_bf16 v[76:79], v[156:159], v[212:215], v[76:79]
	v_mfma_f32_16x16x32_bf16 v[72:75], v[164:167], v[212:215], v[72:75]
	v_mfma_f32_16x16x32_bf16 v[116:119], v[168:171], v[184:187], v[116:119]
	v_mfma_f32_16x16x32_bf16 v[112:115], v[176:179], v[184:187], v[112:115]
	v_mfma_f32_16x16x32_bf16 v[100:103], v[168:171], v[192:195], v[100:103]
	v_mfma_f32_16x16x32_bf16 v[96:99], v[176:179], v[192:195], v[96:99]
	v_mfma_f32_16x16x32_bf16 v[84:87], v[168:171], v[200:203], v[84:87]
	v_mfma_f32_16x16x32_bf16 v[80:83], v[176:179], v[200:203], v[80:83]
	v_mfma_f32_16x16x32_bf16 v[68:71], v[168:171], v[208:211], v[68:71]
	v_mfma_f32_16x16x32_bf16 v[64:67], v[176:179], v[208:211], v[64:67]
	v_mfma_f32_16x16x32_bf16 v[116:119], v[172:175], v[188:191], v[116:119]
	v_mfma_f32_16x16x32_bf16 v[112:115], v[180:183], v[188:191], v[112:115]
	v_mfma_f32_16x16x32_bf16 v[100:103], v[172:175], v[196:199], v[100:103]
	v_mfma_f32_16x16x32_bf16 v[96:99], v[180:183], v[196:199], v[96:99]
	v_mfma_f32_16x16x32_bf16 v[84:87], v[172:175], v[204:207], v[84:87]
	v_mfma_f32_16x16x32_bf16 v[80:83], v[180:183], v[204:207], v[80:83]
	v_mfma_f32_16x16x32_bf16 v[68:71], v[172:175], v[212:215], v[68:71]
	v_mfma_f32_16x16x32_bf16 v[64:67], v[180:183], v[212:215], v[64:67]
	s_barrier
	s_setprio 0
	s_add_i32 s81, s69, s52
	v_lshl_add_u64 v[216:217], s[46:47], 0, v[132:133]
	s_mov_b32 m0, s81
	ds_read_b128 v[184:187], v153 offset:16384
	ds_read_b128 v[188:191], v153 offset:17408
	ds_read_b128 v[192:195], v153 offset:18432
	ds_read_b128 v[196:199], v153 offset:19456
	ds_read_b128 v[200:203], v153 offset:20480
	ds_read_b128 v[204:207], v153 offset:21504
	ds_read_b128 v[208:211], v153 offset:22528
	ds_read_b128 v[212:215], v153 offset:23552
	global_load_lds_dwordx4 v[216:217], off
	s_add_i32 m0, s81, 0x2000
	s_add_u32 s82, s46, 0x40000
	v_lshl_add_u64 v[218:219], s[46:47], 0, v[128:129]
	s_addc_u32 s83, s47, 0
	s_add_i32 s81, s70, s52
	global_load_lds_dwordx4 v[218:219], off
	v_lshl_add_u64 v[220:221], s[82:83], 0, v[132:133]
	s_mov_b32 m0, s81
	v_lshl_add_u64 v[222:223], s[48:49], 0, v[130:131]
	global_load_lds_dwordx4 v[220:221], off
	v_lshl_add_u64 v[220:221], s[82:83], 0, v[128:129]
	s_add_i32 m0, s81, 0x2000
	s_nop 0
	global_load_lds_dwordx4 v[220:221], off
	v_lshl_add_u64 v[220:221], s[48:49], 0, v[134:135]
	s_mov_b32 m0, s43
	s_nop 0
	global_load_lds_dwordx4 v[220:221], off
	s_mov_b32 m0, s56
	s_nop 0
	global_load_lds_dwordx4 v[222:223], off
	s_waitcnt vmcnt(8)
	s_waitcnt lgkmcnt(0)
	s_setprio 1
	s_barrier
; #define PG8_STAGE(bufoff, gbase, voff) do { _Pragma("unroll") for (int _i = 0; _i < 2; ++_i) \
;         __builtin_amdgcn_global_load_lds((const unsigned*)((const char*)(gbase) + (voff)[_i]), (PG8_LAS unsigned*)(lds + (bufoff) + ldsw + _i * 8192), 16, 0, 0); } while (0)
; #define PG8_LDA(dst, b, h) do { _Pragma("unroll") for (int m = 0; m < 4; ++m) _Pragma("unroll") for (int k = 0; k < 2; ++k) dst[m][k] = *(const PG8_LAS bf16x8*)(lds + PG8_SA(b, h) + aoff + m * 2048 + k * 1024); } while (0)
; #define PG8_LDB(dst, b, h) do { _Pragma("unroll") for (int n = 0; n < 2; ++n) _Pragma("unroll") for (int k = 0; k < 2; ++k) dst[n][k] = *(const PG8_LAS bf16x8*)(lds + PG8_SB(b, h) + boff + n * 2048 + k * 1024); } while (0)
; #define PG8_MMA(ai, bj, At, Bt) do { __builtin_amdgcn_s_setprio(1); _Pragma("unroll") for (int m = 0; m < 4; ++m) _Pragma("unroll") for (int n = 0; n < 2; ++n) _Pragma("unroll") for (int k = 0; k < 2; ++k) \
;         acc[ai][bj][m][n] = __builtin_amdgcn_mfma_f32_16x16x32_bf16(Bt[n][k], At[m][k], acc[ai][bj][m][n], 0, 0, 0); __builtin_amdgcn_s_setprio(0); } while (0)
; #define PG8_WAIT_V(n) asm volatile("s_waitcnt vmcnt(" #n ")" ::: "memory")
; #define PG8_WAIT_L(n) asm volatile("s_waitcnt lgkmcnt(" #n ")" ::: "memory")
; #define PG8_BAR __builtin_amdgcn_s_barrier()
; #define PG8_SCHED __builtin_amdgcn_sched_barrier(0)
; template <class Epi, class Sched, bool ALIGN_EPI = false, bool SP2 = false>
; __device__ __forceinline__ void gemm_phase(PG8_LAS unsigned char* lds, const Gemm g, const Sched& S, const Epi& E) {
;     ...
;             PG8_WAIT_V(8); PG8_WAIT_L(0); PG8_BAR; PG8_MMA(1, 0, At, B0); PG8_MMA(1, 1, At, B1); PG8_BAR; PG8_SCHED;
;             PG8_LDB(B0, 1, 0); PG8_LDB(B1, 1, 1); PG8_SCHED; PG8_LDA(At, 1, 0); PG8_STAGE(PG8_SA(0, 1), a2 + hstep, voffA);
;             PG8_WAIT_V(8); PG8_WAIT_L(0); PG8_BAR; PG8_MMA(0, 0, At, B0); PG8_MMA(0, 1, At, B1); PG8_BAR; PG8_SCHED;
	v_mfma_f32_16x16x32_bf16 v[60:63], v[144:147], v[184:187], v[60:63]
	v_mfma_f32_16x16x32_bf16 v[56:59], v[160:163], v[184:187], v[56:59]
	v_mfma_f32_16x16x32_bf16 v[44:47], v[144:147], v[192:195], v[44:47]
	v_mfma_f32_16x16x32_bf16 v[40:43], v[160:163], v[192:195], v[40:43]
	v_mfma_f32_16x16x32_bf16 v[28:31], v[144:147], v[200:203], v[28:31]
	v_mfma_f32_16x16x32_bf16 v[24:27], v[160:163], v[200:203], v[24:27]
	v_mfma_f32_16x16x32_bf16 v[12:15], v[144:147], v[208:211], v[12:15]
	v_mfma_f32_16x16x32_bf16 v[8:11], v[160:163], v[208:211], v[8:11]
	v_mfma_f32_16x16x32_bf16 v[60:63], v[156:159], v[188:191], v[60:63]
	v_mfma_f32_16x16x32_bf16 v[56:59], v[164:167], v[188:191], v[56:59]
	v_mfma_f32_16x16x32_bf16 v[44:47], v[156:159], v[196:199], v[44:47]
	v_mfma_f32_16x16x32_bf16 v[40:43], v[164:167], v[196:199], v[40:43]
	v_mfma_f32_16x16x32_bf16 v[28:31], v[156:159], v[204:207], v[28:31]
	v_mfma_f32_16x16x32_bf16 v[24:27], v[164:167], v[204:207], v[24:27]
	v_mfma_f32_16x16x32_bf16 v[12:15], v[156:159], v[212:215], v[12:15]
	v_mfma_f32_16x16x32_bf16 v[8:11], v[164:167], v[212:215], v[8:11]
	v_mfma_f32_16x16x32_bf16 v[52:55], v[168:171], v[184:187], v[52:55]
	v_mfma_f32_16x16x32_bf16 v[48:51], v[176:179], v[184:187], v[48:51]
	v_mfma_f32_16x16x32_bf16 v[36:39], v[168:171], v[192:195], v[36:39]
	v_mfma_f32_16x16x32_bf16 v[32:35], v[176:179], v[192:195], v[32:35]
	v_mfma_f32_16x16x32_bf16 v[20:23], v[168:171], v[200:203], v[20:23]
	v_mfma_f32_16x16x32_bf16 v[16:19], v[176:179], v[200:203], v[16:19]
	v_mfma_f32_16x16x32_bf16 v[4:7], v[168:171], v[208:211], v[4:7]
	v_mfma_f32_16x16x32_bf16 v[0:3], v[176:179], v[208:211], v[0:3]
	v_mfma_f32_16x16x32_bf16 v[52:55], v[172:175], v[188:191], v[52:55]
	v_mfma_f32_16x16x32_bf16 v[48:51], v[180:183], v[188:191], v[48:51]
	v_mfma_f32_16x16x32_bf16 v[36:39], v[172:175], v[196:199], v[36:39]
	v_mfma_f32_16x16x32_bf16 v[32:35], v[180:183], v[196:199], v[32:35]
	v_mfma_f32_16x16x32_bf16 v[20:23], v[172:175], v[204:207], v[20:23]
	v_mfma_f32_16x16x32_bf16 v[16:19], v[180:183], v[204:207], v[16:19]
	v_mfma_f32_16x16x32_bf16 v[4:7], v[172:175], v[212:215], v[4:7]
	v_mfma_f32_16x16x32_bf16 v[0:3], v[180:183], v[212:215], v[0:3]
	s_barrier
	s_setprio 0
	s_add_i32 s81, 0, 0x18000
	s_add_i32 s82, 0, 0x1c000
	v_add_u32_e32 v164, s81, v149
	v_add_u32_e32 v180, s82, v149
	ds_read_b128 v[144:147], v164
	ds_read_b128 v[156:159], v164 offset:1024
	ds_read_b128 v[160:163], v164 offset:2048
	ds_read_b128 v[164:167], v164 offset:3072
	ds_read_b128 v[168:171], v180
	ds_read_b128 v[172:175], v180 offset:1024
	ds_read_b128 v[176:179], v180 offset:2048
	ds_read_b128 v[180:183], v180 offset:3072
	s_add_u32 s48, s48, 0x40000
	s_addc_u32 s49, s49, 0
	s_mov_b32 m0, s57
	v_lshl_add_u64 v[224:225], s[48:49], 0, v[134:135]
	ds_read_b128 v[184:187], v153 offset:32768
	ds_read_b128 v[188:191], v153 offset:33792
	ds_read_b128 v[192:195], v153 offset:34816
	ds_read_b128 v[196:199], v153 offset:35840
	ds_read_b128 v[200:203], v153 offset:36864
	ds_read_b128 v[204:207], v153 offset:37888
	ds_read_b128 v[208:211], v153 offset:38912
	ds_read_b128 v[212:215], v153 offset:39936
	global_load_lds_dwordx4 v[224:225], off
	v_lshl_add_u64 v[224:225], s[48:49], 0, v[130:131]
	s_mov_b32 m0, s58
	s_nop 0
	global_load_lds_dwordx4 v[224:225], off
	s_waitcnt vmcnt(8)
	s_waitcnt lgkmcnt(0)
	s_setprio 1
	s_barrier
	v_mfma_f32_16x16x32_bf16 v[124:127], v[144:147], v[184:187], v[124:127]
	v_mfma_f32_16x16x32_bf16 v[120:123], v[160:163], v[184:187], v[120:123]
	v_mfma_f32_16x16x32_bf16 v[108:111], v[144:147], v[192:195], v[108:111]
	v_mfma_f32_16x16x32_bf16 v[104:107], v[160:163], v[192:195], v[104:107]
	v_mfma_f32_16x16x32_bf16 v[92:95], v[144:147], v[200:203], v[92:95]
	v_mfma_f32_16x16x32_bf16 v[88:91], v[160:163], v[200:203], v[88:91]
	v_mfma_f32_16x16x32_bf16 v[76:79], v[144:147], v[208:211], v[76:79]
	v_mfma_f32_16x16x32_bf16 v[72:75], v[160:163], v[208:211], v[72:75]
	v_mfma_f32_16x16x32_bf16 v[124:127], v[156:159], v[188:191], v[124:127]
	v_mfma_f32_16x16x32_bf16 v[120:123], v[164:167], v[188:191], v[120:123]
	v_mfma_f32_16x16x32_bf16 v[108:111], v[156:159], v[196:199], v[108:111]
	v_mfma_f32_16x16x32_bf16 v[104:107], v[164:167], v[196:199], v[104:107]
	v_mfma_f32_16x16x32_bf16 v[92:95], v[156:159], v[204:207], v[92:95]
	v_mfma_f32_16x16x32_bf16 v[88:91], v[164:167], v[204:207], v[88:91]
	v_mfma_f32_16x16x32_bf16 v[76:79], v[156:159], v[212:215], v[76:79]
	v_mfma_f32_16x16x32_bf16 v[72:75], v[164:167], v[212:215], v[72:75]
	v_mfma_f32_16x16x32_bf16 v[116:119], v[168:171], v[184:187], v[116:119]
	v_mfma_f32_16x16x32_bf16 v[112:115], v[176:179], v[184:187], v[112:115]
	v_mfma_f32_16x16x32_bf16 v[100:103], v[168:171], v[192:195], v[100:103]
	v_mfma_f32_16x16x32_bf16 v[96:99], v[176:179], v[192:195], v[96:99]
	v_mfma_f32_16x16x32_bf16 v[84:87], v[168:171], v[200:203], v[84:87]
	v_mfma_f32_16x16x32_bf16 v[80:83], v[176:179], v[200:203], v[80:83]
	v_mfma_f32_16x16x32_bf16 v[68:71], v[168:171], v[208:211], v[68:71]
	v_mfma_f32_16x16x32_bf16 v[64:67], v[176:179], v[208:211], v[64:67]
	v_mfma_f32_16x16x32_bf16 v[116:119], v[172:175], v[188:191], v[116:119]
	v_mfma_f32_16x16x32_bf16 v[112:115], v[180:183], v[188:191], v[112:115]
	v_mfma_f32_16x16x32_bf16 v[100:103], v[172:175], v[196:199], v[100:103]
	v_mfma_f32_16x16x32_bf16 v[96:99], v[180:183], v[196:199], v[96:99]
	v_mfma_f32_16x16x32_bf16 v[84:87], v[172:175], v[204:207], v[84:87]
	v_mfma_f32_16x16x32_bf16 v[80:83], v[180:183], v[204:207], v[80:83]
	v_mfma_f32_16x16x32_bf16 v[68:71], v[172:175], v[212:215], v[68:71]
	v_mfma_f32_16x16x32_bf16 v[64:67], v[180:183], v[212:215], v[64:67]
	s_barrier
; #define PG8_STAGE(bufoff, gbase, voff) do { _Pragma("unroll") for (int _i = 0; _i < 2; ++_i) \
;         __builtin_amdgcn_global_load_lds((const unsigned*)((const char*)(gbase) + (voff)[_i]), (PG8_LAS unsigned*)(lds + (bufoff) + ldsw + _i * 8192), 16, 0, 0); } while (0)
; #define PG8_LDA(dst, b, h) do { _Pragma("unroll") for (int m = 0; m < 4; ++m) _Pragma("unroll") for (int k = 0; k < 2; ++k) dst[m][k] = *(const PG8_LAS bf16x8*)(lds + PG8_SA(b, h) + aoff + m * 2048 + k * 1024); } while (0)
; #define PG8_MMA(ai, bj, At, Bt) do { __builtin_amdgcn_s_setprio(1); _Pragma("unroll") for (int m = 0; m < 4; ++m) _Pragma("unroll") for (int n = 0; n < 2; ++n) _Pragma("unroll") for (int k = 0; k < 2; ++k) \
;         acc[ai][bj][m][n] = __builtin_amdgcn_mfma_f32_16x16x32_bf16(Bt[n][k], At[m][k], acc[ai][bj][m][n], 0, 0, 0); __builtin_amdgcn_s_setprio(0); } while (0)
; #define PG8_WAIT_V(n) asm volatile("s_waitcnt vmcnt(" #n ")" ::: "memory")
; #define PG8_WAIT_L(n) asm volatile("s_waitcnt lgkmcnt(" #n ")" ::: "memory")
; #define PG8_BAR __builtin_amdgcn_s_barrier()
; #define PG8_SCHED __builtin_amdgcn_sched_barrier(0)
; template <class Epi, class Sched, bool ALIGN_EPI = false, bool SP2 = false>
; __device__ __forceinline__ void gemm_phase(PG8_LAS unsigned char* lds, const Gemm g, const Sched& S, const Epi& E) {
;     ...
;             PG8_LDA(At, 1, 1); PG8_STAGE(PG8_SB(1, 0), b3, voffB); PG8_STAGE(PG8_SB(1, 1), b3 + hstep, voffB); PG8_STAGE(PG8_SA(1, 0), a3, voffA);
;             PG8_WAIT_V(8); PG8_WAIT_L(0); PG8_BAR; PG8_MMA(1, 0, At, B0); PG8_MMA(1, 1, At, B1); PG8_BAR; PG8_SCHED;
;     ...
;         if constexpr (ALIGN_EPI) { if (wr == 0) PG8_BAR; }
	s_setprio 0
	s_add_i32 s48, s81, s52
	v_lshl_add_u64 v[216:217], v[216:217], 0, s[14:15]
	s_mov_b32 m0, s48
	ds_read_b128 v[184:187], v153 offset:49152
	ds_read_b128 v[188:191], v153 offset:50176
	ds_read_b128 v[192:195], v153 offset:51200
	ds_read_b128 v[196:199], v153 offset:52224
	ds_read_b128 v[200:203], v153 offset:53248
	ds_read_b128 v[204:207], v153 offset:54272
	ds_read_b128 v[208:211], v153 offset:55296
	ds_read_b128 v[212:215], v153 offset:56320
	global_load_lds_dwordx4 v[216:217], off
	s_add_i32 m0, s48, 0x2000
	s_add_u32 s46, s46, 0x40080
	v_lshl_add_u64 v[216:217], v[218:219], 0, s[14:15]
	s_addc_u32 s47, s47, 0
	s_add_i32 s48, s82, s52
	global_load_lds_dwordx4 v[216:217], off
	v_lshl_add_u64 v[216:217], s[46:47], 0, v[132:133]
	s_mov_b32 m0, s48
	s_nop 0
	global_load_lds_dwordx4 v[216:217], off
	v_lshl_add_u64 v[216:217], s[46:47], 0, v[128:129]
	s_add_i32 m0, s48, 0x2000
	s_nop 0
	global_load_lds_dwordx4 v[216:217], off
	v_lshl_add_u64 v[216:217], v[220:221], 0, s[14:15]
	s_mov_b32 m0, s65
	s_nop 0
	global_load_lds_dwordx4 v[216:217], off
	v_lshl_add_u64 v[216:217], v[222:223], 0, s[14:15]
	s_mov_b32 m0, s66
	s_nop 0
	global_load_lds_dwordx4 v[216:217], off
	s_waitcnt vmcnt(8)
	s_waitcnt lgkmcnt(0)
	s_setprio 1
	s_barrier
	v_mfma_f32_16x16x32_bf16 v[60:63], v[144:147], v[184:187], v[60:63]
	v_mfma_f32_16x16x32_bf16 v[56:59], v[160:163], v[184:187], v[56:59]
	v_mfma_f32_16x16x32_bf16 v[44:47], v[144:147], v[192:195], v[44:47]
	v_mfma_f32_16x16x32_bf16 v[40:43], v[160:163], v[192:195], v[40:43]
	v_mfma_f32_16x16x32_bf16 v[28:31], v[144:147], v[200:203], v[28:31]
	v_mfma_f32_16x16x32_bf16 v[24:27], v[160:163], v[200:203], v[24:27]
	v_mfma_f32_16x16x32_bf16 v[12:15], v[144:147], v[208:211], v[12:15]
	v_mfma_f32_16x16x32_bf16 v[8:11], v[160:163], v[208:211], v[8:11]
	v_mfma_f32_16x16x32_bf16 v[60:63], v[156:159], v[188:191], v[60:63]
	v_mfma_f32_16x16x32_bf16 v[56:59], v[164:167], v[188:191], v[56:59]
	v_mfma_f32_16x16x32_bf16 v[44:47], v[156:159], v[196:199], v[44:47]
	v_mfma_f32_16x16x32_bf16 v[40:43], v[164:167], v[196:199], v[40:43]
	v_mfma_f32_16x16x32_bf16 v[28:31], v[156:159], v[204:207], v[28:31]
	v_mfma_f32_16x16x32_bf16 v[24:27], v[164:167], v[204:207], v[24:27]
	v_mfma_f32_16x16x32_bf16 v[12:15], v[156:159], v[212:215], v[12:15]
	v_mfma_f32_16x16x32_bf16 v[8:11], v[164:167], v[212:215], v[8:11]
	v_mfma_f32_16x16x32_bf16 v[52:55], v[168:171], v[184:187], v[52:55]
	v_mfma_f32_16x16x32_bf16 v[48:51], v[176:179], v[184:187], v[48:51]
	v_mfma_f32_16x16x32_bf16 v[36:39], v[168:171], v[192:195], v[36:39]
	v_mfma_f32_16x16x32_bf16 v[32:35], v[176:179], v[192:195], v[32:35]
	v_mfma_f32_16x16x32_bf16 v[20:23], v[168:171], v[200:203], v[20:23]
	v_mfma_f32_16x16x32_bf16 v[16:19], v[176:179], v[200:203], v[16:19]
	v_mfma_f32_16x16x32_bf16 v[4:7], v[168:171], v[208:211], v[4:7]
	v_mfma_f32_16x16x32_bf16 v[0:3], v[176:179], v[208:211], v[0:3]
	v_mfma_f32_16x16x32_bf16 v[52:55], v[172:175], v[188:191], v[52:55]
	v_mfma_f32_16x16x32_bf16 v[48:51], v[180:183], v[188:191], v[48:51]
	v_mfma_f32_16x16x32_bf16 v[36:39], v[172:175], v[196:199], v[36:39]
	v_mfma_f32_16x16x32_bf16 v[32:35], v[180:183], v[196:199], v[32:35]
	v_mfma_f32_16x16x32_bf16 v[20:23], v[172:175], v[204:207], v[20:23]
	v_mfma_f32_16x16x32_bf16 v[16:19], v[180:183], v[204:207], v[16:19]
	v_mfma_f32_16x16x32_bf16 v[4:7], v[172:175], v[212:215], v[4:7]
	v_mfma_f32_16x16x32_bf16 v[0:3], v[180:183], v[212:215], v[0:3]
	s_barrier
	s_setprio 0
	s_add_i32 s80, s80, 2
	s_add_u32 s44, s44, 0x100
	s_addc_u32 s45, s45, 0
	s_add_u32 s78, s78, 0x100
	s_addc_u32 s79, s79, 0
	s_cmp_gt_u32 s80, 13
	s_cbranch_scc0 .LBB0_593
	s_and_b64 vcc, exec, s[16:17]
	s_cbranch_vccz .LBB0_596
	s_barrier

; #define PG8_STAGE(bufoff, gbase, voff) do { _Pragma("unroll") for (int _i = 0; _i < 2; ++_i) \
;         __builtin_amdgcn_global_load_lds((const unsigned*)((const char*)(gbase) + (voff)[_i]), (PG8_LAS unsigned*)(lds + (bufoff) + ldsw + _i * 8192), 16, 0, 0); } while (0)
; #define PG8_LDA(dst, b, h) do { _Pragma("unroll") for (int m = 0; m < 4; ++m) _Pragma("unroll") for (int k = 0; k < 2; ++k) dst[m][k] = *(const PG8_LAS bf16x8*)(lds + PG8_SA(b, h) + aoff + m * 2048 + k * 1024); } while (0)
; #define PG8_LDB(dst, b, h) do { _Pragma("unroll") for (int n = 0; n < 2; ++n) _Pragma("unroll") for (int k = 0; k < 2; ++k) dst[n][k] = *(const PG8_LAS bf16x8*)(lds + PG8_SB(b, h) + boff + n * 2048 + k * 1024); } while (0)
; #define PG8_MMA(ai, bj, At, Bt) do { __builtin_amdgcn_s_setprio(1); _Pragma("unroll") for (int m = 0; m < 4; ++m) _Pragma("unroll") for (int n = 0; n < 2; ++n) _Pragma("unroll") for (int k = 0; k < 2; ++k) \
;         acc[ai][bj][m][n] = __builtin_amdgcn_mfma_f32_16x16x32_bf16(Bt[n][k], At[m][k], acc[ai][bj][m][n], 0, 0, 0); __builtin_amdgcn_s_setprio(0); } while (0)
; #define PG8_WAIT_V(n) asm volatile("s_waitcnt vmcnt(" #n ")" ::: "memory")
; #define PG8_WAIT_L(n) asm volatile("s_waitcnt lgkmcnt(" #n ")" ::: "memory")
; #define PG8_BAR __builtin_amdgcn_s_barrier()
; template <class Epi, class Sched, bool ALIGN_EPI = false, bool SP2 = false>
; __device__ __forceinline__ void gemm_phase(PG8_LAS unsigned char* lds, const Gemm g, const Sched& S, const Epi& E) {
;     ...
;             const char* a1 = cA + (size_t)(t + 1) * kstep;
;             const char* a2 = last ? nA : cA + (size_t)(t + 2) * kstep; const char* b2 = last ? nB : cB + (size_t)(t + 2) * kstep;
;             const char* a3 = a2 + kstep; const char* b3 = b2 + kstep;
;             if (last && has_next) S.a_ready(nxt);
;             if constexpr (SP2) {
;             PG8_LDB(B0, 0, 0); PG8_LDB(B1, 0, 1); PG8_SCHED; PG8_LDA(At, 0, 0); PG8_STAGE(PG8_SA(1, 1), a1 + hstep, voffA);
;             PG8_WAIT_V(8); PG8_WAIT_L(0); PG8_BAR; PG8_MMA(0, 0, At, B0); PG8_MMA(0, 1, At, B1); PG8_BAR; PG8_SCHED;
;             PG8_LDA(At, 0, 1); PG8_STAGE(PG8_SB(0, 0), b2, voffB); PG8_STAGE(PG8_SB(0, 1), b2 + hstep, voffB); PG8_STAGE(PG8_SA(0, 0), a2, voffA);
;             PG8_WAIT_V(8); PG8_WAIT_L(0); PG8_BAR; PG8_MMA(1, 0, At, B0); PG8_MMA(1, 1, At, B1); PG8_BAR; PG8_SCHED;
.LBB0_1012:
	ds_read_b128 v[112:115], v246
	ds_read_b128 v[116:119], v246 offset:1024
	ds_read_b128 v[120:123], v246 offset:2048
	ds_read_b128 v[124:127], v246 offset:3072
	ds_read_b128 v[136:139], v247
	ds_read_b128 v[140:143], v247 offset:1024
	ds_read_b128 v[152:155], v247 offset:2048
	ds_read_b128 v[156:159], v247 offset:3072
	s_add_u32 s44, s42, 0xfffc0080
	s_addc_u32 s45, s43, -1
	s_cmp_eq_u32 s68, 12
	s_cselect_b32 s47, s23, s45
	s_cselect_b32 s46, s39, s44
	s_cselect_b32 s45, s21, s67
	s_cselect_b32 s44, s65, s66
	v_lshl_add_u64 v[206:207], s[42:43], 0, v[200:201]
	s_add_i32 m0, s41, 0xc000
	ds_read_b128 v[160:163], v248
	ds_read_b128 v[164:167], v248 offset:1024
	ds_read_b128 v[168:171], v248 offset:2048
	ds_read_b128 v[172:175], v248 offset:3072
	ds_read_b128 v[176:179], v248 offset:4096
	ds_read_b128 v[180:183], v248 offset:5120
	ds_read_b128 v[184:187], v248 offset:6144
	ds_read_b128 v[188:191], v248 offset:7168
	global_load_lds_dwordx4 v[206:207], off
	v_lshl_add_u64 v[206:207], s[42:43], 0, v[202:203]
	s_add_i32 m0, s41, 0xe000
	s_nop 0
	global_load_lds_dwordx4 v[206:207], off
	s_waitcnt vmcnt(8)
	s_waitcnt lgkmcnt(0)
	s_setprio 1
	s_barrier
	v_mfma_f32_16x16x32_bf16 v[148:151], v[112:115], v[160:163], v[148:151]
	v_mfma_f32_16x16x32_bf16 v[144:147], v[120:123], v[160:163], v[144:147]
	v_mfma_f32_16x16x32_bf16 v[108:111], v[112:115], v[168:171], v[108:111]
	v_mfma_f32_16x16x32_bf16 v[104:107], v[120:123], v[168:171], v[104:107]
	v_mfma_f32_16x16x32_bf16 v[92:95], v[112:115], v[176:179], v[92:95]
	v_mfma_f32_16x16x32_bf16 v[88:91], v[120:123], v[176:179], v[88:91]
	v_mfma_f32_16x16x32_bf16 v[76:79], v[112:115], v[184:187], v[76:79]
	v_mfma_f32_16x16x32_bf16 v[72:75], v[120:123], v[184:187], v[72:75]
	v_mfma_f32_16x16x32_bf16 v[148:151], v[116:119], v[164:167], v[148:151]
	v_mfma_f32_16x16x32_bf16 v[144:147], v[124:127], v[164:167], v[144:147]
	v_mfma_f32_16x16x32_bf16 v[108:111], v[116:119], v[172:175], v[108:111]
	v_mfma_f32_16x16x32_bf16 v[104:107], v[124:127], v[172:175], v[104:107]
	v_mfma_f32_16x16x32_bf16 v[92:95], v[116:119], v[180:183], v[92:95]
	v_mfma_f32_16x16x32_bf16 v[88:91], v[124:127], v[180:183], v[88:91]
	v_mfma_f32_16x16x32_bf16 v[76:79], v[116:119], v[188:191], v[76:79]
	v_mfma_f32_16x16x32_bf16 v[72:75], v[124:127], v[188:191], v[72:75]
	v_mfma_f32_16x16x32_bf16 v[132:135], v[136:139], v[160:163], v[132:135]
	v_mfma_f32_16x16x32_bf16 v[128:131], v[152:155], v[160:163], v[128:131]
	v_mfma_f32_16x16x32_bf16 v[100:103], v[136:139], v[168:171], v[100:103]
	v_mfma_f32_16x16x32_bf16 v[96:99], v[152:155], v[168:171], v[96:99]
	v_mfma_f32_16x16x32_bf16 v[84:87], v[136:139], v[176:179], v[84:87]
	v_mfma_f32_16x16x32_bf16 v[80:83], v[152:155], v[176:179], v[80:83]
	v_mfma_f32_16x16x32_bf16 v[68:71], v[136:139], v[184:187], v[68:71]
	v_mfma_f32_16x16x32_bf16 v[64:67], v[152:155], v[184:187], v[64:67]
	v_mfma_f32_16x16x32_bf16 v[132:135], v[140:143], v[164:167], v[132:135]
	v_mfma_f32_16x16x32_bf16 v[128:131], v[156:159], v[164:167], v[128:131]
	v_mfma_f32_16x16x32_bf16 v[100:103], v[140:143], v[172:175], v[100:103]
	v_mfma_f32_16x16x32_bf16 v[96:99], v[156:159], v[172:175], v[96:99]
	v_mfma_f32_16x16x32_bf16 v[84:87], v[140:143], v[180:183], v[84:87]
	v_mfma_f32_16x16x32_bf16 v[80:83], v[156:159], v[180:183], v[80:83]
	v_mfma_f32_16x16x32_bf16 v[68:71], v[140:143], v[188:191], v[68:71]
	v_mfma_f32_16x16x32_bf16 v[64:67], v[156:159], v[188:191], v[64:67]
	s_barrier
	s_setprio 0
	s_add_i32 s69, s63, s52
	v_lshl_add_u64 v[206:207], s[44:45], 0, v[194:195]
	s_mov_b32 m0, s69
	ds_read_b128 v[160:163], v248 offset:16384
	ds_read_b128 v[164:167], v248 offset:17408
	ds_read_b128 v[168:171], v248 offset:18432
	ds_read_b128 v[172:175], v248 offset:19456
	ds_read_b128 v[176:179], v248 offset:20480
	ds_read_b128 v[180:183], v248 offset:21504
	ds_read_b128 v[184:187], v248 offset:22528
	ds_read_b128 v[188:191], v248 offset:23552
	global_load_lds_dwordx4 v[206:207], off
	s_add_i32 m0, s69, 0x2000
	s_add_u32 s70, s44, 0x40000
	v_lshl_add_u64 v[208:209], s[44:45], 0, v[198:199]
	s_addc_u32 s71, s45, 0
	s_add_i32 s69, s64, s52
	global_load_lds_dwordx4 v[208:209], off
	v_lshl_add_u64 v[210:211], s[70:71], 0, v[194:195]
	s_mov_b32 m0, s69
	v_lshl_add_u64 v[212:213], s[46:47], 0, v[196:197]
	global_load_lds_dwordx4 v[210:211], off
	v_lshl_add_u64 v[210:211], s[70:71], 0, v[198:199]
	s_add_i32 m0, s69, 0x2000
	s_nop 0
	global_load_lds_dwordx4 v[210:211], off
	v_lshl_add_u64 v[210:211], s[46:47], 0, v[192:193]
	s_mov_b32 m0, s41
	s_nop 0
	global_load_lds_dwordx4 v[210:211], off
	s_mov_b32 m0, s53
	s_nop 0
	global_load_lds_dwordx4 v[212:213], off
	s_waitcnt vmcnt(8)
	s_waitcnt lgkmcnt(0)
	s_setprio 1
	s_barrier
; #define PG8_STAGE(bufoff, gbase, voff) do { _Pragma("unroll") for (int _i = 0; _i < 2; ++_i) \
;         __builtin_amdgcn_global_load_lds((const unsigned*)((const char*)(gbase) + (voff)[_i]), (PG8_LAS unsigned*)(lds + (bufoff) + ldsw + _i * 8192), 16, 0, 0); } while (0)
; #define PG8_LDA(dst, b, h) do { _Pragma("unroll") for (int m = 0; m < 4; ++m) _Pragma("unroll") for (int k = 0; k < 2; ++k) dst[m][k] = *(const PG8_LAS bf16x8*)(lds + PG8_SA(b, h) + aoff + m * 2048 + k * 1024); } while (0)
; #define PG8_LDB(dst, b, h) do { _Pragma("unroll") for (int n = 0; n < 2; ++n) _Pragma("unroll") for (int k = 0; k < 2; ++k) dst[n][k] = *(const PG8_LAS bf16x8*)(lds + PG8_SB(b, h) + boff + n * 2048 + k * 1024); } while (0)
; #define PG8_MMA(ai, bj, At, Bt) do { __builtin_amdgcn_s_setprio(1); _Pragma("unroll") for (int m = 0; m < 4; ++m) _Pragma("unroll") for (int n = 0; n < 2; ++n) _Pragma("unroll") for (int k = 0; k < 2; ++k) \
;         acc[ai][bj][m][n] = __builtin_amdgcn_mfma_f32_16x16x32_bf16(Bt[n][k], At[m][k], acc[ai][bj][m][n], 0, 0, 0); __builtin_amdgcn_s_setprio(0); } while (0)
; #define PG8_WAIT_V(n) asm volatile("s_waitcnt vmcnt(" #n ")" ::: "memory")
; #define PG8_WAIT_L(n) asm volatile("s_waitcnt lgkmcnt(" #n ")" ::: "memory")
; #define PG8_BAR __builtin_amdgcn_s_barrier()
; #define PG8_SCHED __builtin_amdgcn_sched_barrier(0)
; template <class Epi, class Sched, bool ALIGN_EPI = false, bool SP2 = false>
; __device__ __forceinline__ void gemm_phase(PG8_LAS unsigned char* lds, const Gemm g, const Sched& S, const Epi& E) {
;     ...
;             PG8_WAIT_V(8); PG8_WAIT_L(0); PG8_BAR; PG8_MMA(1, 0, At, B0); PG8_MMA(1, 1, At, B1); PG8_BAR; PG8_SCHED;
;             PG8_LDB(B0, 1, 0); PG8_LDB(B1, 1, 1); PG8_SCHED; PG8_LDA(At, 1, 0); PG8_STAGE(PG8_SA(0, 1), a2 + hstep, voffA);
;             PG8_WAIT_V(8); PG8_WAIT_L(0); PG8_BAR; PG8_MMA(0, 0, At, B0); PG8_MMA(0, 1, At, B1); PG8_BAR; PG8_SCHED;
	v_mfma_f32_16x16x32_bf16 v[60:63], v[112:115], v[160:163], v[60:63]
	v_mfma_f32_16x16x32_bf16 v[56:59], v[120:123], v[160:163], v[56:59]
	v_mfma_f32_16x16x32_bf16 v[44:47], v[112:115], v[168:171], v[44:47]
	v_mfma_f32_16x16x32_bf16 v[40:43], v[120:123], v[168:171], v[40:43]
	v_mfma_f32_16x16x32_bf16 v[28:31], v[112:115], v[176:179], v[28:31]
	v_mfma_f32_16x16x32_bf16 v[24:27], v[120:123], v[176:179], v[24:27]
	v_mfma_f32_16x16x32_bf16 v[12:15], v[112:115], v[184:187], v[12:15]
	v_mfma_f32_16x16x32_bf16 v[8:11], v[120:123], v[184:187], v[8:11]
	v_mfma_f32_16x16x32_bf16 v[60:63], v[116:119], v[164:167], v[60:63]
	v_mfma_f32_16x16x32_bf16 v[56:59], v[124:127], v[164:167], v[56:59]
	v_mfma_f32_16x16x32_bf16 v[44:47], v[116:119], v[172:175], v[44:47]
	v_mfma_f32_16x16x32_bf16 v[40:43], v[124:127], v[172:175], v[40:43]
	v_mfma_f32_16x16x32_bf16 v[28:31], v[116:119], v[180:183], v[28:31]
	v_mfma_f32_16x16x32_bf16 v[24:27], v[124:127], v[180:183], v[24:27]
	v_mfma_f32_16x16x32_bf16 v[12:15], v[116:119], v[188:191], v[12:15]
	v_mfma_f32_16x16x32_bf16 v[8:11], v[124:127], v[188:191], v[8:11]
	v_mfma_f32_16x16x32_bf16 v[52:55], v[136:139], v[160:163], v[52:55]
	v_mfma_f32_16x16x32_bf16 v[48:51], v[152:155], v[160:163], v[48:51]
	v_mfma_f32_16x16x32_bf16 v[36:39], v[136:139], v[168:171], v[36:39]
	v_mfma_f32_16x16x32_bf16 v[32:35], v[152:155], v[168:171], v[32:35]
	v_mfma_f32_16x16x32_bf16 v[20:23], v[136:139], v[176:179], v[20:23]
	v_mfma_f32_16x16x32_bf16 v[16:19], v[152:155], v[176:179], v[16:19]
	v_mfma_f32_16x16x32_bf16 v[4:7], v[136:139], v[184:187], v[4:7]
	v_mfma_f32_16x16x32_bf16 v[0:3], v[152:155], v[184:187], v[0:3]
	v_mfma_f32_16x16x32_bf16 v[52:55], v[140:143], v[164:167], v[52:55]
	v_mfma_f32_16x16x32_bf16 v[48:51], v[156:159], v[164:167], v[48:51]
	v_mfma_f32_16x16x32_bf16 v[36:39], v[140:143], v[172:175], v[36:39]
	v_mfma_f32_16x16x32_bf16 v[32:35], v[156:159], v[172:175], v[32:35]
	v_mfma_f32_16x16x32_bf16 v[20:23], v[140:143], v[180:183], v[20:23]
	v_mfma_f32_16x16x32_bf16 v[16:19], v[156:159], v[180:183], v[16:19]
	v_mfma_f32_16x16x32_bf16 v[4:7], v[140:143], v[188:191], v[4:7]
	v_mfma_f32_16x16x32_bf16 v[0:3], v[156:159], v[188:191], v[0:3]
	s_barrier
	s_setprio 0
	s_add_i32 s69, 0, 0x18000
	s_add_i32 s70, 0, 0x1c000
	v_add_u32_e32 v124, s69, v244
	v_add_u32_e32 v156, s70, v244
	ds_read_b128 v[112:115], v124
	ds_read_b128 v[116:119], v124 offset:1024
	ds_read_b128 v[120:123], v124 offset:2048
	ds_read_b128 v[124:127], v124 offset:3072
	ds_read_b128 v[136:139], v156
	ds_read_b128 v[140:143], v156 offset:1024
	ds_read_b128 v[152:155], v156 offset:2048
	ds_read_b128 v[156:159], v156 offset:3072
	s_add_u32 s46, s46, 0x40000
	s_addc_u32 s47, s47, 0
	s_mov_b32 m0, s54
	v_lshl_add_u64 v[214:215], s[46:47], 0, v[192:193]
	ds_read_b128 v[160:163], v248 offset:32768
	ds_read_b128 v[164:167], v248 offset:33792
	ds_read_b128 v[168:171], v248 offset:34816
	ds_read_b128 v[172:175], v248 offset:35840
	ds_read_b128 v[176:179], v248 offset:36864
	ds_read_b128 v[180:183], v248 offset:37888
	ds_read_b128 v[184:187], v248 offset:38912
	ds_read_b128 v[188:191], v248 offset:39936
	global_load_lds_dwordx4 v[214:215], off
	v_lshl_add_u64 v[214:215], s[46:47], 0, v[196:197]
	s_mov_b32 m0, s55
	s_nop 0
	global_load_lds_dwordx4 v[214:215], off
	s_waitcnt vmcnt(8)
	s_waitcnt lgkmcnt(0)
	s_setprio 1
	s_barrier
	v_mfma_f32_16x16x32_bf16 v[148:151], v[112:115], v[160:163], v[148:151]
	v_mfma_f32_16x16x32_bf16 v[144:147], v[120:123], v[160:163], v[144:147]
	v_mfma_f32_16x16x32_bf16 v[108:111], v[112:115], v[168:171], v[108:111]
	v_mfma_f32_16x16x32_bf16 v[104:107], v[120:123], v[168:171], v[104:107]
	v_mfma_f32_16x16x32_bf16 v[92:95], v[112:115], v[176:179], v[92:95]
	v_mfma_f32_16x16x32_bf16 v[88:91], v[120:123], v[176:179], v[88:91]
	v_mfma_f32_16x16x32_bf16 v[76:79], v[112:115], v[184:187], v[76:79]
	v_mfma_f32_16x16x32_bf16 v[72:75], v[120:123], v[184:187], v[72:75]
	v_mfma_f32_16x16x32_bf16 v[148:151], v[116:119], v[164:167], v[148:151]
	v_mfma_f32_16x16x32_bf16 v[144:147], v[124:127], v[164:167], v[144:147]
	v_mfma_f32_16x16x32_bf16 v[108:111], v[116:119], v[172:175], v[108:111]
	v_mfma_f32_16x16x32_bf16 v[104:107], v[124:127], v[172:175], v[104:107]
	v_mfma_f32_16x16x32_bf16 v[92:95], v[116:119], v[180:183], v[92:95]
	v_mfma_f32_16x16x32_bf16 v[88:91], v[124:127], v[180:183], v[88:91]
	v_mfma_f32_16x16x32_bf16 v[76:79], v[116:119], v[188:191], v[76:79]
	v_mfma_f32_16x16x32_bf16 v[72:75], v[124:127], v[188:191], v[72:75]
	v_mfma_f32_16x16x32_bf16 v[132:135], v[136:139], v[160:163], v[132:135]
	v_mfma_f32_16x16x32_bf16 v[128:131], v[152:155], v[160:163], v[128:131]
	v_mfma_f32_16x16x32_bf16 v[100:103], v[136:139], v[168:171], v[100:103]
	v_mfma_f32_16x16x32_bf16 v[96:99], v[152:155], v[168:171], v[96:99]
	v_mfma_f32_16x16x32_bf16 v[84:87], v[136:139], v[176:179], v[84:87]
	v_mfma_f32_16x16x32_bf16 v[80:83], v[152:155], v[176:179], v[80:83]
	v_mfma_f32_16x16x32_bf16 v[68:71], v[136:139], v[184:187], v[68:71]
	v_mfma_f32_16x16x32_bf16 v[64:67], v[152:155], v[184:187], v[64:67]
	v_mfma_f32_16x16x32_bf16 v[132:135], v[140:143], v[164:167], v[132:135]
	v_mfma_f32_16x16x32_bf16 v[128:131], v[156:159], v[164:167], v[128:131]
	v_mfma_f32_16x16x32_bf16 v[100:103], v[140:143], v[172:175], v[100:103]
	v_mfma_f32_16x16x32_bf16 v[96:99], v[156:159], v[172:175], v[96:99]
	v_mfma_f32_16x16x32_bf16 v[84:87], v[140:143], v[180:183], v[84:87]
	v_mfma_f32_16x16x32_bf16 v[80:83], v[156:159], v[180:183], v[80:83]
	v_mfma_f32_16x16x32_bf16 v[68:71], v[140:143], v[188:191], v[68:71]
	v_mfma_f32_16x16x32_bf16 v[64:67], v[156:159], v[188:191], v[64:67]
	s_barrier
; #define PG8_STAGE(bufoff, gbase, voff) do { _Pragma("unroll") for (int _i = 0; _i < 2; ++_i) \
;         __builtin_amdgcn_global_load_lds((const unsigned*)((const char*)(gbase) + (voff)[_i]), (PG8_LAS unsigned*)(lds + (bufoff) + ldsw + _i * 8192), 16, 0, 0); } while (0)
; #define PG8_LDA(dst, b, h) do { _Pragma("unroll") for (int m = 0; m < 4; ++m) _Pragma("unroll") for (int k = 0; k < 2; ++k) dst[m][k] = *(const PG8_LAS bf16x8*)(lds + PG8_SA(b, h) + aoff + m * 2048 + k * 1024); } while (0)
; #define PG8_MMA(ai, bj, At, Bt) do { __builtin_amdgcn_s_setprio(1); _Pragma("unroll") for (int m = 0; m < 4; ++m) _Pragma("unroll") for (int n = 0; n < 2; ++n) _Pragma("unroll") for (int k = 0; k < 2; ++k) \
;         acc[ai][bj][m][n] = __builtin_amdgcn_mfma_f32_16x16x32_bf16(Bt[n][k], At[m][k], acc[ai][bj][m][n], 0, 0, 0); __builtin_amdgcn_s_setprio(0); } while (0)
; #define PG8_WAIT_V(n) asm volatile("s_waitcnt vmcnt(" #n ")" ::: "memory")
; #define PG8_WAIT_L(n) asm volatile("s_waitcnt lgkmcnt(" #n ")" ::: "memory")
; #define PG8_BAR __builtin_amdgcn_s_barrier()
; #define PG8_SCHED __builtin_amdgcn_sched_barrier(0)
; template <class Epi, class Sched, bool ALIGN_EPI = false, bool SP2 = false>
; __device__ __forceinline__ void gemm_phase(PG8_LAS unsigned char* lds, const Gemm g, const Sched& S, const Epi& E) {
;     ...
;             PG8_LDA(At, 1, 1); PG8_STAGE(PG8_SB(1, 0), b3, voffB); PG8_STAGE(PG8_SB(1, 1), b3 + hstep, voffB); PG8_STAGE(PG8_SA(1, 0), a3, voffA);
;             PG8_WAIT_V(8); PG8_WAIT_L(0); PG8_BAR; PG8_MMA(1, 0, At, B0); PG8_MMA(1, 1, At, B1); PG8_BAR; PG8_SCHED;
;     ...
;         if constexpr (ALIGN_EPI) { if (wr == 0) PG8_BAR; }
	s_setprio 0
	s_add_i32 s46, s69, s52
	v_lshl_add_u64 v[206:207], v[206:207], 0, s[16:17]
	s_mov_b32 m0, s46
	ds_read_b128 v[160:163], v248 offset:49152
	ds_read_b128 v[164:167], v248 offset:50176
	ds_read_b128 v[168:171], v248 offset:51200
	ds_read_b128 v[172:175], v248 offset:52224
	ds_read_b128 v[176:179], v248 offset:53248
	ds_read_b128 v[180:183], v248 offset:54272
	ds_read_b128 v[184:187], v248 offset:55296
	ds_read_b128 v[188:191], v248 offset:56320
	global_load_lds_dwordx4 v[206:207], off
	s_add_i32 m0, s46, 0x2000
	s_add_u32 s44, s44, 0x40080
	v_lshl_add_u64 v[206:207], v[208:209], 0, s[16:17]
	s_addc_u32 s45, s45, 0
	s_add_i32 s46, s70, s52
	global_load_lds_dwordx4 v[206:207], off
	v_lshl_add_u64 v[206:207], s[44:45], 0, v[194:195]
	s_mov_b32 m0, s46
	s_nop 0
	global_load_lds_dwordx4 v[206:207], off
	v_lshl_add_u64 v[206:207], s[44:45], 0, v[198:199]
	s_add_i32 m0, s46, 0x2000
	s_nop 0
	global_load_lds_dwordx4 v[206:207], off
	v_lshl_add_u64 v[206:207], v[210:211], 0, s[16:17]
	s_mov_b32 m0, s57
	s_nop 0
	global_load_lds_dwordx4 v[206:207], off
	v_lshl_add_u64 v[206:207], v[212:213], 0, s[16:17]
	s_mov_b32 m0, s58
	s_nop 0
	global_load_lds_dwordx4 v[206:207], off
	s_waitcnt vmcnt(8)
	s_waitcnt lgkmcnt(0)
	s_setprio 1
	s_barrier
	v_mfma_f32_16x16x32_bf16 v[60:63], v[112:115], v[160:163], v[60:63]
	v_mfma_f32_16x16x32_bf16 v[56:59], v[120:123], v[160:163], v[56:59]
	v_mfma_f32_16x16x32_bf16 v[44:47], v[112:115], v[168:171], v[44:47]
	v_mfma_f32_16x16x32_bf16 v[40:43], v[120:123], v[168:171], v[40:43]
	v_mfma_f32_16x16x32_bf16 v[28:31], v[112:115], v[176:179], v[28:31]
	v_mfma_f32_16x16x32_bf16 v[24:27], v[120:123], v[176:179], v[24:27]
	v_mfma_f32_16x16x32_bf16 v[12:15], v[112:115], v[184:187], v[12:15]
	v_mfma_f32_16x16x32_bf16 v[8:11], v[120:123], v[184:187], v[8:11]
	v_mfma_f32_16x16x32_bf16 v[60:63], v[116:119], v[164:167], v[60:63]
	v_mfma_f32_16x16x32_bf16 v[56:59], v[124:127], v[164:167], v[56:59]
	v_mfma_f32_16x16x32_bf16 v[44:47], v[116:119], v[172:175], v[44:47]
	v_mfma_f32_16x16x32_bf16 v[40:43], v[124:127], v[172:175], v[40:43]
	v_mfma_f32_16x16x32_bf16 v[28:31], v[116:119], v[180:183], v[28:31]
	v_mfma_f32_16x16x32_bf16 v[24:27], v[124:127], v[180:183], v[24:27]
	v_mfma_f32_16x16x32_bf16 v[12:15], v[116:119], v[188:191], v[12:15]
	v_mfma_f32_16x16x32_bf16 v[8:11], v[124:127], v[188:191], v[8:11]
	v_mfma_f32_16x16x32_bf16 v[52:55], v[136:139], v[160:163], v[52:55]
	v_mfma_f32_16x16x32_bf16 v[48:51], v[152:155], v[160:163], v[48:51]
	v_mfma_f32_16x16x32_bf16 v[36:39], v[136:139], v[168:171], v[36:39]
	v_mfma_f32_16x16x32_bf16 v[32:35], v[152:155], v[168:171], v[32:35]
	v_mfma_f32_16x16x32_bf16 v[20:23], v[136:139], v[176:179], v[20:23]
	v_mfma_f32_16x16x32_bf16 v[16:19], v[152:155], v[176:179], v[16:19]
	v_mfma_f32_16x16x32_bf16 v[4:7], v[136:139], v[184:187], v[4:7]
	v_mfma_f32_16x16x32_bf16 v[0:3], v[152:155], v[184:187], v[0:3]
	v_mfma_f32_16x16x32_bf16 v[52:55], v[140:143], v[164:167], v[52:55]
	v_mfma_f32_16x16x32_bf16 v[48:51], v[156:159], v[164:167], v[48:51]
	v_mfma_f32_16x16x32_bf16 v[36:39], v[140:143], v[172:175], v[36:39]
	v_mfma_f32_16x16x32_bf16 v[32:35], v[156:159], v[172:175], v[32:35]
	v_mfma_f32_16x16x32_bf16 v[20:23], v[140:143], v[180:183], v[20:23]
	v_mfma_f32_16x16x32_bf16 v[16:19], v[156:159], v[180:183], v[16:19]
	v_mfma_f32_16x16x32_bf16 v[4:7], v[140:143], v[188:191], v[4:7]
	v_mfma_f32_16x16x32_bf16 v[0:3], v[156:159], v[188:191], v[0:3]
	s_barrier
	s_setprio 0
	s_add_i32 s68, s68, 2
	s_add_u32 s42, s42, 0x100
	s_addc_u32 s43, s43, 0
	s_add_u32 s66, s66, 0x100
	s_addc_u32 s67, s67, 0
	s_cmp_gt_u32 s68, 13
	s_cbranch_scc0 .LBB0_1012
	s_and_b64 vcc, exec, s[18:19]
	s_cbranch_vccz .LBB0_1015
	s_barrier

; #define PG8_STAGE(bufoff, gbase, voff) do { _Pragma("unroll") for (int _i = 0; _i < 2; ++_i) \
;         __builtin_amdgcn_global_load_lds((const unsigned*)((const char*)(gbase) + (voff)[_i]), (PG8_LAS unsigned*)(lds + (bufoff) + ldsw + _i * 8192), 16, 0, 0); } while (0)
; #define PG8_LDA(dst, b, h) do { _Pragma("unroll") for (int m = 0; m < 4; ++m) _Pragma("unroll") for (int k = 0; k < 2; ++k) dst[m][k] = *(const PG8_LAS bf16x8*)(lds + PG8_SA(b, h) + aoff + m * 2048 + k * 1024); } while (0)
; #define PG8_LDB(dst, b, h) do { _Pragma("unroll") for (int n = 0; n < 2; ++n) _Pragma("unroll") for (int k = 0; k < 2; ++k) dst[n][k] = *(const PG8_LAS bf16x8*)(lds + PG8_SB(b, h) + boff + n * 2048 + k * 1024); } while (0)
; #define PG8_MMA(ai, bj, At, Bt) do { __builtin_amdgcn_s_setprio(1); _Pragma("unroll") for (int m = 0; m < 4; ++m) _Pragma("unroll") for (int n = 0; n < 2; ++n) _Pragma("unroll") for (int k = 0; k < 2; ++k) \
;         acc[ai][bj][m][n] = __builtin_amdgcn_mfma_f32_16x16x32_bf16(Bt[n][k], At[m][k], acc[ai][bj][m][n], 0, 0, 0); __builtin_amdgcn_s_setprio(0); } while (0)
; #define PG8_WAIT_V(n) asm volatile("s_waitcnt vmcnt(" #n ")" ::: "memory")
; #define PG8_WAIT_L(n) asm volatile("s_waitcnt lgkmcnt(" #n ")" ::: "memory")
; #define PG8_BAR __builtin_amdgcn_s_barrier()
; template <class Epi, class Sched, bool ALIGN_EPI = false, bool SP2 = false>
; __device__ __forceinline__ void gemm_phase(PG8_LAS unsigned char* lds, const Gemm g, const Sched& S, const Epi& E) {
;     ...
;             const char* a1 = cA + (size_t)(t + 1) * kstep;
;             const char* a2 = last ? nA : cA + (size_t)(t + 2) * kstep; const char* b2 = last ? nB : cB + (size_t)(t + 2) * kstep;
;             const char* a3 = a2 + kstep; const char* b3 = b2 + kstep;
;             if (last && has_next) S.a_ready(nxt);
;             if constexpr (SP2) {
;             PG8_LDB(B0, 0, 0); PG8_LDB(B1, 0, 1); PG8_SCHED; PG8_LDA(At, 0, 0); PG8_STAGE(PG8_SA(1, 1), a1 + hstep, voffA);
;             PG8_WAIT_V(8); PG8_WAIT_L(0); PG8_BAR; PG8_MMA(0, 0, At, B0); PG8_MMA(0, 1, At, B1); PG8_BAR; PG8_SCHED;
;             PG8_LDA(At, 0, 1); PG8_STAGE(PG8_SB(0, 0), b2, voffB); PG8_STAGE(PG8_SB(0, 1), b2 + hstep, voffB); PG8_STAGE(PG8_SA(0, 0), a2, voffA);
;             PG8_WAIT_V(8); PG8_WAIT_L(0); PG8_BAR; PG8_MMA(1, 0, At, B0); PG8_MMA(1, 1, At, B1); PG8_BAR; PG8_SCHED;
.LBB0_1194:
	ds_read_b128 v[154:157], v149
	ds_read_b128 v[158:161], v149 offset:1024
	ds_read_b128 v[162:165], v149 offset:2048
	ds_read_b128 v[166:169], v149 offset:3072
	ds_read_b128 v[170:173], v150
	ds_read_b128 v[174:177], v150 offset:1024
	ds_read_b128 v[178:181], v150 offset:2048
	ds_read_b128 v[182:185], v150 offset:3072
	s_add_u32 s40, s38, 0xfffc0080
	s_addc_u32 s41, s39, -1
	s_cmp_eq_u32 s68, 12
	s_cselect_b32 s43, s21, s41
	s_cselect_b32 s42, s64, s40
	s_cselect_b32 s41, s19, s67
	s_cselect_b32 s40, s65, s66
	v_lshl_add_u64 v[144:145], s[38:39], 0, v[136:137]
	s_add_i32 m0, s37, 0xc000
	ds_read_b128 v[186:189], v151
	ds_read_b128 v[190:193], v151 offset:1024
	ds_read_b128 v[194:197], v151 offset:2048
	ds_read_b128 v[198:201], v151 offset:3072
	ds_read_b128 v[202:205], v151 offset:4096
	ds_read_b128 v[206:209], v151 offset:5120
	ds_read_b128 v[210:213], v151 offset:6144
	ds_read_b128 v[214:217], v151 offset:7168
	global_load_lds_dwordx4 v[144:145], off
	v_lshl_add_u64 v[144:145], s[38:39], 0, v[138:139]
	s_add_i32 m0, s37, 0xe000
	s_nop 0
	global_load_lds_dwordx4 v[144:145], off
	s_waitcnt vmcnt(8)
	s_waitcnt lgkmcnt(0)
	s_setprio 1
	s_barrier
	v_mfma_f32_16x16x32_bf16 v[120:123], v[154:157], v[186:189], v[120:123]
	v_mfma_f32_16x16x32_bf16 v[116:119], v[162:165], v[186:189], v[116:119]
	v_mfma_f32_16x16x32_bf16 v[108:111], v[154:157], v[194:197], v[108:111]
	v_mfma_f32_16x16x32_bf16 v[100:103], v[162:165], v[194:197], v[100:103]
	v_mfma_f32_16x16x32_bf16 v[92:95], v[154:157], v[202:205], v[92:95]
	v_mfma_f32_16x16x32_bf16 v[84:87], v[162:165], v[202:205], v[84:87]
	v_mfma_f32_16x16x32_bf16 v[76:79], v[154:157], v[210:213], v[76:79]
	v_mfma_f32_16x16x32_bf16 v[68:71], v[162:165], v[210:213], v[68:71]
	v_mfma_f32_16x16x32_bf16 v[120:123], v[158:161], v[190:193], v[120:123]
	v_mfma_f32_16x16x32_bf16 v[116:119], v[166:169], v[190:193], v[116:119]
	v_mfma_f32_16x16x32_bf16 v[108:111], v[158:161], v[198:201], v[108:111]
	v_mfma_f32_16x16x32_bf16 v[100:103], v[166:169], v[198:201], v[100:103]
	v_mfma_f32_16x16x32_bf16 v[92:95], v[158:161], v[206:209], v[92:95]
	v_mfma_f32_16x16x32_bf16 v[84:87], v[166:169], v[206:209], v[84:87]
	v_mfma_f32_16x16x32_bf16 v[76:79], v[158:161], v[214:217], v[76:79]
	v_mfma_f32_16x16x32_bf16 v[68:71], v[166:169], v[214:217], v[68:71]
	v_mfma_f32_16x16x32_bf16 v[124:127], v[170:173], v[186:189], v[124:127]
	v_mfma_f32_16x16x32_bf16 v[112:115], v[178:181], v[186:189], v[112:115]
	v_mfma_f32_16x16x32_bf16 v[104:107], v[170:173], v[194:197], v[104:107]
	v_mfma_f32_16x16x32_bf16 v[96:99], v[178:181], v[194:197], v[96:99]
	v_mfma_f32_16x16x32_bf16 v[88:91], v[170:173], v[202:205], v[88:91]
	v_mfma_f32_16x16x32_bf16 v[80:83], v[178:181], v[202:205], v[80:83]
	v_mfma_f32_16x16x32_bf16 v[72:75], v[170:173], v[210:213], v[72:75]
	v_mfma_f32_16x16x32_bf16 v[64:67], v[178:181], v[210:213], v[64:67]
	v_mfma_f32_16x16x32_bf16 v[124:127], v[174:177], v[190:193], v[124:127]
	v_mfma_f32_16x16x32_bf16 v[112:115], v[182:185], v[190:193], v[112:115]
	v_mfma_f32_16x16x32_bf16 v[104:107], v[174:177], v[198:201], v[104:107]
	v_mfma_f32_16x16x32_bf16 v[96:99], v[182:185], v[198:201], v[96:99]
	v_mfma_f32_16x16x32_bf16 v[88:91], v[174:177], v[206:209], v[88:91]
	v_mfma_f32_16x16x32_bf16 v[80:83], v[182:185], v[206:209], v[80:83]
	v_mfma_f32_16x16x32_bf16 v[72:75], v[174:177], v[214:217], v[72:75]
	v_mfma_f32_16x16x32_bf16 v[64:67], v[182:185], v[214:217], v[64:67]
	s_barrier
	s_setprio 0
	s_add_i32 s69, s57, s48
	v_lshl_add_u64 v[144:145], s[40:41], 0, v[132:133]
	s_mov_b32 m0, s69
	ds_read_b128 v[186:189], v151 offset:16384
	ds_read_b128 v[190:193], v151 offset:17408
	ds_read_b128 v[194:197], v151 offset:18432
	ds_read_b128 v[198:201], v151 offset:19456
	ds_read_b128 v[202:205], v151 offset:20480
	ds_read_b128 v[206:209], v151 offset:21504
	ds_read_b128 v[210:213], v151 offset:22528
	ds_read_b128 v[214:217], v151 offset:23552
	global_load_lds_dwordx4 v[144:145], off
	s_add_i32 m0, s69, 0x2000
	s_add_u32 s70, s40, 0x40000
	v_lshl_add_u64 v[218:219], s[40:41], 0, v[128:129]
	s_addc_u32 s71, s41, 0
	s_add_i32 s69, s58, s48
	global_load_lds_dwordx4 v[218:219], off
	v_lshl_add_u64 v[220:221], s[70:71], 0, v[132:133]
	s_mov_b32 m0, s69
	v_lshl_add_u64 v[222:223], s[42:43], 0, v[130:131]
	global_load_lds_dwordx4 v[220:221], off
	v_lshl_add_u64 v[220:221], s[70:71], 0, v[128:129]
	s_add_i32 m0, s69, 0x2000
	s_nop 0
	global_load_lds_dwordx4 v[220:221], off
	v_lshl_add_u64 v[220:221], s[42:43], 0, v[134:135]
	s_mov_b32 m0, s37
	s_nop 0
	global_load_lds_dwordx4 v[220:221], off
	s_mov_b32 m0, s50
	s_nop 0
	global_load_lds_dwordx4 v[222:223], off
	s_waitcnt vmcnt(8)
	s_waitcnt lgkmcnt(0)
	s_setprio 1
	s_barrier
; #define PG8_STAGE(bufoff, gbase, voff) do { _Pragma("unroll") for (int _i = 0; _i < 2; ++_i) \
;         __builtin_amdgcn_global_load_lds((const unsigned*)((const char*)(gbase) + (voff)[_i]), (PG8_LAS unsigned*)(lds + (bufoff) + ldsw + _i * 8192), 16, 0, 0); } while (0)
; #define PG8_LDA(dst, b, h) do { _Pragma("unroll") for (int m = 0; m < 4; ++m) _Pragma("unroll") for (int k = 0; k < 2; ++k) dst[m][k] = *(const PG8_LAS bf16x8*)(lds + PG8_SA(b, h) + aoff + m * 2048 + k * 1024); } while (0)
; #define PG8_LDB(dst, b, h) do { _Pragma("unroll") for (int n = 0; n < 2; ++n) _Pragma("unroll") for (int k = 0; k < 2; ++k) dst[n][k] = *(const PG8_LAS bf16x8*)(lds + PG8_SB(b, h) + boff + n * 2048 + k * 1024); } while (0)
; #define PG8_MMA(ai, bj, At, Bt) do { __builtin_amdgcn_s_setprio(1); _Pragma("unroll") for (int m = 0; m < 4; ++m) _Pragma("unroll") for (int n = 0; n < 2; ++n) _Pragma("unroll") for (int k = 0; k < 2; ++k) \
;         acc[ai][bj][m][n] = __builtin_amdgcn_mfma_f32_16x16x32_bf16(Bt[n][k], At[m][k], acc[ai][bj][m][n], 0, 0, 0); __builtin_amdgcn_s_setprio(0); } while (0)
; #define PG8_WAIT_V(n) asm volatile("s_waitcnt vmcnt(" #n ")" ::: "memory")
; #define PG8_WAIT_L(n) asm volatile("s_waitcnt lgkmcnt(" #n ")" ::: "memory")
; #define PG8_BAR __builtin_amdgcn_s_barrier()
; #define PG8_SCHED __builtin_amdgcn_sched_barrier(0)
; template <class Epi, class Sched, bool ALIGN_EPI = false, bool SP2 = false>
; __device__ __forceinline__ void gemm_phase(PG8_LAS unsigned char* lds, const Gemm g, const Sched& S, const Epi& E) {
;     ...
;             PG8_WAIT_V(8); PG8_WAIT_L(0); PG8_BAR; PG8_MMA(1, 0, At, B0); PG8_MMA(1, 1, At, B1); PG8_BAR; PG8_SCHED;
;             PG8_LDB(B0, 1, 0); PG8_LDB(B1, 1, 1); PG8_SCHED; PG8_LDA(At, 1, 0); PG8_STAGE(PG8_SA(0, 1), a2 + hstep, voffA);
;             PG8_WAIT_V(8); PG8_WAIT_L(0); PG8_BAR; PG8_MMA(0, 0, At, B0); PG8_MMA(0, 1, At, B1); PG8_BAR; PG8_SCHED;
	v_mfma_f32_16x16x32_bf16 v[60:63], v[154:157], v[186:189], v[60:63]
	v_mfma_f32_16x16x32_bf16 v[52:55], v[162:165], v[186:189], v[52:55]
	v_mfma_f32_16x16x32_bf16 v[44:47], v[154:157], v[194:197], v[44:47]
	v_mfma_f32_16x16x32_bf16 v[36:39], v[162:165], v[194:197], v[36:39]
	v_mfma_f32_16x16x32_bf16 v[28:31], v[154:157], v[202:205], v[28:31]
	v_mfma_f32_16x16x32_bf16 v[20:23], v[162:165], v[202:205], v[20:23]
	v_mfma_f32_16x16x32_bf16 v[12:15], v[154:157], v[210:213], v[12:15]
	v_mfma_f32_16x16x32_bf16 v[4:7], v[162:165], v[210:213], v[4:7]
	v_mfma_f32_16x16x32_bf16 v[60:63], v[158:161], v[190:193], v[60:63]
	v_mfma_f32_16x16x32_bf16 v[52:55], v[166:169], v[190:193], v[52:55]
	v_mfma_f32_16x16x32_bf16 v[44:47], v[158:161], v[198:201], v[44:47]
	v_mfma_f32_16x16x32_bf16 v[36:39], v[166:169], v[198:201], v[36:39]
	v_mfma_f32_16x16x32_bf16 v[28:31], v[158:161], v[206:209], v[28:31]
	v_mfma_f32_16x16x32_bf16 v[20:23], v[166:169], v[206:209], v[20:23]
	v_mfma_f32_16x16x32_bf16 v[12:15], v[158:161], v[214:217], v[12:15]
	v_mfma_f32_16x16x32_bf16 v[4:7], v[166:169], v[214:217], v[4:7]
	v_mfma_f32_16x16x32_bf16 v[56:59], v[170:173], v[186:189], v[56:59]
	v_mfma_f32_16x16x32_bf16 v[48:51], v[178:181], v[186:189], v[48:51]
	v_mfma_f32_16x16x32_bf16 v[40:43], v[170:173], v[194:197], v[40:43]
	v_mfma_f32_16x16x32_bf16 v[32:35], v[178:181], v[194:197], v[32:35]
	v_mfma_f32_16x16x32_bf16 v[24:27], v[170:173], v[202:205], v[24:27]
	v_mfma_f32_16x16x32_bf16 v[16:19], v[178:181], v[202:205], v[16:19]
	v_mfma_f32_16x16x32_bf16 v[8:11], v[170:173], v[210:213], v[8:11]
	v_mfma_f32_16x16x32_bf16 v[0:3], v[178:181], v[210:213], v[0:3]
	v_mfma_f32_16x16x32_bf16 v[56:59], v[174:177], v[190:193], v[56:59]
	v_mfma_f32_16x16x32_bf16 v[48:51], v[182:185], v[190:193], v[48:51]
	v_mfma_f32_16x16x32_bf16 v[40:43], v[174:177], v[198:201], v[40:43]
	v_mfma_f32_16x16x32_bf16 v[32:35], v[182:185], v[198:201], v[32:35]
	v_mfma_f32_16x16x32_bf16 v[24:27], v[174:177], v[206:209], v[24:27]
	v_mfma_f32_16x16x32_bf16 v[16:19], v[182:185], v[206:209], v[16:19]
	v_mfma_f32_16x16x32_bf16 v[8:11], v[174:177], v[214:217], v[8:11]
	v_mfma_f32_16x16x32_bf16 v[0:3], v[182:185], v[214:217], v[0:3]
	s_barrier
	s_setprio 0
	s_add_i32 s69, 0, 0x18000
	v_add_u32_e32 v153, s69, v147
	s_add_i32 s70, 0, 0x1c000
	ds_read_b128 v[154:157], v153
	ds_read_b128 v[158:161], v153 offset:1024
	ds_read_b128 v[162:165], v153 offset:2048
	ds_read_b128 v[166:169], v153 offset:3072
	v_add_u32_e32 v153, s70, v147
	ds_read_b128 v[170:173], v153
	ds_read_b128 v[174:177], v153 offset:1024
	ds_read_b128 v[178:181], v153 offset:2048
	ds_read_b128 v[182:185], v153 offset:3072
	s_add_u32 s42, s42, 0x40000
	s_addc_u32 s43, s43, 0
	s_mov_b32 m0, s51
	v_lshl_add_u64 v[224:225], s[42:43], 0, v[134:135]
	ds_read_b128 v[186:189], v151 offset:32768
	ds_read_b128 v[190:193], v151 offset:33792
	ds_read_b128 v[194:197], v151 offset:34816
	ds_read_b128 v[198:201], v151 offset:35840
	ds_read_b128 v[202:205], v151 offset:36864
	ds_read_b128 v[206:209], v151 offset:37888
	ds_read_b128 v[210:213], v151 offset:38912
	ds_read_b128 v[214:217], v151 offset:39936
	global_load_lds_dwordx4 v[224:225], off
	v_lshl_add_u64 v[224:225], s[42:43], 0, v[130:131]
	s_mov_b32 m0, s52
	s_nop 0
	global_load_lds_dwordx4 v[224:225], off
	s_waitcnt vmcnt(8)
	s_waitcnt lgkmcnt(0)
	s_setprio 1
	s_barrier
	v_mfma_f32_16x16x32_bf16 v[120:123], v[154:157], v[186:189], v[120:123]
	v_mfma_f32_16x16x32_bf16 v[116:119], v[162:165], v[186:189], v[116:119]
	v_mfma_f32_16x16x32_bf16 v[108:111], v[154:157], v[194:197], v[108:111]
	v_mfma_f32_16x16x32_bf16 v[100:103], v[162:165], v[194:197], v[100:103]
	v_mfma_f32_16x16x32_bf16 v[92:95], v[154:157], v[202:205], v[92:95]
	v_mfma_f32_16x16x32_bf16 v[84:87], v[162:165], v[202:205], v[84:87]
	v_mfma_f32_16x16x32_bf16 v[76:79], v[154:157], v[210:213], v[76:79]
	v_mfma_f32_16x16x32_bf16 v[68:71], v[162:165], v[210:213], v[68:71]
	v_mfma_f32_16x16x32_bf16 v[120:123], v[158:161], v[190:193], v[120:123]
	v_mfma_f32_16x16x32_bf16 v[116:119], v[166:169], v[190:193], v[116:119]
	v_mfma_f32_16x16x32_bf16 v[108:111], v[158:161], v[198:201], v[108:111]
	v_mfma_f32_16x16x32_bf16 v[100:103], v[166:169], v[198:201], v[100:103]
	v_mfma_f32_16x16x32_bf16 v[92:95], v[158:161], v[206:209], v[92:95]
	v_mfma_f32_16x16x32_bf16 v[84:87], v[166:169], v[206:209], v[84:87]
	v_mfma_f32_16x16x32_bf16 v[76:79], v[158:161], v[214:217], v[76:79]
	v_mfma_f32_16x16x32_bf16 v[68:71], v[166:169], v[214:217], v[68:71]
	v_mfma_f32_16x16x32_bf16 v[124:127], v[170:173], v[186:189], v[124:127]
	v_mfma_f32_16x16x32_bf16 v[112:115], v[178:181], v[186:189], v[112:115]
	v_mfma_f32_16x16x32_bf16 v[104:107], v[170:173], v[194:197], v[104:107]
	v_mfma_f32_16x16x32_bf16 v[96:99], v[178:181], v[194:197], v[96:99]
	v_mfma_f32_16x16x32_bf16 v[88:91], v[170:173], v[202:205], v[88:91]
	v_mfma_f32_16x16x32_bf16 v[80:83], v[178:181], v[202:205], v[80:83]
	v_mfma_f32_16x16x32_bf16 v[72:75], v[170:173], v[210:213], v[72:75]
	v_mfma_f32_16x16x32_bf16 v[64:67], v[178:181], v[210:213], v[64:67]
	v_mfma_f32_16x16x32_bf16 v[124:127], v[174:177], v[190:193], v[124:127]
	v_mfma_f32_16x16x32_bf16 v[112:115], v[182:185], v[190:193], v[112:115]
	v_mfma_f32_16x16x32_bf16 v[104:107], v[174:177], v[198:201], v[104:107]
	v_mfma_f32_16x16x32_bf16 v[96:99], v[182:185], v[198:201], v[96:99]
	v_mfma_f32_16x16x32_bf16 v[88:91], v[174:177], v[206:209], v[88:91]
	v_mfma_f32_16x16x32_bf16 v[80:83], v[182:185], v[206:209], v[80:83]
	v_mfma_f32_16x16x32_bf16 v[72:75], v[174:177], v[214:217], v[72:75]
	v_mfma_f32_16x16x32_bf16 v[64:67], v[182:185], v[214:217], v[64:67]
	s_barrier
; #define PG8_STAGE(bufoff, gbase, voff) do { _Pragma("unroll") for (int _i = 0; _i < 2; ++_i) \
;         __builtin_amdgcn_global_load_lds((const unsigned*)((const char*)(gbase) + (voff)[_i]), (PG8_LAS unsigned*)(lds + (bufoff) + ldsw + _i * 8192), 16, 0, 0); } while (0)
; #define PG8_LDA(dst, b, h) do { _Pragma("unroll") for (int m = 0; m < 4; ++m) _Pragma("unroll") for (int k = 0; k < 2; ++k) dst[m][k] = *(const PG8_LAS bf16x8*)(lds + PG8_SA(b, h) + aoff + m * 2048 + k * 1024); } while (0)
; #define PG8_MMA(ai, bj, At, Bt) do { __builtin_amdgcn_s_setprio(1); _Pragma("unroll") for (int m = 0; m < 4; ++m) _Pragma("unroll") for (int n = 0; n < 2; ++n) _Pragma("unroll") for (int k = 0; k < 2; ++k) \
;         acc[ai][bj][m][n] = __builtin_amdgcn_mfma_f32_16x16x32_bf16(Bt[n][k], At[m][k], acc[ai][bj][m][n], 0, 0, 0); __builtin_amdgcn_s_setprio(0); } while (0)
; #define PG8_WAIT_V(n) asm volatile("s_waitcnt vmcnt(" #n ")" ::: "memory")
; #define PG8_WAIT_L(n) asm volatile("s_waitcnt lgkmcnt(" #n ")" ::: "memory")
; #define PG8_BAR __builtin_amdgcn_s_barrier()
; #define PG8_SCHED __builtin_amdgcn_sched_barrier(0)
; template <class Epi, class Sched, bool ALIGN_EPI = false, bool SP2 = false>
; __device__ __forceinline__ void gemm_phase(PG8_LAS unsigned char* lds, const Gemm g, const Sched& S, const Epi& E) {
;     ...
;             PG8_LDA(At, 1, 1); PG8_STAGE(PG8_SB(1, 0), b3, voffB); PG8_STAGE(PG8_SB(1, 1), b3 + hstep, voffB); PG8_STAGE(PG8_SA(1, 0), a3, voffA);
;             PG8_WAIT_V(8); PG8_WAIT_L(0); PG8_BAR; PG8_MMA(1, 0, At, B0); PG8_MMA(1, 1, At, B1); PG8_BAR; PG8_SCHED;
;     ...
;         if constexpr (ALIGN_EPI) { if (wr == 0) PG8_BAR; }
	s_setprio 0
	s_add_i32 s42, s69, s48
	v_lshl_add_u64 v[144:145], v[144:145], 0, s[14:15]
	s_mov_b32 m0, s42
	ds_read_b128 v[186:189], v151 offset:49152
	ds_read_b128 v[190:193], v151 offset:50176
	ds_read_b128 v[194:197], v151 offset:51200
	ds_read_b128 v[198:201], v151 offset:52224
	ds_read_b128 v[202:205], v151 offset:53248
	ds_read_b128 v[206:209], v151 offset:54272
	ds_read_b128 v[210:213], v151 offset:55296
	ds_read_b128 v[214:217], v151 offset:56320
	global_load_lds_dwordx4 v[144:145], off
	s_add_i32 m0, s42, 0x2000
	s_add_u32 s40, s40, 0x40080
	v_lshl_add_u64 v[144:145], v[218:219], 0, s[14:15]
	s_addc_u32 s41, s41, 0
	s_add_i32 s42, s70, s48
	global_load_lds_dwordx4 v[144:145], off
	v_lshl_add_u64 v[144:145], s[40:41], 0, v[132:133]
	s_mov_b32 m0, s42
	s_nop 0
	global_load_lds_dwordx4 v[144:145], off
	v_lshl_add_u64 v[144:145], s[40:41], 0, v[128:129]
	s_add_i32 m0, s42, 0x2000
	s_nop 0
	global_load_lds_dwordx4 v[144:145], off
	v_lshl_add_u64 v[144:145], v[220:221], 0, s[14:15]
	s_mov_b32 m0, s53
	s_nop 0
	global_load_lds_dwordx4 v[144:145], off
	v_lshl_add_u64 v[144:145], v[222:223], 0, s[14:15]
	s_mov_b32 m0, s54
	s_nop 0
	global_load_lds_dwordx4 v[144:145], off
	s_waitcnt vmcnt(8)
	s_waitcnt lgkmcnt(0)
	s_setprio 1
	s_barrier
	v_mfma_f32_16x16x32_bf16 v[60:63], v[154:157], v[186:189], v[60:63]
	v_mfma_f32_16x16x32_bf16 v[52:55], v[162:165], v[186:189], v[52:55]
	v_mfma_f32_16x16x32_bf16 v[44:47], v[154:157], v[194:197], v[44:47]
	v_mfma_f32_16x16x32_bf16 v[36:39], v[162:165], v[194:197], v[36:39]
	v_mfma_f32_16x16x32_bf16 v[28:31], v[154:157], v[202:205], v[28:31]
	v_mfma_f32_16x16x32_bf16 v[20:23], v[162:165], v[202:205], v[20:23]
	v_mfma_f32_16x16x32_bf16 v[12:15], v[154:157], v[210:213], v[12:15]
	v_mfma_f32_16x16x32_bf16 v[4:7], v[162:165], v[210:213], v[4:7]
	v_mfma_f32_16x16x32_bf16 v[60:63], v[158:161], v[190:193], v[60:63]
	v_mfma_f32_16x16x32_bf16 v[52:55], v[166:169], v[190:193], v[52:55]
	v_mfma_f32_16x16x32_bf16 v[44:47], v[158:161], v[198:201], v[44:47]
	v_mfma_f32_16x16x32_bf16 v[36:39], v[166:169], v[198:201], v[36:39]
	v_mfma_f32_16x16x32_bf16 v[28:31], v[158:161], v[206:209], v[28:31]
	v_mfma_f32_16x16x32_bf16 v[20:23], v[166:169], v[206:209], v[20:23]
	v_mfma_f32_16x16x32_bf16 v[12:15], v[158:161], v[214:217], v[12:15]
	v_mfma_f32_16x16x32_bf16 v[4:7], v[166:169], v[214:217], v[4:7]
	v_mfma_f32_16x16x32_bf16 v[56:59], v[170:173], v[186:189], v[56:59]
	v_mfma_f32_16x16x32_bf16 v[48:51], v[178:181], v[186:189], v[48:51]
	v_mfma_f32_16x16x32_bf16 v[40:43], v[170:173], v[194:197], v[40:43]
	v_mfma_f32_16x16x32_bf16 v[32:35], v[178:181], v[194:197], v[32:35]
	v_mfma_f32_16x16x32_bf16 v[24:27], v[170:173], v[202:205], v[24:27]
	v_mfma_f32_16x16x32_bf16 v[16:19], v[178:181], v[202:205], v[16:19]
	v_mfma_f32_16x16x32_bf16 v[8:11], v[170:173], v[210:213], v[8:11]
	v_mfma_f32_16x16x32_bf16 v[0:3], v[178:181], v[210:213], v[0:3]
	v_mfma_f32_16x16x32_bf16 v[56:59], v[174:177], v[190:193], v[56:59]
	v_mfma_f32_16x16x32_bf16 v[48:51], v[182:185], v[190:193], v[48:51]
	v_mfma_f32_16x16x32_bf16 v[40:43], v[174:177], v[198:201], v[40:43]
	v_mfma_f32_16x16x32_bf16 v[32:35], v[182:185], v[198:201], v[32:35]
	v_mfma_f32_16x16x32_bf16 v[24:27], v[174:177], v[206:209], v[24:27]
	v_mfma_f32_16x16x32_bf16 v[16:19], v[182:185], v[206:209], v[16:19]
	v_mfma_f32_16x16x32_bf16 v[8:11], v[174:177], v[214:217], v[8:11]
	v_mfma_f32_16x16x32_bf16 v[0:3], v[182:185], v[214:217], v[0:3]
	s_barrier
	s_setprio 0
	s_add_i32 s68, s68, 2
	s_add_u32 s38, s38, 0x100
	s_addc_u32 s39, s39, 0
	s_add_u32 s66, s66, 0x100
	s_addc_u32 s67, s67, 0
	s_cmp_gt_u32 s68, 13
	s_cbranch_scc0 .LBB0_1194
	s_and_b64 vcc, exec, s[16:17]
	s_cbranch_vccz .LBB0_1197
	s_barrier

; #define PG8_STAGE(bufoff, gbase, voff) do { _Pragma("unroll") for (int _i = 0; _i < 2; ++_i) \
;         __builtin_amdgcn_global_load_lds((const unsigned*)((const char*)(gbase) + (voff)[_i]), (PG8_LAS unsigned*)(lds + (bufoff) + ldsw + _i * 8192), 16, 0, 0); } while (0)
; #define PG8_LDA(dst, b, h) do { _Pragma("unroll") for (int m = 0; m < 4; ++m) _Pragma("unroll") for (int k = 0; k < 2; ++k) dst[m][k] = *(const PG8_LAS bf16x8*)(lds + PG8_SA(b, h) + aoff + m * 2048 + k * 1024); } while (0)
; #define PG8_LDB(dst, b, h) do { _Pragma("unroll") for (int n = 0; n < 2; ++n) _Pragma("unroll") for (int k = 0; k < 2; ++k) dst[n][k] = *(const PG8_LAS bf16x8*)(lds + PG8_SB(b, h) + boff + n * 2048 + k * 1024); } while (0)
; #define PG8_MMA(ai, bj, At, Bt) do { __builtin_amdgcn_s_setprio(1); _Pragma("unroll") for (int m = 0; m < 4; ++m) _Pragma("unroll") for (int n = 0; n < 2; ++n) _Pragma("unroll") for (int k = 0; k < 2; ++k) \
;         acc[ai][bj][m][n] = __builtin_amdgcn_mfma_f32_16x16x32_bf16(Bt[n][k], At[m][k], acc[ai][bj][m][n], 0, 0, 0); __builtin_amdgcn_s_setprio(0); } while (0)
; #define PG8_WAIT_V(n) asm volatile("s_waitcnt vmcnt(" #n ")" ::: "memory")
; #define PG8_WAIT_L(n) asm volatile("s_waitcnt lgkmcnt(" #n ")" ::: "memory")
; #define PG8_BAR __builtin_amdgcn_s_barrier()
; template <class Epi, class Sched, bool ALIGN_EPI = false, bool SP2 = false>
; __device__ __forceinline__ void gemm_phase(PG8_LAS unsigned char* lds, const Gemm g, const Sched& S, const Epi& E) {
;     ...
;             const char* a1 = cA + (size_t)(t + 1) * kstep;
;             const char* a2 = last ? nA : cA + (size_t)(t + 2) * kstep; const char* b2 = last ? nB : cB + (size_t)(t + 2) * kstep;
;             const char* a3 = a2 + kstep; const char* b3 = b2 + kstep;
;             if (last && has_next) S.a_ready(nxt);
;             if constexpr (SP2) {
;             PG8_LDB(B0, 0, 0); PG8_LDB(B1, 0, 1); PG8_SCHED; PG8_LDA(At, 0, 0); PG8_STAGE(PG8_SA(1, 1), a1 + hstep, voffA);
;             PG8_WAIT_V(8); PG8_WAIT_L(0); PG8_BAR; PG8_MMA(0, 0, At, B0); PG8_MMA(0, 1, At, B1); PG8_BAR; PG8_SCHED;
;             PG8_LDA(At, 0, 1); PG8_STAGE(PG8_SB(0, 0), b2, voffB); PG8_STAGE(PG8_SB(0, 1), b2 + hstep, voffB); PG8_STAGE(PG8_SA(0, 0), a2, voffA);
;             PG8_WAIT_V(8); PG8_WAIT_L(0); PG8_BAR; PG8_MMA(1, 0, At, B0); PG8_MMA(1, 1, At, B1); PG8_BAR; PG8_SCHED;
.LBB0_1906:
	ds_read_b128 v[144:147], v151
	ds_read_b128 v[156:159], v151 offset:1024
	ds_read_b128 v[160:163], v151 offset:2048
	ds_read_b128 v[164:167], v151 offset:3072
	ds_read_b128 v[168:171], v152
	ds_read_b128 v[172:175], v152 offset:1024
	ds_read_b128 v[176:179], v152 offset:2048
	ds_read_b128 v[180:183], v152 offset:3072
	s_add_u32 s40, s38, 0xfffc0080
	s_addc_u32 s41, s39, -1
	s_cmp_eq_u32 s68, 12
	s_cselect_b32 s43, s21, s41
	s_cselect_b32 s42, s64, s40
	s_cselect_b32 s41, s19, s67
	s_cselect_b32 s40, s65, s66
	v_lshl_add_u64 v[216:217], s[38:39], 0, v[136:137]
	s_add_i32 m0, s37, 0xc000
	ds_read_b128 v[184:187], v153
	ds_read_b128 v[188:191], v153 offset:1024
	ds_read_b128 v[192:195], v153 offset:2048
	ds_read_b128 v[196:199], v153 offset:3072
	ds_read_b128 v[200:203], v153 offset:4096
	ds_read_b128 v[204:207], v153 offset:5120
	ds_read_b128 v[208:211], v153 offset:6144
	ds_read_b128 v[212:215], v153 offset:7168
	global_load_lds_dwordx4 v[216:217], off
	v_lshl_add_u64 v[216:217], s[38:39], 0, v[138:139]
	s_add_i32 m0, s37, 0xe000
	s_nop 0
	global_load_lds_dwordx4 v[216:217], off
	s_waitcnt vmcnt(8)
	s_waitcnt lgkmcnt(0)
	s_setprio 1
	s_barrier
	v_mfma_f32_16x16x32_bf16 v[124:127], v[144:147], v[184:187], v[124:127]
	v_mfma_f32_16x16x32_bf16 v[120:123], v[160:163], v[184:187], v[120:123]
	v_mfma_f32_16x16x32_bf16 v[108:111], v[144:147], v[192:195], v[108:111]
	v_mfma_f32_16x16x32_bf16 v[104:107], v[160:163], v[192:195], v[104:107]
	v_mfma_f32_16x16x32_bf16 v[92:95], v[144:147], v[200:203], v[92:95]
	v_mfma_f32_16x16x32_bf16 v[88:91], v[160:163], v[200:203], v[88:91]
	v_mfma_f32_16x16x32_bf16 v[76:79], v[144:147], v[208:211], v[76:79]
	v_mfma_f32_16x16x32_bf16 v[72:75], v[160:163], v[208:211], v[72:75]
	v_mfma_f32_16x16x32_bf16 v[124:127], v[156:159], v[188:191], v[124:127]
	v_mfma_f32_16x16x32_bf16 v[120:123], v[164:167], v[188:191], v[120:123]
	v_mfma_f32_16x16x32_bf16 v[108:111], v[156:159], v[196:199], v[108:111]
	v_mfma_f32_16x16x32_bf16 v[104:107], v[164:167], v[196:199], v[104:107]
	v_mfma_f32_16x16x32_bf16 v[92:95], v[156:159], v[204:207], v[92:95]
	v_mfma_f32_16x16x32_bf16 v[88:91], v[164:167], v[204:207], v[88:91]
	v_mfma_f32_16x16x32_bf16 v[76:79], v[156:159], v[212:215], v[76:79]
	v_mfma_f32_16x16x32_bf16 v[72:75], v[164:167], v[212:215], v[72:75]
	v_mfma_f32_16x16x32_bf16 v[116:119], v[168:171], v[184:187], v[116:119]
	v_mfma_f32_16x16x32_bf16 v[112:115], v[176:179], v[184:187], v[112:115]
	v_mfma_f32_16x16x32_bf16 v[100:103], v[168:171], v[192:195], v[100:103]
	v_mfma_f32_16x16x32_bf16 v[96:99], v[176:179], v[192:195], v[96:99]
	v_mfma_f32_16x16x32_bf16 v[84:87], v[168:171], v[200:203], v[84:87]
	v_mfma_f32_16x16x32_bf16 v[80:83], v[176:179], v[200:203], v[80:83]
	v_mfma_f32_16x16x32_bf16 v[68:71], v[168:171], v[208:211], v[68:71]
	v_mfma_f32_16x16x32_bf16 v[64:67], v[176:179], v[208:211], v[64:67]
	v_mfma_f32_16x16x32_bf16 v[116:119], v[172:175], v[188:191], v[116:119]
	v_mfma_f32_16x16x32_bf16 v[112:115], v[180:183], v[188:191], v[112:115]
	v_mfma_f32_16x16x32_bf16 v[100:103], v[172:175], v[196:199], v[100:103]
	v_mfma_f32_16x16x32_bf16 v[96:99], v[180:183], v[196:199], v[96:99]
	v_mfma_f32_16x16x32_bf16 v[84:87], v[172:175], v[204:207], v[84:87]
	v_mfma_f32_16x16x32_bf16 v[80:83], v[180:183], v[204:207], v[80:83]
	v_mfma_f32_16x16x32_bf16 v[68:71], v[172:175], v[212:215], v[68:71]
	v_mfma_f32_16x16x32_bf16 v[64:67], v[180:183], v[212:215], v[64:67]
	s_barrier
	s_setprio 0
	s_add_i32 s69, s57, s48
	v_lshl_add_u64 v[216:217], s[40:41], 0, v[132:133]
	s_mov_b32 m0, s69
	ds_read_b128 v[184:187], v153 offset:16384
	ds_read_b128 v[188:191], v153 offset:17408
	ds_read_b128 v[192:195], v153 offset:18432
	ds_read_b128 v[196:199], v153 offset:19456
	ds_read_b128 v[200:203], v153 offset:20480
	ds_read_b128 v[204:207], v153 offset:21504
	ds_read_b128 v[208:211], v153 offset:22528
	ds_read_b128 v[212:215], v153 offset:23552
	global_load_lds_dwordx4 v[216:217], off
	s_add_i32 m0, s69, 0x2000
	s_add_u32 s70, s40, 0x40000
	v_lshl_add_u64 v[218:219], s[40:41], 0, v[128:129]
	s_addc_u32 s71, s41, 0
	s_add_i32 s69, s58, s48
	global_load_lds_dwordx4 v[218:219], off
	v_lshl_add_u64 v[220:221], s[70:71], 0, v[132:133]
	s_mov_b32 m0, s69
	v_lshl_add_u64 v[222:223], s[42:43], 0, v[130:131]
	global_load_lds_dwordx4 v[220:221], off
	v_lshl_add_u64 v[220:221], s[70:71], 0, v[128:129]
	s_add_i32 m0, s69, 0x2000
	s_nop 0
	global_load_lds_dwordx4 v[220:221], off
	v_lshl_add_u64 v[220:221], s[42:43], 0, v[134:135]
	s_mov_b32 m0, s37
	s_nop 0
	global_load_lds_dwordx4 v[220:221], off
	s_mov_b32 m0, s50
	s_nop 0
	global_load_lds_dwordx4 v[222:223], off
	s_waitcnt vmcnt(8)
	s_waitcnt lgkmcnt(0)
	s_setprio 1
	s_barrier
; #define PG8_STAGE(bufoff, gbase, voff) do { _Pragma("unroll") for (int _i = 0; _i < 2; ++_i) \
;         __builtin_amdgcn_global_load_lds((const unsigned*)((const char*)(gbase) + (voff)[_i]), (PG8_LAS unsigned*)(lds + (bufoff) + ldsw + _i * 8192), 16, 0, 0); } while (0)
; #define PG8_LDA(dst, b, h) do { _Pragma("unroll") for (int m = 0; m < 4; ++m) _Pragma("unroll") for (int k = 0; k < 2; ++k) dst[m][k] = *(const PG8_LAS bf16x8*)(lds + PG8_SA(b, h) + aoff + m * 2048 + k * 1024); } while (0)
; #define PG8_LDB(dst, b, h) do { _Pragma("unroll") for (int n = 0; n < 2; ++n) _Pragma("unroll") for (int k = 0; k < 2; ++k) dst[n][k] = *(const PG8_LAS bf16x8*)(lds + PG8_SB(b, h) + boff + n * 2048 + k * 1024); } while (0)
; #define PG8_MMA(ai, bj, At, Bt) do { __builtin_amdgcn_s_setprio(1); _Pragma("unroll") for (int m = 0; m < 4; ++m) _Pragma("unroll") for (int n = 0; n < 2; ++n) _Pragma("unroll") for (int k = 0; k < 2; ++k) \
;         acc[ai][bj][m][n] = __builtin_amdgcn_mfma_f32_16x16x32_bf16(Bt[n][k], At[m][k], acc[ai][bj][m][n], 0, 0, 0); __builtin_amdgcn_s_setprio(0); } while (0)
; #define PG8_WAIT_V(n) asm volatile("s_waitcnt vmcnt(" #n ")" ::: "memory")
; #define PG8_WAIT_L(n) asm volatile("s_waitcnt lgkmcnt(" #n ")" ::: "memory")
; #define PG8_BAR __builtin_amdgcn_s_barrier()
; #define PG8_SCHED __builtin_amdgcn_sched_barrier(0)
; template <class Epi, class Sched, bool ALIGN_EPI = false, bool SP2 = false>
; __device__ __forceinline__ void gemm_phase(PG8_LAS unsigned char* lds, const Gemm g, const Sched& S, const Epi& E) {
;     ...
;             PG8_WAIT_V(8); PG8_WAIT_L(0); PG8_BAR; PG8_MMA(1, 0, At, B0); PG8_MMA(1, 1, At, B1); PG8_BAR; PG8_SCHED;
;             PG8_LDB(B0, 1, 0); PG8_LDB(B1, 1, 1); PG8_SCHED; PG8_LDA(At, 1, 0); PG8_STAGE(PG8_SA(0, 1), a2 + hstep, voffA);
;             PG8_WAIT_V(8); PG8_WAIT_L(0); PG8_BAR; PG8_MMA(0, 0, At, B0); PG8_MMA(0, 1, At, B1); PG8_BAR; PG8_SCHED;
	v_mfma_f32_16x16x32_bf16 v[60:63], v[144:147], v[184:187], v[60:63]
	v_mfma_f32_16x16x32_bf16 v[56:59], v[160:163], v[184:187], v[56:59]
	v_mfma_f32_16x16x32_bf16 v[44:47], v[144:147], v[192:195], v[44:47]
	v_mfma_f32_16x16x32_bf16 v[40:43], v[160:163], v[192:195], v[40:43]
	v_mfma_f32_16x16x32_bf16 v[28:31], v[144:147], v[200:203], v[28:31]
	v_mfma_f32_16x16x32_bf16 v[24:27], v[160:163], v[200:203], v[24:27]
	v_mfma_f32_16x16x32_bf16 v[12:15], v[144:147], v[208:211], v[12:15]
	v_mfma_f32_16x16x32_bf16 v[8:11], v[160:163], v[208:211], v[8:11]
	v_mfma_f32_16x16x32_bf16 v[60:63], v[156:159], v[188:191], v[60:63]
	v_mfma_f32_16x16x32_bf16 v[56:59], v[164:167], v[188:191], v[56:59]
	v_mfma_f32_16x16x32_bf16 v[44:47], v[156:159], v[196:199], v[44:47]
	v_mfma_f32_16x16x32_bf16 v[40:43], v[164:167], v[196:199], v[40:43]
	v_mfma_f32_16x16x32_bf16 v[28:31], v[156:159], v[204:207], v[28:31]
	v_mfma_f32_16x16x32_bf16 v[24:27], v[164:167], v[204:207], v[24:27]
	v_mfma_f32_16x16x32_bf16 v[12:15], v[156:159], v[212:215], v[12:15]
	v_mfma_f32_16x16x32_bf16 v[8:11], v[164:167], v[212:215], v[8:11]
	v_mfma_f32_16x16x32_bf16 v[52:55], v[168:171], v[184:187], v[52:55]
	v_mfma_f32_16x16x32_bf16 v[48:51], v[176:179], v[184:187], v[48:51]
	v_mfma_f32_16x16x32_bf16 v[36:39], v[168:171], v[192:195], v[36:39]
	v_mfma_f32_16x16x32_bf16 v[32:35], v[176:179], v[192:195], v[32:35]
	v_mfma_f32_16x16x32_bf16 v[20:23], v[168:171], v[200:203], v[20:23]
	v_mfma_f32_16x16x32_bf16 v[16:19], v[176:179], v[200:203], v[16:19]
	v_mfma_f32_16x16x32_bf16 v[4:7], v[168:171], v[208:211], v[4:7]
	v_mfma_f32_16x16x32_bf16 v[0:3], v[176:179], v[208:211], v[0:3]
	v_mfma_f32_16x16x32_bf16 v[52:55], v[172:175], v[188:191], v[52:55]
	v_mfma_f32_16x16x32_bf16 v[48:51], v[180:183], v[188:191], v[48:51]
	v_mfma_f32_16x16x32_bf16 v[36:39], v[172:175], v[196:199], v[36:39]
	v_mfma_f32_16x16x32_bf16 v[32:35], v[180:183], v[196:199], v[32:35]
	v_mfma_f32_16x16x32_bf16 v[20:23], v[172:175], v[204:207], v[20:23]
	v_mfma_f32_16x16x32_bf16 v[16:19], v[180:183], v[204:207], v[16:19]
	v_mfma_f32_16x16x32_bf16 v[4:7], v[172:175], v[212:215], v[4:7]
	v_mfma_f32_16x16x32_bf16 v[0:3], v[180:183], v[212:215], v[0:3]
	s_barrier
	s_setprio 0
	s_add_i32 s69, 0, 0x18000
	s_add_i32 s70, 0, 0x1c000
	v_add_u32_e32 v164, s69, v149
	v_add_u32_e32 v180, s70, v149
	ds_read_b128 v[144:147], v164
	ds_read_b128 v[156:159], v164 offset:1024
	ds_read_b128 v[160:163], v164 offset:2048
	ds_read_b128 v[164:167], v164 offset:3072
	ds_read_b128 v[168:171], v180
	ds_read_b128 v[172:175], v180 offset:1024
	ds_read_b128 v[176:179], v180 offset:2048
	ds_read_b128 v[180:183], v180 offset:3072
	s_add_u32 s42, s42, 0x40000
	s_addc_u32 s43, s43, 0
	s_mov_b32 m0, s51
	v_lshl_add_u64 v[224:225], s[42:43], 0, v[134:135]
	ds_read_b128 v[184:187], v153 offset:32768
	ds_read_b128 v[188:191], v153 offset:33792
	ds_read_b128 v[192:195], v153 offset:34816
	ds_read_b128 v[196:199], v153 offset:35840
	ds_read_b128 v[200:203], v153 offset:36864
	ds_read_b128 v[204:207], v153 offset:37888
	ds_read_b128 v[208:211], v153 offset:38912
	ds_read_b128 v[212:215], v153 offset:39936
	global_load_lds_dwordx4 v[224:225], off
	v_lshl_add_u64 v[224:225], s[42:43], 0, v[130:131]
	s_mov_b32 m0, s52
	s_nop 0
	global_load_lds_dwordx4 v[224:225], off
	s_waitcnt vmcnt(8)
	s_waitcnt lgkmcnt(0)
	s_setprio 1
	s_barrier
	v_mfma_f32_16x16x32_bf16 v[124:127], v[144:147], v[184:187], v[124:127]
	v_mfma_f32_16x16x32_bf16 v[120:123], v[160:163], v[184:187], v[120:123]
	v_mfma_f32_16x16x32_bf16 v[108:111], v[144:147], v[192:195], v[108:111]
	v_mfma_f32_16x16x32_bf16 v[104:107], v[160:163], v[192:195], v[104:107]
	v_mfma_f32_16x16x32_bf16 v[92:95], v[144:147], v[200:203], v[92:95]
	v_mfma_f32_16x16x32_bf16 v[88:91], v[160:163], v[200:203], v[88:91]
	v_mfma_f32_16x16x32_bf16 v[76:79], v[144:147], v[208:211], v[76:79]
	v_mfma_f32_16x16x32_bf16 v[72:75], v[160:163], v[208:211], v[72:75]
	v_mfma_f32_16x16x32_bf16 v[124:127], v[156:159], v[188:191], v[124:127]
	v_mfma_f32_16x16x32_bf16 v[120:123], v[164:167], v[188:191], v[120:123]
	v_mfma_f32_16x16x32_bf16 v[108:111], v[156:159], v[196:199], v[108:111]
	v_mfma_f32_16x16x32_bf16 v[104:107], v[164:167], v[196:199], v[104:107]
	v_mfma_f32_16x16x32_bf16 v[92:95], v[156:159], v[204:207], v[92:95]
	v_mfma_f32_16x16x32_bf16 v[88:91], v[164:167], v[204:207], v[88:91]
	v_mfma_f32_16x16x32_bf16 v[76:79], v[156:159], v[212:215], v[76:79]
	v_mfma_f32_16x16x32_bf16 v[72:75], v[164:167], v[212:215], v[72:75]
	v_mfma_f32_16x16x32_bf16 v[116:119], v[168:171], v[184:187], v[116:119]
	v_mfma_f32_16x16x32_bf16 v[112:115], v[176:179], v[184:187], v[112:115]
	v_mfma_f32_16x16x32_bf16 v[100:103], v[168:171], v[192:195], v[100:103]
	v_mfma_f32_16x16x32_bf16 v[96:99], v[176:179], v[192:195], v[96:99]
	v_mfma_f32_16x16x32_bf16 v[84:87], v[168:171], v[200:203], v[84:87]
	v_mfma_f32_16x16x32_bf16 v[80:83], v[176:179], v[200:203], v[80:83]
	v_mfma_f32_16x16x32_bf16 v[68:71], v[168:171], v[208:211], v[68:71]
	v_mfma_f32_16x16x32_bf16 v[64:67], v[176:179], v[208:211], v[64:67]
	v_mfma_f32_16x16x32_bf16 v[116:119], v[172:175], v[188:191], v[116:119]
	v_mfma_f32_16x16x32_bf16 v[112:115], v[180:183], v[188:191], v[112:115]
	v_mfma_f32_16x16x32_bf16 v[100:103], v[172:175], v[196:199], v[100:103]
	v_mfma_f32_16x16x32_bf16 v[96:99], v[180:183], v[196:199], v[96:99]
	v_mfma_f32_16x16x32_bf16 v[84:87], v[172:175], v[204:207], v[84:87]
	v_mfma_f32_16x16x32_bf16 v[80:83], v[180:183], v[204:207], v[80:83]
	v_mfma_f32_16x16x32_bf16 v[68:71], v[172:175], v[212:215], v[68:71]
	v_mfma_f32_16x16x32_bf16 v[64:67], v[180:183], v[212:215], v[64:67]
	s_barrier
; #define PG8_STAGE(bufoff, gbase, voff) do { _Pragma("unroll") for (int _i = 0; _i < 2; ++_i) \
;         __builtin_amdgcn_global_load_lds((const unsigned*)((const char*)(gbase) + (voff)[_i]), (PG8_LAS unsigned*)(lds + (bufoff) + ldsw + _i * 8192), 16, 0, 0); } while (0)
; #define PG8_LDA(dst, b, h) do { _Pragma("unroll") for (int m = 0; m < 4; ++m) _Pragma("unroll") for (int k = 0; k < 2; ++k) dst[m][k] = *(const PG8_LAS bf16x8*)(lds + PG8_SA(b, h) + aoff + m * 2048 + k * 1024); } while (0)
; #define PG8_MMA(ai, bj, At, Bt) do { __builtin_amdgcn_s_setprio(1); _Pragma("unroll") for (int m = 0; m < 4; ++m) _Pragma("unroll") for (int n = 0; n < 2; ++n) _Pragma("unroll") for (int k = 0; k < 2; ++k) \
;         acc[ai][bj][m][n] = __builtin_amdgcn_mfma_f32_16x16x32_bf16(Bt[n][k], At[m][k], acc[ai][bj][m][n], 0, 0, 0); __builtin_amdgcn_s_setprio(0); } while (0)
; #define PG8_WAIT_V(n) asm volatile("s_waitcnt vmcnt(" #n ")" ::: "memory")
; #define PG8_WAIT_L(n) asm volatile("s_waitcnt lgkmcnt(" #n ")" ::: "memory")
; #define PG8_BAR __builtin_amdgcn_s_barrier()
; #define PG8_SCHED __builtin_amdgcn_sched_barrier(0)
; template <class Epi, class Sched, bool ALIGN_EPI = false, bool SP2 = false>
; __device__ __forceinline__ void gemm_phase(PG8_LAS unsigned char* lds, const Gemm g, const Sched& S, const Epi& E) {
;     ...
;             PG8_LDA(At, 1, 1); PG8_STAGE(PG8_SB(1, 0), b3, voffB); PG8_STAGE(PG8_SB(1, 1), b3 + hstep, voffB); PG8_STAGE(PG8_SA(1, 0), a3, voffA);
;             PG8_WAIT_V(8); PG8_WAIT_L(0); PG8_BAR; PG8_MMA(1, 0, At, B0); PG8_MMA(1, 1, At, B1); PG8_BAR; PG8_SCHED;
;     ...
;         if constexpr (ALIGN_EPI) { if (wr == 0) PG8_BAR; }
	s_setprio 0
	s_add_i32 s42, s69, s48
	v_lshl_add_u64 v[216:217], v[216:217], 0, s[14:15]
	s_mov_b32 m0, s42
	ds_read_b128 v[184:187], v153 offset:49152
	ds_read_b128 v[188:191], v153 offset:50176
	ds_read_b128 v[192:195], v153 offset:51200
	ds_read_b128 v[196:199], v153 offset:52224
	ds_read_b128 v[200:203], v153 offset:53248
	ds_read_b128 v[204:207], v153 offset:54272
	ds_read_b128 v[208:211], v153 offset:55296
	ds_read_b128 v[212:215], v153 offset:56320
	global_load_lds_dwordx4 v[216:217], off
	s_add_i32 m0, s42, 0x2000
	s_add_u32 s40, s40, 0x40080
	v_lshl_add_u64 v[216:217], v[218:219], 0, s[14:15]
	s_addc_u32 s41, s41, 0
	s_add_i32 s42, s70, s48
	global_load_lds_dwordx4 v[216:217], off
	v_lshl_add_u64 v[216:217], s[40:41], 0, v[132:133]
	s_mov_b32 m0, s42
	s_nop 0
	global_load_lds_dwordx4 v[216:217], off
	v_lshl_add_u64 v[216:217], s[40:41], 0, v[128:129]
	s_add_i32 m0, s42, 0x2000
	s_nop 0
	global_load_lds_dwordx4 v[216:217], off
	v_lshl_add_u64 v[216:217], v[220:221], 0, s[14:15]
	s_mov_b32 m0, s53
	s_nop 0
	global_load_lds_dwordx4 v[216:217], off
	v_lshl_add_u64 v[216:217], v[222:223], 0, s[14:15]
	s_mov_b32 m0, s54
	s_nop 0
	global_load_lds_dwordx4 v[216:217], off
	s_waitcnt vmcnt(8)
	s_waitcnt lgkmcnt(0)
	s_setprio 1
	s_barrier
	v_mfma_f32_16x16x32_bf16 v[60:63], v[144:147], v[184:187], v[60:63]
	v_mfma_f32_16x16x32_bf16 v[56:59], v[160:163], v[184:187], v[56:59]
	v_mfma_f32_16x16x32_bf16 v[44:47], v[144:147], v[192:195], v[44:47]
	v_mfma_f32_16x16x32_bf16 v[40:43], v[160:163], v[192:195], v[40:43]
	v_mfma_f32_16x16x32_bf16 v[28:31], v[144:147], v[200:203], v[28:31]
	v_mfma_f32_16x16x32_bf16 v[24:27], v[160:163], v[200:203], v[24:27]
	v_mfma_f32_16x16x32_bf16 v[12:15], v[144:147], v[208:211], v[12:15]
	v_mfma_f32_16x16x32_bf16 v[8:11], v[160:163], v[208:211], v[8:11]
	v_mfma_f32_16x16x32_bf16 v[60:63], v[156:159], v[188:191], v[60:63]
	v_mfma_f32_16x16x32_bf16 v[56:59], v[164:167], v[188:191], v[56:59]
	v_mfma_f32_16x16x32_bf16 v[44:47], v[156:159], v[196:199], v[44:47]
	v_mfma_f32_16x16x32_bf16 v[40:43], v[164:167], v[196:199], v[40:43]
	v_mfma_f32_16x16x32_bf16 v[28:31], v[156:159], v[204:207], v[28:31]
	v_mfma_f32_16x16x32_bf16 v[24:27], v[164:167], v[204:207], v[24:27]
	v_mfma_f32_16x16x32_bf16 v[12:15], v[156:159], v[212:215], v[12:15]
	v_mfma_f32_16x16x32_bf16 v[8:11], v[164:167], v[212:215], v[8:11]
	v_mfma_f32_16x16x32_bf16 v[52:55], v[168:171], v[184:187], v[52:55]
	v_mfma_f32_16x16x32_bf16 v[48:51], v[176:179], v[184:187], v[48:51]
	v_mfma_f32_16x16x32_bf16 v[36:39], v[168:171], v[192:195], v[36:39]
	v_mfma_f32_16x16x32_bf16 v[32:35], v[176:179], v[192:195], v[32:35]
	v_mfma_f32_16x16x32_bf16 v[20:23], v[168:171], v[200:203], v[20:23]
	v_mfma_f32_16x16x32_bf16 v[16:19], v[176:179], v[200:203], v[16:19]
	v_mfma_f32_16x16x32_bf16 v[4:7], v[168:171], v[208:211], v[4:7]
	v_mfma_f32_16x16x32_bf16 v[0:3], v[176:179], v[208:211], v[0:3]
	v_mfma_f32_16x16x32_bf16 v[52:55], v[172:175], v[188:191], v[52:55]
	v_mfma_f32_16x16x32_bf16 v[48:51], v[180:183], v[188:191], v[48:51]
	v_mfma_f32_16x16x32_bf16 v[36:39], v[172:175], v[196:199], v[36:39]
	v_mfma_f32_16x16x32_bf16 v[32:35], v[180:183], v[196:199], v[32:35]
	v_mfma_f32_16x16x32_bf16 v[20:23], v[172:175], v[204:207], v[20:23]
	v_mfma_f32_16x16x32_bf16 v[16:19], v[180:183], v[204:207], v[16:19]
	v_mfma_f32_16x16x32_bf16 v[4:7], v[172:175], v[212:215], v[4:7]
	v_mfma_f32_16x16x32_bf16 v[0:3], v[180:183], v[212:215], v[0:3]
	s_barrier
	s_setprio 0
	s_add_i32 s68, s68, 2
	s_add_u32 s38, s38, 0x100
	s_addc_u32 s39, s39, 0
	s_add_u32 s66, s66, 0x100
	s_addc_u32 s67, s67, 0
	s_cmp_gt_u32 s68, 13
	s_cbranch_scc0 .LBB0_1906
	s_and_b64 vcc, exec, s[16:17]
	s_cbranch_vccz .LBB0_1909
	s_barrier

; #define PG8_STAGE(bufoff, gbase, voff) do { _Pragma("unroll") for (int _i = 0; _i < 2; ++_i) \
;         __builtin_amdgcn_global_load_lds((const unsigned*)((const char*)(gbase) + (voff)[_i]), (PG8_LAS unsigned*)(lds + (bufoff) + ldsw + _i * 8192), 16, 0, 0); } while (0)
; #define PG8_LDA(dst, b, h) do { _Pragma("unroll") for (int m = 0; m < 4; ++m) _Pragma("unroll") for (int k = 0; k < 2; ++k) dst[m][k] = *(const PG8_LAS bf16x8*)(lds + PG8_SA(b, h) + aoff + m * 2048 + k * 1024); } while (0)
; #define PG8_LDB(dst, b, h) do { _Pragma("unroll") for (int n = 0; n < 2; ++n) _Pragma("unroll") for (int k = 0; k < 2; ++k) dst[n][k] = *(const PG8_LAS bf16x8*)(lds + PG8_SB(b, h) + boff + n * 2048 + k * 1024); } while (0)
; #define PG8_MMA(ai, bj, At, Bt) do { __builtin_amdgcn_s_setprio(1); _Pragma("unroll") for (int m = 0; m < 4; ++m) _Pragma("unroll") for (int n = 0; n < 2; ++n) _Pragma("unroll") for (int k = 0; k < 2; ++k) \
;         acc[ai][bj][m][n] = __builtin_amdgcn_mfma_f32_16x16x32_bf16(Bt[n][k], At[m][k], acc[ai][bj][m][n], 0, 0, 0); __builtin_amdgcn_s_setprio(0); } while (0)
; #define PG8_WAIT_V(n) asm volatile("s_waitcnt vmcnt(" #n ")" ::: "memory")
; #define PG8_WAIT_L(n) asm volatile("s_waitcnt lgkmcnt(" #n ")" ::: "memory")
; #define PG8_BAR __builtin_amdgcn_s_barrier()
; template <class Epi, class Sched, bool ALIGN_EPI = false, bool SP2 = false>
; __device__ __forceinline__ void gemm_phase(PG8_LAS unsigned char* lds, const Gemm g, const Sched& S, const Epi& E) {
;     ...
;             const char* a1 = cA + (size_t)(t + 1) * kstep;
;             const char* a2 = last ? nA : cA + (size_t)(t + 2) * kstep; const char* b2 = last ? nB : cB + (size_t)(t + 2) * kstep;
;             const char* a3 = a2 + kstep; const char* b3 = b2 + kstep;
;             if (last && has_next) S.a_ready(nxt);
;             if constexpr (SP2) {
;             PG8_LDB(B0, 0, 0); PG8_LDB(B1, 0, 1); PG8_SCHED; PG8_LDA(At, 0, 0); PG8_STAGE(PG8_SA(1, 1), a1 + hstep, voffA);
;             PG8_WAIT_V(8); PG8_WAIT_L(0); PG8_BAR; PG8_MMA(0, 0, At, B0); PG8_MMA(0, 1, At, B1); PG8_BAR; PG8_SCHED;
;             PG8_LDA(At, 0, 1); PG8_STAGE(PG8_SB(0, 0), b2, voffB); PG8_STAGE(PG8_SB(0, 1), b2 + hstep, voffB); PG8_STAGE(PG8_SA(0, 0), a2, voffA);
;             PG8_WAIT_V(8); PG8_WAIT_L(0); PG8_BAR; PG8_MMA(1, 0, At, B0); PG8_MMA(1, 1, At, B1); PG8_BAR; PG8_SCHED;
.LBB0_2597:
	ds_read_b128 v[128:131], v201
	ds_read_b128 v[132:135], v201 offset:1024
	ds_read_b128 v[136:139], v201 offset:2048
	ds_read_b128 v[140:143], v201 offset:3072
	ds_read_b128 v[144:147], v202
	ds_read_b128 v[148:151], v202 offset:1024
	ds_read_b128 v[152:155], v202 offset:2048
	ds_read_b128 v[156:159], v202 offset:3072
	s_add_u32 s40, s38, 0xfff50080
	s_addc_u32 s41, s39, -1
	s_cmp_eq_u32 s68, 40
	s_cselect_b32 s43, s7, s41
	s_cselect_b32 s42, s6, s40
	s_cselect_b32 s41, s37, s67
	s_cselect_b32 s40, s36, s66
	v_lshl_add_u64 v[196:197], s[38:39], 0, v[176:177]
	s_add_i32 m0, s49, 0xc000
	ds_read_b128 v[160:163], v203
	ds_read_b128 v[164:167], v203 offset:1024
	ds_read_b128 v[184:187], v203 offset:2048
	ds_read_b128 v[188:191], v203 offset:3072
	ds_read_b128 v[192:195], v203 offset:4096
	ds_read_b128 v[204:207], v203 offset:5120
	ds_read_b128 v[208:211], v203 offset:6144
	ds_read_b128 v[212:215], v203 offset:7168
	global_load_lds_dwordx4 v[196:197], off
	v_lshl_add_u64 v[196:197], s[38:39], 0, v[178:179]
	s_add_i32 m0, s49, 0xe000
	s_nop 0
	global_load_lds_dwordx4 v[196:197], off
	s_waitcnt vmcnt(8)
	s_waitcnt lgkmcnt(0)
	s_setprio 1
	s_barrier
	v_mfma_f32_16x16x32_bf16 v[124:127], v[128:131], v[160:163], v[124:127]
	v_mfma_f32_16x16x32_bf16 v[120:123], v[136:139], v[160:163], v[120:123]
	v_mfma_f32_16x16x32_bf16 v[116:119], v[128:131], v[184:187], v[116:119]
	v_mfma_f32_16x16x32_bf16 v[104:107], v[136:139], v[184:187], v[104:107]
	v_mfma_f32_16x16x32_bf16 v[92:95], v[128:131], v[192:195], v[92:95]
	v_mfma_f32_16x16x32_bf16 v[88:91], v[136:139], v[192:195], v[88:91]
	v_mfma_f32_16x16x32_bf16 v[76:79], v[128:131], v[208:211], v[76:79]
	v_mfma_f32_16x16x32_bf16 v[72:75], v[136:139], v[208:211], v[72:75]
	v_mfma_f32_16x16x32_bf16 v[124:127], v[132:135], v[164:167], v[124:127]
	v_mfma_f32_16x16x32_bf16 v[120:123], v[140:143], v[164:167], v[120:123]
	v_mfma_f32_16x16x32_bf16 v[116:119], v[132:135], v[188:191], v[116:119]
	v_mfma_f32_16x16x32_bf16 v[104:107], v[140:143], v[188:191], v[104:107]
	v_mfma_f32_16x16x32_bf16 v[92:95], v[132:135], v[204:207], v[92:95]
	v_mfma_f32_16x16x32_bf16 v[88:91], v[140:143], v[204:207], v[88:91]
	v_mfma_f32_16x16x32_bf16 v[76:79], v[132:135], v[212:215], v[76:79]
	v_mfma_f32_16x16x32_bf16 v[72:75], v[140:143], v[212:215], v[72:75]
	v_mfma_f32_16x16x32_bf16 v[112:115], v[144:147], v[160:163], v[112:115]
	v_mfma_f32_16x16x32_bf16 v[108:111], v[152:155], v[160:163], v[108:111]
	v_mfma_f32_16x16x32_bf16 v[100:103], v[144:147], v[184:187], v[100:103]
	v_mfma_f32_16x16x32_bf16 v[96:99], v[152:155], v[184:187], v[96:99]
	v_mfma_f32_16x16x32_bf16 v[84:87], v[144:147], v[192:195], v[84:87]
	v_mfma_f32_16x16x32_bf16 v[80:83], v[152:155], v[192:195], v[80:83]
	v_mfma_f32_16x16x32_bf16 v[68:71], v[144:147], v[208:211], v[68:71]
	v_mfma_f32_16x16x32_bf16 v[64:67], v[152:155], v[208:211], v[64:67]
	v_mfma_f32_16x16x32_bf16 v[112:115], v[148:151], v[164:167], v[112:115]
	v_mfma_f32_16x16x32_bf16 v[108:111], v[156:159], v[164:167], v[108:111]
	v_mfma_f32_16x16x32_bf16 v[100:103], v[148:151], v[188:191], v[100:103]
	v_mfma_f32_16x16x32_bf16 v[96:99], v[156:159], v[188:191], v[96:99]
	v_mfma_f32_16x16x32_bf16 v[84:87], v[148:151], v[204:207], v[84:87]
	v_mfma_f32_16x16x32_bf16 v[80:83], v[156:159], v[204:207], v[80:83]
	v_mfma_f32_16x16x32_bf16 v[68:71], v[148:151], v[212:215], v[68:71]
	v_mfma_f32_16x16x32_bf16 v[64:67], v[156:159], v[212:215], v[64:67]
	s_barrier
	s_setprio 0
	s_add_i32 s69, s57, s48
	v_lshl_add_u64 v[196:197], s[40:41], 0, v[170:171]
	s_mov_b32 m0, s69
	ds_read_b128 v[160:163], v203 offset:16384
	ds_read_b128 v[164:167], v203 offset:17408
	ds_read_b128 v[184:187], v203 offset:18432
	ds_read_b128 v[188:191], v203 offset:19456
	ds_read_b128 v[192:195], v203 offset:20480
	ds_read_b128 v[204:207], v203 offset:21504
	ds_read_b128 v[208:211], v203 offset:22528
	ds_read_b128 v[212:215], v203 offset:23552
	global_load_lds_dwordx4 v[196:197], off
	s_add_i32 m0, s69, 0x2000
	s_add_u32 s70, s40, 0xb0000
	v_lshl_add_u64 v[216:217], s[40:41], 0, v[174:175]
	s_addc_u32 s71, s41, 0
	s_add_i32 s69, s58, s48
	global_load_lds_dwordx4 v[216:217], off
	v_lshl_add_u64 v[218:219], s[70:71], 0, v[170:171]
	s_mov_b32 m0, s69
	v_lshl_add_u64 v[220:221], s[42:43], 0, v[172:173]
	global_load_lds_dwordx4 v[218:219], off
	v_lshl_add_u64 v[218:219], s[70:71], 0, v[174:175]
	s_add_i32 m0, s69, 0x2000
	s_nop 0
	global_load_lds_dwordx4 v[218:219], off
	v_lshl_add_u64 v[218:219], s[42:43], 0, v[168:169]
	s_mov_b32 m0, s49
	s_nop 0
	global_load_lds_dwordx4 v[218:219], off
	s_mov_b32 m0, s50
	s_nop 0
	global_load_lds_dwordx4 v[220:221], off
	s_waitcnt vmcnt(8)
	s_waitcnt lgkmcnt(0)
	s_setprio 1
	s_barrier
; #define PG8_STAGE(bufoff, gbase, voff) do { _Pragma("unroll") for (int _i = 0; _i < 2; ++_i) \
;         __builtin_amdgcn_global_load_lds((const unsigned*)((const char*)(gbase) + (voff)[_i]), (PG8_LAS unsigned*)(lds + (bufoff) + ldsw + _i * 8192), 16, 0, 0); } while (0)
; #define PG8_LDA(dst, b, h) do { _Pragma("unroll") for (int m = 0; m < 4; ++m) _Pragma("unroll") for (int k = 0; k < 2; ++k) dst[m][k] = *(const PG8_LAS bf16x8*)(lds + PG8_SA(b, h) + aoff + m * 2048 + k * 1024); } while (0)
; #define PG8_LDB(dst, b, h) do { _Pragma("unroll") for (int n = 0; n < 2; ++n) _Pragma("unroll") for (int k = 0; k < 2; ++k) dst[n][k] = *(const PG8_LAS bf16x8*)(lds + PG8_SB(b, h) + boff + n * 2048 + k * 1024); } while (0)
; #define PG8_MMA(ai, bj, At, Bt) do { __builtin_amdgcn_s_setprio(1); _Pragma("unroll") for (int m = 0; m < 4; ++m) _Pragma("unroll") for (int n = 0; n < 2; ++n) _Pragma("unroll") for (int k = 0; k < 2; ++k) \
;         acc[ai][bj][m][n] = __builtin_amdgcn_mfma_f32_16x16x32_bf16(Bt[n][k], At[m][k], acc[ai][bj][m][n], 0, 0, 0); __builtin_amdgcn_s_setprio(0); } while (0)
; #define PG8_WAIT_V(n) asm volatile("s_waitcnt vmcnt(" #n ")" ::: "memory")
; #define PG8_WAIT_L(n) asm volatile("s_waitcnt lgkmcnt(" #n ")" ::: "memory")
; #define PG8_BAR __builtin_amdgcn_s_barrier()
; #define PG8_SCHED __builtin_amdgcn_sched_barrier(0)
; template <class Epi, class Sched, bool ALIGN_EPI = false, bool SP2 = false>
; __device__ __forceinline__ void gemm_phase(PG8_LAS unsigned char* lds, const Gemm g, const Sched& S, const Epi& E) {
;     ...
;             PG8_WAIT_V(8); PG8_WAIT_L(0); PG8_BAR; PG8_MMA(1, 0, At, B0); PG8_MMA(1, 1, At, B1); PG8_BAR; PG8_SCHED;
;             PG8_LDB(B0, 1, 0); PG8_LDB(B1, 1, 1); PG8_SCHED; PG8_LDA(At, 1, 0); PG8_STAGE(PG8_SA(0, 1), a2 + hstep, voffA);
;             PG8_WAIT_V(8); PG8_WAIT_L(0); PG8_BAR; PG8_MMA(0, 0, At, B0); PG8_MMA(0, 1, At, B1); PG8_BAR; PG8_SCHED;
	v_mfma_f32_16x16x32_bf16 v[60:63], v[128:131], v[160:163], v[60:63]
	v_mfma_f32_16x16x32_bf16 v[56:59], v[136:139], v[160:163], v[56:59]
	v_mfma_f32_16x16x32_bf16 v[44:47], v[128:131], v[184:187], v[44:47]
	v_mfma_f32_16x16x32_bf16 v[40:43], v[136:139], v[184:187], v[40:43]
	v_mfma_f32_16x16x32_bf16 v[28:31], v[128:131], v[192:195], v[28:31]
	v_mfma_f32_16x16x32_bf16 v[24:27], v[136:139], v[192:195], v[24:27]
	v_mfma_f32_16x16x32_bf16 v[12:15], v[128:131], v[208:211], v[12:15]
	v_mfma_f32_16x16x32_bf16 v[8:11], v[136:139], v[208:211], v[8:11]
	v_mfma_f32_16x16x32_bf16 v[60:63], v[132:135], v[164:167], v[60:63]
	v_mfma_f32_16x16x32_bf16 v[56:59], v[140:143], v[164:167], v[56:59]
	v_mfma_f32_16x16x32_bf16 v[44:47], v[132:135], v[188:191], v[44:47]
	v_mfma_f32_16x16x32_bf16 v[40:43], v[140:143], v[188:191], v[40:43]
	v_mfma_f32_16x16x32_bf16 v[28:31], v[132:135], v[204:207], v[28:31]
	v_mfma_f32_16x16x32_bf16 v[24:27], v[140:143], v[204:207], v[24:27]
	v_mfma_f32_16x16x32_bf16 v[12:15], v[132:135], v[212:215], v[12:15]
	v_mfma_f32_16x16x32_bf16 v[8:11], v[140:143], v[212:215], v[8:11]
	v_mfma_f32_16x16x32_bf16 v[52:55], v[144:147], v[160:163], v[52:55]
	v_mfma_f32_16x16x32_bf16 v[48:51], v[152:155], v[160:163], v[48:51]
	v_mfma_f32_16x16x32_bf16 v[36:39], v[144:147], v[184:187], v[36:39]
	v_mfma_f32_16x16x32_bf16 v[32:35], v[152:155], v[184:187], v[32:35]
	v_mfma_f32_16x16x32_bf16 v[20:23], v[144:147], v[192:195], v[20:23]
	v_mfma_f32_16x16x32_bf16 v[16:19], v[152:155], v[192:195], v[16:19]
	v_mfma_f32_16x16x32_bf16 v[4:7], v[144:147], v[208:211], v[4:7]
	v_mfma_f32_16x16x32_bf16 v[0:3], v[152:155], v[208:211], v[0:3]
	v_mfma_f32_16x16x32_bf16 v[52:55], v[148:151], v[164:167], v[52:55]
	v_mfma_f32_16x16x32_bf16 v[48:51], v[156:159], v[164:167], v[48:51]
	v_mfma_f32_16x16x32_bf16 v[36:39], v[148:151], v[188:191], v[36:39]
	v_mfma_f32_16x16x32_bf16 v[32:35], v[156:159], v[188:191], v[32:35]
	v_mfma_f32_16x16x32_bf16 v[20:23], v[148:151], v[204:207], v[20:23]
	v_mfma_f32_16x16x32_bf16 v[16:19], v[156:159], v[204:207], v[16:19]
	v_mfma_f32_16x16x32_bf16 v[4:7], v[148:151], v[212:215], v[4:7]
	v_mfma_f32_16x16x32_bf16 v[0:3], v[156:159], v[212:215], v[0:3]
	s_barrier
	s_setprio 0
	s_add_i32 s69, 0, 0x18000
	s_add_i32 s70, 0, 0x1c000
	v_add_u32_e32 v140, s69, v199
	v_add_u32_e32 v156, s70, v199
	ds_read_b128 v[128:131], v140
	ds_read_b128 v[132:135], v140 offset:1024
	ds_read_b128 v[136:139], v140 offset:2048
	ds_read_b128 v[140:143], v140 offset:3072
	ds_read_b128 v[144:147], v156
	ds_read_b128 v[148:151], v156 offset:1024
	ds_read_b128 v[152:155], v156 offset:2048
	ds_read_b128 v[156:159], v156 offset:3072
	s_add_u32 s42, s42, 0xb0000
	s_addc_u32 s43, s43, 0
	s_mov_b32 m0, s51
	v_lshl_add_u64 v[222:223], s[42:43], 0, v[168:169]
	ds_read_b128 v[160:163], v203 offset:32768
	ds_read_b128 v[164:167], v203 offset:33792
	ds_read_b128 v[184:187], v203 offset:34816
	ds_read_b128 v[188:191], v203 offset:35840
	ds_read_b128 v[192:195], v203 offset:36864
	ds_read_b128 v[204:207], v203 offset:37888
	ds_read_b128 v[208:211], v203 offset:38912
	ds_read_b128 v[212:215], v203 offset:39936
	global_load_lds_dwordx4 v[222:223], off
	v_lshl_add_u64 v[222:223], s[42:43], 0, v[172:173]
	s_mov_b32 m0, s52
	s_nop 0
	global_load_lds_dwordx4 v[222:223], off
	s_waitcnt vmcnt(8)
	s_waitcnt lgkmcnt(0)
	s_setprio 1
	s_barrier
	v_mfma_f32_16x16x32_bf16 v[124:127], v[128:131], v[160:163], v[124:127]
	v_mfma_f32_16x16x32_bf16 v[120:123], v[136:139], v[160:163], v[120:123]
	v_mfma_f32_16x16x32_bf16 v[116:119], v[128:131], v[184:187], v[116:119]
	v_mfma_f32_16x16x32_bf16 v[104:107], v[136:139], v[184:187], v[104:107]
	v_mfma_f32_16x16x32_bf16 v[92:95], v[128:131], v[192:195], v[92:95]
	v_mfma_f32_16x16x32_bf16 v[88:91], v[136:139], v[192:195], v[88:91]
	v_mfma_f32_16x16x32_bf16 v[76:79], v[128:131], v[208:211], v[76:79]
	v_mfma_f32_16x16x32_bf16 v[72:75], v[136:139], v[208:211], v[72:75]
	v_mfma_f32_16x16x32_bf16 v[124:127], v[132:135], v[164:167], v[124:127]
	v_mfma_f32_16x16x32_bf16 v[120:123], v[140:143], v[164:167], v[120:123]
	v_mfma_f32_16x16x32_bf16 v[116:119], v[132:135], v[188:191], v[116:119]
	v_mfma_f32_16x16x32_bf16 v[104:107], v[140:143], v[188:191], v[104:107]
	v_mfma_f32_16x16x32_bf16 v[92:95], v[132:135], v[204:207], v[92:95]
	v_mfma_f32_16x16x32_bf16 v[88:91], v[140:143], v[204:207], v[88:91]
	v_mfma_f32_16x16x32_bf16 v[76:79], v[132:135], v[212:215], v[76:79]
	v_mfma_f32_16x16x32_bf16 v[72:75], v[140:143], v[212:215], v[72:75]
	v_mfma_f32_16x16x32_bf16 v[112:115], v[144:147], v[160:163], v[112:115]
	v_mfma_f32_16x16x32_bf16 v[108:111], v[152:155], v[160:163], v[108:111]
	v_mfma_f32_16x16x32_bf16 v[100:103], v[144:147], v[184:187], v[100:103]
	v_mfma_f32_16x16x32_bf16 v[96:99], v[152:155], v[184:187], v[96:99]
	v_mfma_f32_16x16x32_bf16 v[84:87], v[144:147], v[192:195], v[84:87]
	v_mfma_f32_16x16x32_bf16 v[80:83], v[152:155], v[192:195], v[80:83]
	v_mfma_f32_16x16x32_bf16 v[68:71], v[144:147], v[208:211], v[68:71]
	v_mfma_f32_16x16x32_bf16 v[64:67], v[152:155], v[208:211], v[64:67]
	v_mfma_f32_16x16x32_bf16 v[112:115], v[148:151], v[164:167], v[112:115]
	v_mfma_f32_16x16x32_bf16 v[108:111], v[156:159], v[164:167], v[108:111]
	v_mfma_f32_16x16x32_bf16 v[100:103], v[148:151], v[188:191], v[100:103]
	v_mfma_f32_16x16x32_bf16 v[96:99], v[156:159], v[188:191], v[96:99]
	v_mfma_f32_16x16x32_bf16 v[84:87], v[148:151], v[204:207], v[84:87]
	v_mfma_f32_16x16x32_bf16 v[80:83], v[156:159], v[204:207], v[80:83]
	v_mfma_f32_16x16x32_bf16 v[68:71], v[148:151], v[212:215], v[68:71]
	v_mfma_f32_16x16x32_bf16 v[64:67], v[156:159], v[212:215], v[64:67]
	s_barrier
; #define PG8_STAGE(bufoff, gbase, voff) do { _Pragma("unroll") for (int _i = 0; _i < 2; ++_i) \
;         __builtin_amdgcn_global_load_lds((const unsigned*)((const char*)(gbase) + (voff)[_i]), (PG8_LAS unsigned*)(lds + (bufoff) + ldsw + _i * 8192), 16, 0, 0); } while (0)
; #define PG8_LDA(dst, b, h) do { _Pragma("unroll") for (int m = 0; m < 4; ++m) _Pragma("unroll") for (int k = 0; k < 2; ++k) dst[m][k] = *(const PG8_LAS bf16x8*)(lds + PG8_SA(b, h) + aoff + m * 2048 + k * 1024); } while (0)
; #define PG8_MMA(ai, bj, At, Bt) do { __builtin_amdgcn_s_setprio(1); _Pragma("unroll") for (int m = 0; m < 4; ++m) _Pragma("unroll") for (int n = 0; n < 2; ++n) _Pragma("unroll") for (int k = 0; k < 2; ++k) \
;         acc[ai][bj][m][n] = __builtin_amdgcn_mfma_f32_16x16x32_bf16(Bt[n][k], At[m][k], acc[ai][bj][m][n], 0, 0, 0); __builtin_amdgcn_s_setprio(0); } while (0)
; #define PG8_WAIT_V(n) asm volatile("s_waitcnt vmcnt(" #n ")" ::: "memory")
; #define PG8_WAIT_L(n) asm volatile("s_waitcnt lgkmcnt(" #n ")" ::: "memory")
; #define PG8_BAR __builtin_amdgcn_s_barrier()
; #define PG8_SCHED __builtin_amdgcn_sched_barrier(0)
; template <class Epi, class Sched, bool ALIGN_EPI = false, bool SP2 = false>
; __device__ __forceinline__ void gemm_phase(PG8_LAS unsigned char* lds, const Gemm g, const Sched& S, const Epi& E) {
;     ...
;             PG8_LDA(At, 1, 1); PG8_STAGE(PG8_SB(1, 0), b3, voffB); PG8_STAGE(PG8_SB(1, 1), b3 + hstep, voffB); PG8_STAGE(PG8_SA(1, 0), a3, voffA);
;             PG8_WAIT_V(8); PG8_WAIT_L(0); PG8_BAR; PG8_MMA(1, 0, At, B0); PG8_MMA(1, 1, At, B1); PG8_BAR; PG8_SCHED;
;     ...
;         if constexpr (ALIGN_EPI) { if (wr == 0) PG8_BAR; }
	s_setprio 0
	s_add_i32 s42, s69, s48
	v_lshl_add_u64 v[196:197], v[196:197], 0, s[14:15]
	s_mov_b32 m0, s42
	ds_read_b128 v[160:163], v203 offset:49152
	ds_read_b128 v[164:167], v203 offset:50176
	ds_read_b128 v[184:187], v203 offset:51200
	ds_read_b128 v[188:191], v203 offset:52224
	ds_read_b128 v[192:195], v203 offset:53248
	ds_read_b128 v[204:207], v203 offset:54272
	ds_read_b128 v[208:211], v203 offset:55296
	ds_read_b128 v[212:215], v203 offset:56320
	global_load_lds_dwordx4 v[196:197], off
	s_add_i32 m0, s42, 0x2000
	s_add_u32 s40, s40, 0xb0080
	v_lshl_add_u64 v[196:197], v[216:217], 0, s[14:15]
	s_addc_u32 s41, s41, 0
	s_add_i32 s42, s70, s48
	global_load_lds_dwordx4 v[196:197], off
	v_lshl_add_u64 v[196:197], s[40:41], 0, v[170:171]
	s_mov_b32 m0, s42
	s_nop 0
	global_load_lds_dwordx4 v[196:197], off
	v_lshl_add_u64 v[196:197], s[40:41], 0, v[174:175]
	s_add_i32 m0, s42, 0x2000
	s_nop 0
	global_load_lds_dwordx4 v[196:197], off
	v_lshl_add_u64 v[196:197], v[218:219], 0, s[14:15]
	s_mov_b32 m0, s54
	s_nop 0
	global_load_lds_dwordx4 v[196:197], off
	v_lshl_add_u64 v[196:197], v[220:221], 0, s[14:15]
	s_mov_b32 m0, s55
	s_nop 0
	global_load_lds_dwordx4 v[196:197], off
	s_waitcnt vmcnt(8)
	s_waitcnt lgkmcnt(0)
	s_setprio 1
	s_barrier
	v_mfma_f32_16x16x32_bf16 v[60:63], v[128:131], v[160:163], v[60:63]
	v_mfma_f32_16x16x32_bf16 v[56:59], v[136:139], v[160:163], v[56:59]
	v_mfma_f32_16x16x32_bf16 v[44:47], v[128:131], v[184:187], v[44:47]
	v_mfma_f32_16x16x32_bf16 v[40:43], v[136:139], v[184:187], v[40:43]
	v_mfma_f32_16x16x32_bf16 v[28:31], v[128:131], v[192:195], v[28:31]
	v_mfma_f32_16x16x32_bf16 v[24:27], v[136:139], v[192:195], v[24:27]
	v_mfma_f32_16x16x32_bf16 v[12:15], v[128:131], v[208:211], v[12:15]
	v_mfma_f32_16x16x32_bf16 v[8:11], v[136:139], v[208:211], v[8:11]
	v_mfma_f32_16x16x32_bf16 v[60:63], v[132:135], v[164:167], v[60:63]
	v_mfma_f32_16x16x32_bf16 v[56:59], v[140:143], v[164:167], v[56:59]
	v_mfma_f32_16x16x32_bf16 v[44:47], v[132:135], v[188:191], v[44:47]
	v_mfma_f32_16x16x32_bf16 v[40:43], v[140:143], v[188:191], v[40:43]
	v_mfma_f32_16x16x32_bf16 v[28:31], v[132:135], v[204:207], v[28:31]
	v_mfma_f32_16x16x32_bf16 v[24:27], v[140:143], v[204:207], v[24:27]
	v_mfma_f32_16x16x32_bf16 v[12:15], v[132:135], v[212:215], v[12:15]
	v_mfma_f32_16x16x32_bf16 v[8:11], v[140:143], v[212:215], v[8:11]
	v_mfma_f32_16x16x32_bf16 v[52:55], v[144:147], v[160:163], v[52:55]
	v_mfma_f32_16x16x32_bf16 v[48:51], v[152:155], v[160:163], v[48:51]
	v_mfma_f32_16x16x32_bf16 v[36:39], v[144:147], v[184:187], v[36:39]
	v_mfma_f32_16x16x32_bf16 v[32:35], v[152:155], v[184:187], v[32:35]
	v_mfma_f32_16x16x32_bf16 v[20:23], v[144:147], v[192:195], v[20:23]
	v_mfma_f32_16x16x32_bf16 v[16:19], v[152:155], v[192:195], v[16:19]
	v_mfma_f32_16x16x32_bf16 v[4:7], v[144:147], v[208:211], v[4:7]
	v_mfma_f32_16x16x32_bf16 v[0:3], v[152:155], v[208:211], v[0:3]
	v_mfma_f32_16x16x32_bf16 v[52:55], v[148:151], v[164:167], v[52:55]
	v_mfma_f32_16x16x32_bf16 v[48:51], v[156:159], v[164:167], v[48:51]
	v_mfma_f32_16x16x32_bf16 v[36:39], v[148:151], v[188:191], v[36:39]
	v_mfma_f32_16x16x32_bf16 v[32:35], v[156:159], v[188:191], v[32:35]
	v_mfma_f32_16x16x32_bf16 v[20:23], v[148:151], v[204:207], v[20:23]
	v_mfma_f32_16x16x32_bf16 v[16:19], v[156:159], v[204:207], v[16:19]
	v_mfma_f32_16x16x32_bf16 v[4:7], v[148:151], v[212:215], v[4:7]
	v_mfma_f32_16x16x32_bf16 v[0:3], v[156:159], v[212:215], v[0:3]
	s_barrier
	s_setprio 0
	s_add_i32 s68, s68, 2
	s_add_u32 s38, s38, 0x100
	s_addc_u32 s39, s39, 0
	s_add_u32 s66, s66, 0x100
	s_addc_u32 s67, s67, 0
	s_cmp_gt_u32 s68, 41
	s_cbranch_scc0 .LBB0_2597
	s_and_b64 vcc, exec, s[16:17]
	s_cbranch_vccz .LBB0_2600
	s_barrier
